# strategy 4 (static s_setprio 1 for waves 0-3, all per-phase s_setprio flips deleted) on top of v16
# baseline (speedup 1.0000x reference)
; #define LAS __attribute__((address_space(3)))
; __global__ void __launch_bounds__(512, 2) hybrid_fwd(Args args) {
;     extern __shared__ __attribute__((aligned(16))) unsigned char lds_raw[];
;     Frame F0;
;     F0.lds = (LAS unsigned char*)lds_raw; F0.ws = args.ws; F0.in = args.in; F0.out = args.out;
;     F0.tid = threadIdx.x; F0.lane = F0.tid & 63; F0.wave = __builtin_amdgcn_readfirstlane(F0.tid >> 6); F0.G = gridDim.x; F0.bid = blockIdx.x; F0.gw = F0.bid * 8 + F0.wave; F0.NGW = F0.G * 8;
;     volatile LAS unsigned* ctlw = (volatile LAS unsigned*)(F0.lds + LDS_CTLW);
;     if (F0.tid < 16) ctlw[F0.tid] = 0u;
;     __syncthreads();
;     const int lo = args.ph_lo, hi = args.ph_hi; const int VAR = args.variant;
;     XcdBarrier bar; bar.bar = (unsigned*)(F0.ws + WS_CTL) + CW_BAR + args.bar_region * XCD_BAR_WORDS; bar.x = 0; bar.st = ctlw;
;     if (hi - lo > 1) bar = xcd_barrier_post((unsigned*)(F0.ws + WS_CTL) + CW_BAR + args.bar_region * XCD_BAR_WORDS, ctlw);
_Z10hybrid_fwd4Args:
	s_load_dwordx4 s[4:7], s[0:1], 0x120
	s_load_dword s76, s[0:1], 0x140
	s_mov_b32 s96, s2
	s_add_u32 s2, s0, 0x140
	s_addc_u32 s3, s1, 0
	s_waitcnt lgkmcnt(0)
	v_writelane_b32 v254, s4, 0
	v_cmp_gt_u32_e32 vcc, 16, v0
	s_nop 0
	v_writelane_b32 v254, s5, 1
	v_writelane_b32 v254, s6, 2
	v_writelane_b32 v254, s7, 3
	v_writelane_b32 v254, s2, 4
	v_readfirstlane_b32 s6, v0
	s_nop 0
	v_writelane_b32 v254, s3, 5
	s_and_saveexec_b64 s[2:3], vcc
	v_lshl_add_u32 v1, v0, 2, 0
	v_add_u32_e32 v1, 0x27fc0, v1
	v_mov_b32_e32 v2, 0
	ds_write_b32 v1, v2
	s_or_b64 exec, exec, s[2:3]
	s_load_dwordx4 s[88:91], s[0:1], 0x130
	s_load_dwordx4 s[8:11], s[0:1], 0x120
	v_cmp_eq_u32_e32 vcc, 0, v0
	s_waitcnt lgkmcnt(0)
	s_barrier
	v_readfirstlane_b32 s2, v0
	s_nop 3
	s_and_b32 s2, s2, 0x3ff
	s_lshr_b32 s2, s2, 6
	s_cmp_ge_u32 s2, 4
	s_cbranch_scc1 .Lprio_done
	s_setprio 1
.Lprio_done:
	s_mul_i32 s2, s90, 0xd80
	s_ashr_i32 s3, s2, 31
	s_lshl_b64 s[2:3], s[2:3], 2
	s_add_u32 s2, s10, s2
	s_addc_u32 s3, s11, s3
	s_add_u32 s74, s2, 0x4000
	s_addc_u32 s75, s3, 0
	s_sub_i32 s2, s89, s88
	s_mov_b32 s3, 0
	v_writelane_b32 v254, s3, 6
	s_cmp_lt_i32 s2, 2
	s_cbranch_scc1 .LBB0_7
	s_getreg_b32 s2, hwreg(HW_REG_XCC_ID, 0, 4)
	s_and_b32 s2, s2, 15
	v_writelane_b32 v254, s2, 6
	s_and_saveexec_b64 s[2:3], vcc
	s_cbranch_execz .LBB0_6
	s_mov_b64 s[4:5], exec
	v_mbcnt_lo_u32_b32 v1, s4, 0
	v_mbcnt_hi_u32_b32 v1, s5, v1
	v_cmp_eq_u32_e32 vcc, 0, v1
	s_and_b64 s[8:9], exec, vcc
	s_mov_b64 exec, s[8:9]
	s_cbranch_execz .LBB0_6
	v_readlane_b32 s7, v254, 6
	s_lshl_b32 s7, s7, 8
	s_bcnt1_i32_b64 s4, s[4:5]
	v_mov_b32_e32 v1, s7
	v_mov_b32_e32 v2, s4
	global_atomic_add v1, v2, s[74:75] offset:1024

; #define PG8_STAGE(...) PG8_STAGE_(__VA_ARGS__, 0u)
; #define PG8_WAIT_V(n) asm volatile("s_waitcnt vmcnt(" #n ")" ::: "memory")
; #define PG8_WAIT_L(n) asm volatile("s_waitcnt lgkmcnt(" #n ")" ::: "memory")
; #define PG8_BAR __builtin_amdgcn_s_barrier()
; #define PG8_SCHED __builtin_amdgcn_sched_barrier(0)
; template <class Epi, class Sched, bool ALIGN_EPI = true, bool SP2 = true>
; __device__ __forceinline__ void gemm_phase(LAS unsigned char* lds, const Gemm g, const Sched& S, const Epi& E) {
;     ...
;             const bool last = (t == nt - 2);
;             const char* a1 = cA + (size_t)(t + 1) * kstep;
;             const char* a2 = last ? nA : cA + (size_t)(t + 2) * kstep; const char* b2 = last ? nB : cB + (size_t)(t + 2) * kstep;
;             const char* a3 = a2 + kstep; const char* b3 = b2 + kstep;
;             if constexpr (SP2) {
;             PG8_LDB(B0, 0, 0); PG8_LDB(B1, 0, 1); PG8_SCHED; PG8_LDA(At, 0, 0); PG8_STAGE(PG8_SA(1, 1), a1, voffAh);
;             PG8_WAIT_V(8); PG8_WAIT_L(0); PG8_BAR; PG8_MMA(0, 0, At, B0); PG8_MMA(0, 1, At, B1); PG8_BAR; PG8_SCHED;
;             if constexpr (!Epi::HALF_M) PG8_LDA(At, 0, 1); PG8_STAGE(PG8_SB(0, 0), b2, voffB); PG8_STAGE(PG8_SB(0, 1), b2, voffBh); PG8_STAGE(PG8_SA(0, 0), a2, voffA);
;             PG8_WAIT_V(8); PG8_WAIT_L(0); PG8_BAR; if constexpr (!Epi::HALF_M) { PG8_MMA(1, 0, At, B0); PG8_MMA(1, 1, At, B1); } PG8_BAR; PG8_SCHED;
.LBB0_638:
	ds_read_b128 v[30:33], v146
	ds_read_b128 v[152:155], v146 offset:1024
	ds_read_b128 v[156:159], v146 offset:2048
	ds_read_b128 v[160:163], v146 offset:3072
	ds_read_b128 v[164:167], v147
	ds_read_b128 v[168:171], v147 offset:1024
	ds_read_b128 v[172:175], v147 offset:2048
	ds_read_b128 v[176:179], v147 offset:3072
	s_add_i32 s60, s24, 2
	s_add_u32 s26, s22, 0x80
	s_addc_u32 s25, s23, 0
	s_cmp_eq_u32 s54, s24
	s_cselect_b32 s24, s5, s26
	s_cselect_b32 s25, s3, s25
	s_cselect_b32 s27, s15, s59
	s_cselect_b32 s26, s17, s58
	v_mov_b32_e32 v34, v142
	ds_read_b128 v[180:183], v148
	ds_read_b128 v[184:187], v148 offset:1024
	ds_read_b128 v[188:191], v148 offset:2048
	ds_read_b128 v[192:195], v148 offset:3072
	ds_read_b128 v[206:209], v148 offset:4096
	ds_read_b128 v[210:213], v148 offset:5120
	ds_read_b128 v[214:217], v148 offset:6144
	ds_read_b128 v[218:221], v148 offset:7168
	s_add_i32 m0, s43, 0xc000
	s_nop 0
	global_load_lds_dwordx4 v34, s[22:23]
	v_mov_b32_e32 v34, v143
	s_add_i32 m0, s43, 0xe000
	s_nop 0
	global_load_lds_dwordx4 v34, s[22:23]
	s_waitcnt vmcnt(8)
	s_waitcnt lgkmcnt(0)
	s_barrier
	s_waitcnt lgkmcnt(0)
	v_mfma_f32_16x16x32_f16 v[132:135], v[30:33], v[180:183], v[132:135]
	v_mfma_f32_16x16x32_f16 v[128:131], v[156:159], v[180:183], v[128:131]
	v_mfma_f32_16x16x32_f16 v[116:119], v[30:33], v[188:191], v[116:119]
	v_mfma_f32_16x16x32_f16 v[112:115], v[156:159], v[188:191], v[112:115]
	v_mfma_f32_16x16x32_f16 v[100:103], v[30:33], v[206:209], v[100:103]
	v_mfma_f32_16x16x32_f16 v[96:99], v[156:159], v[206:209], v[96:99]
	v_mfma_f32_16x16x32_f16 v[84:87], v[30:33], v[214:217], v[84:87]
	v_mfma_f32_16x16x32_f16 v[80:83], v[156:159], v[214:217], v[80:83]
	v_mfma_f32_16x16x32_f16 v[132:135], v[152:155], v[184:187], v[132:135]
	v_mfma_f32_16x16x32_f16 v[128:131], v[160:163], v[184:187], v[128:131]
	v_mfma_f32_16x16x32_f16 v[116:119], v[152:155], v[192:195], v[116:119]
	v_mfma_f32_16x16x32_f16 v[112:115], v[160:163], v[192:195], v[112:115]
	v_mfma_f32_16x16x32_f16 v[100:103], v[152:155], v[210:213], v[100:103]
	v_mfma_f32_16x16x32_f16 v[96:99], v[160:163], v[210:213], v[96:99]
	v_mfma_f32_16x16x32_f16 v[84:87], v[152:155], v[218:221], v[84:87]
	v_mfma_f32_16x16x32_f16 v[80:83], v[160:163], v[218:221], v[80:83]
	v_mfma_f32_16x16x32_f16 v[124:127], v[164:167], v[180:183], v[124:127]
	v_mfma_f32_16x16x32_f16 v[120:123], v[172:175], v[180:183], v[120:123]
	v_mfma_f32_16x16x32_f16 v[108:111], v[164:167], v[188:191], v[108:111]
	v_mfma_f32_16x16x32_f16 v[104:107], v[172:175], v[188:191], v[104:107]
	v_mfma_f32_16x16x32_f16 v[92:95], v[164:167], v[206:209], v[92:95]
	v_mfma_f32_16x16x32_f16 v[88:91], v[172:175], v[206:209], v[88:91]
	v_mfma_f32_16x16x32_f16 v[76:79], v[164:167], v[214:217], v[76:79]
	v_mfma_f32_16x16x32_f16 v[72:75], v[172:175], v[214:217], v[72:75]
	v_mfma_f32_16x16x32_f16 v[124:127], v[168:171], v[184:187], v[124:127]
	v_mfma_f32_16x16x32_f16 v[120:123], v[176:179], v[184:187], v[120:123]
	v_mfma_f32_16x16x32_f16 v[108:111], v[168:171], v[192:195], v[108:111]
	v_mfma_f32_16x16x32_f16 v[104:107], v[176:179], v[192:195], v[104:107]
	v_mfma_f32_16x16x32_f16 v[92:95], v[168:171], v[210:213], v[92:95]
	v_mfma_f32_16x16x32_f16 v[88:91], v[176:179], v[210:213], v[88:91]
	v_mfma_f32_16x16x32_f16 v[76:79], v[168:171], v[218:221], v[76:79]
	v_mfma_f32_16x16x32_f16 v[72:75], v[176:179], v[218:221], v[72:75]
	s_barrier
	v_mov_b32_e32 v34, v137
	s_mov_b32 m0, s39
	ds_read_b128 v[180:183], v148 offset:16384
	ds_read_b128 v[184:187], v148 offset:17408
	ds_read_b128 v[188:191], v148 offset:18432
	ds_read_b128 v[192:195], v148 offset:19456
	ds_read_b128 v[206:209], v148 offset:20480
	ds_read_b128 v[210:213], v148 offset:21504
	ds_read_b128 v[214:217], v148 offset:22528
	ds_read_b128 v[218:221], v148 offset:23552
	s_nop 0
	global_load_lds_dwordx4 v34, s[26:27]
	v_mov_b32_e32 v34, v139
	s_mov_b32 m0, s40
	s_nop 0
	global_load_lds_dwordx4 v34, s[26:27]
	v_mov_b32_e32 v34, v140
	s_mov_b32 m0, s41
	s_nop 0
	global_load_lds_dwordx4 v34, s[26:27]
	v_mov_b32_e32 v34, v141
	s_mov_b32 m0, s42
	s_nop 0
	global_load_lds_dwordx4 v34, s[26:27]
	v_mov_b32_e32 v34, v136
	s_mov_b32 m0, s43
	s_nop 0
	global_load_lds_dwordx4 v34, s[24:25]
	v_mov_b32_e32 v34, v138
	s_mov_b32 m0, s44
	s_nop 0
	global_load_lds_dwordx4 v34, s[24:25]
	s_waitcnt vmcnt(8)
	s_waitcnt lgkmcnt(0)
	s_barrier
	s_waitcnt lgkmcnt(0)
	v_mfma_f32_16x16x32_f16 v[68:71], v[30:33], v[180:183], v[68:71]
	v_mfma_f32_16x16x32_f16 v[64:67], v[156:159], v[180:183], v[64:67]
	v_mfma_f32_16x16x32_f16 v[52:55], v[30:33], v[188:191], v[52:55]
	v_mfma_f32_16x16x32_f16 v[48:51], v[156:159], v[188:191], v[48:51]
	v_mfma_f32_16x16x32_f16 v[36:39], v[30:33], v[206:209], v[36:39]
	v_mfma_f32_16x16x32_f16 v[26:29], v[156:159], v[206:209], v[26:29]
	v_mfma_f32_16x16x32_f16 v[14:17], v[30:33], v[214:217], v[14:17]
	v_mfma_f32_16x16x32_f16 v[10:13], v[156:159], v[214:217], v[10:13]
	v_mfma_f32_16x16x32_f16 v[68:71], v[152:155], v[184:187], v[68:71]
	v_mfma_f32_16x16x32_f16 v[64:67], v[160:163], v[184:187], v[64:67]
	v_mfma_f32_16x16x32_f16 v[52:55], v[152:155], v[192:195], v[52:55]
	v_mfma_f32_16x16x32_f16 v[48:51], v[160:163], v[192:195], v[48:51]
	v_mfma_f32_16x16x32_f16 v[36:39], v[152:155], v[210:213], v[36:39]
	v_mfma_f32_16x16x32_f16 v[26:29], v[160:163], v[210:213], v[26:29]
	v_mfma_f32_16x16x32_f16 v[14:17], v[152:155], v[218:221], v[14:17]
	v_mfma_f32_16x16x32_f16 v[10:13], v[160:163], v[218:221], v[10:13]
	v_mfma_f32_16x16x32_f16 v[56:59], v[172:175], v[180:183], v[56:59]
	v_mfma_f32_16x16x32_f16 v[44:47], v[164:167], v[188:191], v[44:47]
	v_mfma_f32_16x16x32_f16 v[40:43], v[172:175], v[188:191], v[40:43]
	v_mfma_f32_16x16x32_f16 v[22:25], v[164:167], v[206:209], v[22:25]
	v_mfma_f32_16x16x32_f16 v[18:21], v[172:175], v[206:209], v[18:21]
	v_mfma_f32_16x16x32_f16 v[6:9], v[164:167], v[214:217], v[6:9]
	v_mfma_f32_16x16x32_f16 v[2:5], v[172:175], v[214:217], v[2:5]
	v_mfma_f32_16x16x32_f16 v[30:33], v[164:167], v[180:183], v[60:63]
	v_mfma_f32_16x16x32_f16 v[56:59], v[176:179], v[184:187], v[56:59]
	v_mfma_f32_16x16x32_f16 v[44:47], v[168:171], v[192:195], v[44:47]
	v_mfma_f32_16x16x32_f16 v[40:43], v[176:179], v[192:195], v[40:43]
	v_mfma_f32_16x16x32_f16 v[22:25], v[168:171], v[210:213], v[22:25]
	v_mfma_f32_16x16x32_f16 v[18:21], v[176:179], v[210:213], v[18:21]
	v_mfma_f32_16x16x32_f16 v[6:9], v[168:171], v[218:221], v[6:9]
	v_mfma_f32_16x16x32_f16 v[2:5], v[176:179], v[218:221], v[2:5]
	v_mfma_f32_16x16x32_f16 v[30:33], v[168:171], v[184:187], v[30:33]
	s_barrier
; #define PG8_STAGE(...) PG8_STAGE_(__VA_ARGS__, 0u)
; #define PG8_WAIT_V(n) asm volatile("s_waitcnt vmcnt(" #n ")" ::: "memory")
; #define PG8_WAIT_L(n) asm volatile("s_waitcnt lgkmcnt(" #n ")" ::: "memory")
; #define PG8_BAR __builtin_amdgcn_s_barrier()
; #define PG8_SCHED __builtin_amdgcn_sched_barrier(0)
; template <class Epi, class Sched, bool ALIGN_EPI = true, bool SP2 = true>
; __device__ __forceinline__ void gemm_phase(LAS unsigned char* lds, const Gemm g, const Sched& S, const Epi& E) {
;     ...
;             PG8_LDB(B0, 1, 0); PG8_LDB(B1, 1, 1); PG8_SCHED; PG8_LDA(At, 1, 0); PG8_STAGE(PG8_SA(0, 1), a2, voffAh);
;             PG8_WAIT_V(8); PG8_WAIT_L(0); PG8_BAR; PG8_MMA(0, 0, At, B0); PG8_MMA(0, 1, At, B1); PG8_BAR; PG8_SCHED;
	ds_read_b128 v[60:63], v149
	ds_read_b128 v[152:155], v149 offset:1024
	ds_read_b128 v[156:159], v149 offset:2048
	ds_read_b128 v[160:163], v149 offset:3072
	ds_read_b128 v[164:167], v150
	ds_read_b128 v[168:171], v150 offset:1024
	ds_read_b128 v[172:175], v150 offset:2048
	ds_read_b128 v[176:179], v150 offset:3072
	v_mov_b32_e32 v34, v142
	s_mov_b32 m0, s45
	ds_read_b128 v[180:183], v148 offset:32768
	ds_read_b128 v[184:187], v148 offset:33792
	ds_read_b128 v[188:191], v148 offset:34816
	ds_read_b128 v[192:195], v148 offset:35840
	ds_read_b128 v[206:209], v148 offset:36864
	ds_read_b128 v[210:213], v148 offset:37888
	ds_read_b128 v[214:217], v148 offset:38912
	ds_read_b128 v[218:221], v148 offset:39936
	s_nop 0
	global_load_lds_dwordx4 v34, s[24:25]
	v_mov_b32_e32 v34, v143
	s_mov_b32 m0, s46
	s_nop 0
	global_load_lds_dwordx4 v34, s[24:25]
	s_waitcnt vmcnt(8)
	s_waitcnt lgkmcnt(0)
	s_barrier
	s_waitcnt lgkmcnt(0)
	v_mfma_f32_16x16x32_f16 v[132:135], v[60:63], v[180:183], v[132:135]
	v_mfma_f32_16x16x32_f16 v[128:131], v[156:159], v[180:183], v[128:131]
	v_mfma_f32_16x16x32_f16 v[116:119], v[60:63], v[188:191], v[116:119]
	v_mfma_f32_16x16x32_f16 v[112:115], v[156:159], v[188:191], v[112:115]
	v_mfma_f32_16x16x32_f16 v[100:103], v[60:63], v[206:209], v[100:103]
	v_mfma_f32_16x16x32_f16 v[96:99], v[156:159], v[206:209], v[96:99]
	v_mfma_f32_16x16x32_f16 v[84:87], v[60:63], v[214:217], v[84:87]
	v_mfma_f32_16x16x32_f16 v[80:83], v[156:159], v[214:217], v[80:83]
	v_mfma_f32_16x16x32_f16 v[132:135], v[152:155], v[184:187], v[132:135]
	v_mfma_f32_16x16x32_f16 v[128:131], v[160:163], v[184:187], v[128:131]
	v_mfma_f32_16x16x32_f16 v[116:119], v[152:155], v[192:195], v[116:119]
	v_mfma_f32_16x16x32_f16 v[112:115], v[160:163], v[192:195], v[112:115]
	v_mfma_f32_16x16x32_f16 v[100:103], v[152:155], v[210:213], v[100:103]
	v_mfma_f32_16x16x32_f16 v[96:99], v[160:163], v[210:213], v[96:99]
	v_mfma_f32_16x16x32_f16 v[84:87], v[152:155], v[218:221], v[84:87]
	v_mfma_f32_16x16x32_f16 v[80:83], v[160:163], v[218:221], v[80:83]
	v_mfma_f32_16x16x32_f16 v[124:127], v[164:167], v[180:183], v[124:127]
	v_mfma_f32_16x16x32_f16 v[120:123], v[172:175], v[180:183], v[120:123]
	v_mfma_f32_16x16x32_f16 v[108:111], v[164:167], v[188:191], v[108:111]
	v_mfma_f32_16x16x32_f16 v[104:107], v[172:175], v[188:191], v[104:107]
	v_mfma_f32_16x16x32_f16 v[92:95], v[164:167], v[206:209], v[92:95]
	v_mfma_f32_16x16x32_f16 v[88:91], v[172:175], v[206:209], v[88:91]
	v_mfma_f32_16x16x32_f16 v[76:79], v[164:167], v[214:217], v[76:79]
	v_mfma_f32_16x16x32_f16 v[72:75], v[172:175], v[214:217], v[72:75]
	v_mfma_f32_16x16x32_f16 v[124:127], v[168:171], v[184:187], v[124:127]
	v_mfma_f32_16x16x32_f16 v[120:123], v[176:179], v[184:187], v[120:123]
	v_mfma_f32_16x16x32_f16 v[108:111], v[168:171], v[192:195], v[108:111]
	v_mfma_f32_16x16x32_f16 v[104:107], v[176:179], v[192:195], v[104:107]
	v_mfma_f32_16x16x32_f16 v[92:95], v[168:171], v[210:213], v[92:95]
	v_mfma_f32_16x16x32_f16 v[88:91], v[176:179], v[210:213], v[88:91]
	v_mfma_f32_16x16x32_f16 v[76:79], v[168:171], v[218:221], v[76:79]
	v_mfma_f32_16x16x32_f16 v[72:75], v[176:179], v[218:221], v[72:75]
	s_barrier
; #define PG8_STAGE(...) PG8_STAGE_(__VA_ARGS__, 0u)
; #define PG8_WAIT_V(n) asm volatile("s_waitcnt vmcnt(" #n ")" ::: "memory")
; #define PG8_WAIT_L(n) asm volatile("s_waitcnt lgkmcnt(" #n ")" ::: "memory")
; #define PG8_BAR __builtin_amdgcn_s_barrier()
; #define PG8_SCHED __builtin_amdgcn_sched_barrier(0)
; template <class Epi, class Sched, bool ALIGN_EPI = true, bool SP2 = true>
; __device__ __forceinline__ void gemm_phase(LAS unsigned char* lds, const Gemm g, const Sched& S, const Epi& E) {
;     ...
;             if constexpr (!Epi::HALF_M) PG8_LDA(At, 1, 1); PG8_STAGE(PG8_SB(1, 0), b3, voffB); PG8_STAGE(PG8_SB(1, 1), b3, voffBh); PG8_STAGE(PG8_SA(1, 0), a3, voffA);
;             PG8_WAIT_V(8); PG8_WAIT_L(0); PG8_BAR; if constexpr (!Epi::HALF_M) { PG8_MMA(1, 0, At, B0); PG8_MMA(1, 1, At, B1); } PG8_BAR; PG8_SCHED;
	v_mov_b32_e32 v34, v137
	ds_read_b128 v[180:183], v148 offset:49152
	ds_read_b128 v[184:187], v148 offset:50176
	ds_read_b128 v[188:191], v148 offset:51200
	ds_read_b128 v[192:195], v148 offset:52224
	ds_read_b128 v[206:209], v148 offset:53248
	ds_read_b128 v[210:213], v148 offset:54272
	ds_read_b128 v[214:217], v148 offset:55296
	ds_read_b128 v[218:221], v148 offset:56320
	s_mov_b32 m0, s47
	v_lshl_add_u64 v[222:223], s[26:27], 0, v[34:35]
	v_lshl_add_u64 v[222:223], v[222:223], 0, s[80:81]
	v_mov_b32_e32 v34, v139
	global_load_lds_dwordx4 v[222:223], off
	s_mov_b32 m0, s48
	v_lshl_add_u64 v[222:223], s[26:27], 0, v[34:35]
	v_lshl_add_u64 v[222:223], v[222:223], 0, s[80:81]
	v_mov_b32_e32 v34, v140
	global_load_lds_dwordx4 v[222:223], off
	s_mov_b32 m0, s51
	v_lshl_add_u64 v[222:223], s[26:27], 0, v[34:35]
	v_lshl_add_u64 v[222:223], v[222:223], 0, s[80:81]
	v_mov_b32_e32 v34, v141
	global_load_lds_dwordx4 v[222:223], off
	s_mov_b32 m0, s52
	v_lshl_add_u64 v[222:223], s[26:27], 0, v[34:35]
	v_lshl_add_u64 v[222:223], v[222:223], 0, s[80:81]
	v_mov_b32_e32 v34, v136
	global_load_lds_dwordx4 v[222:223], off
	s_mov_b32 m0, s49
	v_lshl_add_u64 v[222:223], s[24:25], 0, v[34:35]
	v_lshl_add_u64 v[222:223], v[222:223], 0, s[80:81]
	v_mov_b32_e32 v34, v138
	global_load_lds_dwordx4 v[222:223], off
	s_mov_b32 m0, s50
	v_lshl_add_u64 v[222:223], s[24:25], 0, v[34:35]
	v_lshl_add_u64 v[222:223], v[222:223], 0, s[80:81]
	global_load_lds_dwordx4 v[222:223], off
	s_waitcnt vmcnt(8)
	s_waitcnt lgkmcnt(0)
	s_barrier
	s_waitcnt lgkmcnt(0)
	v_mfma_f32_16x16x32_f16 v[68:71], v[60:63], v[180:183], v[68:71]
	v_mfma_f32_16x16x32_f16 v[64:67], v[156:159], v[180:183], v[64:67]
	v_mfma_f32_16x16x32_f16 v[52:55], v[60:63], v[188:191], v[52:55]
	v_mfma_f32_16x16x32_f16 v[48:51], v[156:159], v[188:191], v[48:51]
	v_mfma_f32_16x16x32_f16 v[36:39], v[60:63], v[206:209], v[36:39]
	v_mfma_f32_16x16x32_f16 v[26:29], v[156:159], v[206:209], v[26:29]
	v_mfma_f32_16x16x32_f16 v[14:17], v[60:63], v[214:217], v[14:17]
	v_mfma_f32_16x16x32_f16 v[10:13], v[156:159], v[214:217], v[10:13]
	v_mfma_f32_16x16x32_f16 v[68:71], v[152:155], v[184:187], v[68:71]
	v_mfma_f32_16x16x32_f16 v[64:67], v[160:163], v[184:187], v[64:67]
	v_mfma_f32_16x16x32_f16 v[52:55], v[152:155], v[192:195], v[52:55]
	v_mfma_f32_16x16x32_f16 v[48:51], v[160:163], v[192:195], v[48:51]
	v_mfma_f32_16x16x32_f16 v[36:39], v[152:155], v[210:213], v[36:39]
	v_mfma_f32_16x16x32_f16 v[26:29], v[160:163], v[210:213], v[26:29]
	v_mfma_f32_16x16x32_f16 v[14:17], v[152:155], v[218:221], v[14:17]
	v_mfma_f32_16x16x32_f16 v[10:13], v[160:163], v[218:221], v[10:13]
	v_mfma_f32_16x16x32_f16 v[30:33], v[164:167], v[180:183], v[30:33]
	v_mfma_f32_16x16x32_f16 v[60:63], v[168:171], v[184:187], v[30:33]
	v_mfma_f32_16x16x32_f16 v[30:33], v[172:175], v[180:183], v[56:59]
	v_mfma_f32_16x16x32_f16 v[56:59], v[176:179], v[184:187], v[30:33]
	v_mfma_f32_16x16x32_f16 v[30:33], v[164:167], v[188:191], v[44:47]
	v_mfma_f32_16x16x32_f16 v[44:47], v[168:171], v[192:195], v[30:33]
	v_mfma_f32_16x16x32_f16 v[30:33], v[172:175], v[188:191], v[40:43]
	v_mfma_f32_16x16x32_f16 v[22:25], v[164:167], v[206:209], v[22:25]
	v_mfma_f32_16x16x32_f16 v[18:21], v[172:175], v[206:209], v[18:21]
	v_mfma_f32_16x16x32_f16 v[6:9], v[164:167], v[214:217], v[6:9]
	v_mfma_f32_16x16x32_f16 v[2:5], v[172:175], v[214:217], v[2:5]
	v_mfma_f32_16x16x32_f16 v[40:43], v[176:179], v[192:195], v[30:33]
	v_mfma_f32_16x16x32_f16 v[22:25], v[168:171], v[210:213], v[22:25]
	v_mfma_f32_16x16x32_f16 v[18:21], v[176:179], v[210:213], v[18:21]
	v_mfma_f32_16x16x32_f16 v[6:9], v[168:171], v[218:221], v[6:9]
	v_mfma_f32_16x16x32_f16 v[2:5], v[176:179], v[218:221], v[2:5]
	s_barrier
	s_add_u32 s22, s22, 0x100
	s_addc_u32 s23, s23, 0
	s_add_u32 s58, s58, 0x100
	s_addc_u32 s59, s59, 0
	s_cmp_ge_i32 s60, s53
	s_mov_b32 s24, s60
	s_cbranch_scc0 .LBB0_638

; #define PG8_STAGE(...) PG8_STAGE_(__VA_ARGS__, 0u)
; #define PG8_WAIT_V(n) asm volatile("s_waitcnt vmcnt(" #n ")" ::: "memory")
; #define PG8_WAIT_L(n) asm volatile("s_waitcnt lgkmcnt(" #n ")" ::: "memory")
; #define PG8_BAR __builtin_amdgcn_s_barrier()
; #define PG8_SCHED __builtin_amdgcn_sched_barrier(0)
; template <class Epi, class Sched, bool ALIGN_EPI = true, bool SP2 = true>
; __device__ __forceinline__ void gemm_phase(LAS unsigned char* lds, const Gemm g, const Sched& S, const Epi& E) {
;     ...
;             const bool last = (t == nt - 2);
;             const char* a1 = cA + (size_t)(t + 1) * kstep;
;             const char* a2 = last ? nA : cA + (size_t)(t + 2) * kstep; const char* b2 = last ? nB : cB + (size_t)(t + 2) * kstep;
;             const char* a3 = a2 + kstep; const char* b3 = b2 + kstep;
;             if constexpr (SP2) {
;             PG8_LDB(B0, 0, 0); PG8_LDB(B1, 0, 1); PG8_SCHED; PG8_LDA(At, 0, 0); PG8_STAGE(PG8_SA(1, 1), a1, voffAh);
;             PG8_WAIT_V(8); PG8_WAIT_L(0); PG8_BAR; PG8_MMA(0, 0, At, B0); PG8_MMA(0, 1, At, B1); PG8_BAR; PG8_SCHED;
;             if constexpr (!Epi::HALF_M) PG8_LDA(At, 0, 1); PG8_STAGE(PG8_SB(0, 0), b2, voffB); PG8_STAGE(PG8_SB(0, 1), b2, voffBh); PG8_STAGE(PG8_SA(0, 0), a2, voffA);
;             PG8_WAIT_V(8); PG8_WAIT_L(0); PG8_BAR; if constexpr (!Epi::HALF_M) { PG8_MMA(1, 0, At, B0); PG8_MMA(1, 1, At, B1); } PG8_BAR; PG8_SCHED;
.LBB0_697:
	v_add_u32_e32 v2, s35, v172
	v_add_u32_e32 v14, s38, v172
	ds_read_b128 v[18:21], v2
	ds_read_b128 v[22:25], v2 offset:1024
	ds_read_b128 v[26:29], v2 offset:2048
	ds_read_b128 v[30:33], v2 offset:3072
	ds_read_b128 v[2:5], v14
	ds_read_b128 v[6:9], v14 offset:1024
	ds_read_b128 v[10:13], v14 offset:2048
	ds_read_b128 v[14:17], v14 offset:3072
	s_add_i32 s62, s20, 2
	s_add_u32 s22, s18, 0x80
	s_addc_u32 s21, s19, 0
	s_cmp_eq_u32 s54, s20
	s_cselect_b32 s20, s11, s22
	s_cselect_b32 s21, s9, s21
	s_cselect_b32 s23, s30, s61
	s_cselect_b32 s22, s59, s60
	v_mov_b32_e32 v34, v170
	ds_read_b128 v[176:179], v174
	ds_read_b128 v[180:183], v174 offset:1024
	ds_read_b128 v[184:187], v174 offset:2048
	ds_read_b128 v[188:191], v174 offset:3072
	ds_read_b128 v[206:209], v174 offset:4096
	ds_read_b128 v[210:213], v174 offset:5120
	ds_read_b128 v[214:217], v174 offset:6144
	ds_read_b128 v[218:221], v174 offset:7168
	s_add_i32 m0, s41, 0xc000
	s_nop 0
	global_load_lds_dwordx4 v34, s[18:19]
	v_mov_b32_e32 v34, v171
	s_add_i32 m0, s41, 0xe000
	s_nop 0
	global_load_lds_dwordx4 v34, s[18:19]
	s_waitcnt vmcnt(8)
	s_waitcnt lgkmcnt(0)
	s_barrier
	s_waitcnt lgkmcnt(0)
	v_mfma_scale_f32_16x16x128_f8f6f4 v[160:163], v[18:25], v[176:183], v[160:163], v1, v1 op_sel_hi:[0,0,0]
	v_mfma_scale_f32_16x16x128_f8f6f4 v[156:159], v[26:33], v[176:183], v[156:159], v1, v1 op_sel_hi:[0,0,0]
	v_mfma_scale_f32_16x16x128_f8f6f4 v[144:147], v[18:25], v[184:191], v[144:147], v1, v1 op_sel_hi:[0,0,0]
	v_mfma_scale_f32_16x16x128_f8f6f4 v[140:143], v[26:33], v[184:191], v[140:143], v1, v1 op_sel_hi:[0,0,0]
	v_mfma_scale_f32_16x16x128_f8f6f4 v[128:131], v[18:25], v[206:213], v[128:131], v1, v1 op_sel_hi:[0,0,0]
	v_mfma_scale_f32_16x16x128_f8f6f4 v[124:127], v[26:33], v[206:213], v[124:127], v1, v1 op_sel_hi:[0,0,0]
	v_mfma_scale_f32_16x16x128_f8f6f4 v[112:115], v[18:25], v[214:221], v[112:115], v1, v1 op_sel_hi:[0,0,0]
	v_mfma_scale_f32_16x16x128_f8f6f4 v[108:111], v[26:33], v[214:221], v[108:111], v1, v1 op_sel_hi:[0,0,0]
	v_mfma_scale_f32_16x16x128_f8f6f4 v[152:155], v[2:9], v[176:183], v[152:155], v1, v1 op_sel_hi:[0,0,0]
	v_mfma_scale_f32_16x16x128_f8f6f4 v[148:151], v[10:17], v[176:183], v[148:151], v1, v1 op_sel_hi:[0,0,0]
	v_mfma_scale_f32_16x16x128_f8f6f4 v[136:139], v[2:9], v[184:191], v[136:139], v1, v1 op_sel_hi:[0,0,0]
	v_mfma_scale_f32_16x16x128_f8f6f4 v[132:135], v[10:17], v[184:191], v[132:135], v1, v1 op_sel_hi:[0,0,0]
	v_mfma_scale_f32_16x16x128_f8f6f4 v[120:123], v[2:9], v[206:213], v[120:123], v1, v1 op_sel_hi:[0,0,0]
	v_mfma_scale_f32_16x16x128_f8f6f4 v[116:119], v[10:17], v[206:213], v[116:119], v1, v1 op_sel_hi:[0,0,0]
	v_mfma_scale_f32_16x16x128_f8f6f4 v[104:107], v[2:9], v[214:221], v[104:107], v1, v1 op_sel_hi:[0,0,0]
	v_mfma_scale_f32_16x16x128_f8f6f4 v[100:103], v[10:17], v[214:221], v[100:103], v1, v1 op_sel_hi:[0,0,0]
	s_barrier
	v_mov_b32_e32 v34, v165
	s_mov_b32 m0, s36
	ds_read_b128 v[176:179], v174 offset:16384
	ds_read_b128 v[180:183], v174 offset:17408
	ds_read_b128 v[184:187], v174 offset:18432
	ds_read_b128 v[188:191], v174 offset:19456
	ds_read_b128 v[206:209], v174 offset:20480
	ds_read_b128 v[210:213], v174 offset:21504
	ds_read_b128 v[214:217], v174 offset:22528
	ds_read_b128 v[218:221], v174 offset:23552
	s_nop 0
	global_load_lds_dwordx4 v34, s[22:23]
	v_mov_b32_e32 v34, v167
	s_mov_b32 m0, s37
	s_nop 0
	global_load_lds_dwordx4 v34, s[22:23]
	v_mov_b32_e32 v34, v168
	s_mov_b32 m0, s39
	s_nop 0
	global_load_lds_dwordx4 v34, s[22:23]
	v_mov_b32_e32 v34, v169
	s_mov_b32 m0, s40
	s_nop 0
	global_load_lds_dwordx4 v34, s[22:23]
	v_mov_b32_e32 v34, v164
	s_mov_b32 m0, s41
	s_nop 0
	global_load_lds_dwordx4 v34, s[20:21]
	v_mov_b32_e32 v34, v166
	s_mov_b32 m0, s42
	s_nop 0
	global_load_lds_dwordx4 v34, s[20:21]
	s_waitcnt vmcnt(8)
	s_waitcnt lgkmcnt(0)
	s_barrier
	s_waitcnt lgkmcnt(0)
	v_mfma_scale_f32_16x16x128_f8f6f4 v[96:99], v[18:25], v[176:183], v[96:99], v1, v1 op_sel_hi:[0,0,0]
	v_mfma_scale_f32_16x16x128_f8f6f4 v[92:95], v[26:33], v[176:183], v[92:95], v1, v1 op_sel_hi:[0,0,0]
	v_mfma_scale_f32_16x16x128_f8f6f4 v[80:83], v[18:25], v[184:191], v[80:83], v1, v1 op_sel_hi:[0,0,0]
	v_mfma_scale_f32_16x16x128_f8f6f4 v[76:79], v[26:33], v[184:191], v[76:79], v1, v1 op_sel_hi:[0,0,0]
	v_mfma_scale_f32_16x16x128_f8f6f4 v[64:67], v[18:25], v[206:213], v[64:67], v1, v1 op_sel_hi:[0,0,0]
	v_mfma_scale_f32_16x16x128_f8f6f4 v[60:63], v[26:33], v[206:213], v[60:63], v1, v1 op_sel_hi:[0,0,0]
	v_mfma_scale_f32_16x16x128_f8f6f4 v[48:51], v[18:25], v[214:221], v[48:51], v1, v1 op_sel_hi:[0,0,0]
	v_mfma_scale_f32_16x16x128_f8f6f4 v[44:47], v[26:33], v[214:221], v[44:47], v1, v1 op_sel_hi:[0,0,0]
	v_mfma_scale_f32_16x16x128_f8f6f4 v[88:91], v[2:9], v[176:183], v[88:91], v1, v1 op_sel_hi:[0,0,0]
	v_mfma_scale_f32_16x16x128_f8f6f4 v[84:87], v[10:17], v[176:183], v[84:87], v1, v1 op_sel_hi:[0,0,0]
	v_mfma_scale_f32_16x16x128_f8f6f4 v[72:75], v[2:9], v[184:191], v[72:75], v1, v1 op_sel_hi:[0,0,0]
	v_mfma_scale_f32_16x16x128_f8f6f4 v[68:71], v[10:17], v[184:191], v[68:71], v1, v1 op_sel_hi:[0,0,0]
	v_mfma_scale_f32_16x16x128_f8f6f4 v[56:59], v[2:9], v[206:213], v[56:59], v1, v1 op_sel_hi:[0,0,0]
	v_mfma_scale_f32_16x16x128_f8f6f4 v[52:55], v[10:17], v[206:213], v[52:55], v1, v1 op_sel_hi:[0,0,0]
	v_mfma_scale_f32_16x16x128_f8f6f4 v[40:43], v[2:9], v[214:221], v[40:43], v1, v1 op_sel_hi:[0,0,0]
	v_mfma_scale_f32_16x16x128_f8f6f4 v[36:39], v[10:17], v[214:221], v[36:39], v1, v1 op_sel_hi:[0,0,0]
	s_barrier
; #define PG8_STAGE(...) PG8_STAGE_(__VA_ARGS__, 0u)
; #define PG8_WAIT_V(n) asm volatile("s_waitcnt vmcnt(" #n ")" ::: "memory")
; #define PG8_WAIT_L(n) asm volatile("s_waitcnt lgkmcnt(" #n ")" ::: "memory")
; #define PG8_BAR __builtin_amdgcn_s_barrier()
; #define PG8_SCHED __builtin_amdgcn_sched_barrier(0)
; template <class Epi, class Sched, bool ALIGN_EPI = true, bool SP2 = true>
; __device__ __forceinline__ void gemm_phase(LAS unsigned char* lds, const Gemm g, const Sched& S, const Epi& E) {
;     ...
;             PG8_LDB(B0, 1, 0); PG8_LDB(B1, 1, 1); PG8_SCHED; PG8_LDA(At, 1, 0); PG8_STAGE(PG8_SA(0, 1), a2, voffAh);
;             PG8_WAIT_V(8); PG8_WAIT_L(0); PG8_BAR; PG8_MMA(0, 0, At, B0); PG8_MMA(0, 1, At, B1); PG8_BAR; PG8_SCHED;
;             if constexpr (!Epi::HALF_M) PG8_LDA(At, 1, 1); PG8_STAGE(PG8_SB(1, 0), b3, voffB); PG8_STAGE(PG8_SB(1, 1), b3, voffBh); PG8_STAGE(PG8_SA(1, 0), a3, voffA);
;             PG8_WAIT_V(8); PG8_WAIT_L(0); PG8_BAR; if constexpr (!Epi::HALF_M) { PG8_MMA(1, 0, At, B0); PG8_MMA(1, 1, At, B1); } PG8_BAR; PG8_SCHED;
	v_add_u32_e32 v10, s46, v172
	v_add_u32_e32 v30, s51, v172
	ds_read_b128 v[2:5], v10
	ds_read_b128 v[6:9], v10 offset:1024
	ds_read_b128 v[18:21], v10 offset:2048
	ds_read_b128 v[22:25], v10 offset:3072
	ds_read_b128 v[10:13], v30
	ds_read_b128 v[14:17], v30 offset:1024
	ds_read_b128 v[26:29], v30 offset:2048
	ds_read_b128 v[30:33], v30 offset:3072
	v_mov_b32_e32 v34, v170
	s_mov_b32 m0, s43
	ds_read_b128 v[176:179], v174 offset:32768
	ds_read_b128 v[180:183], v174 offset:33792
	ds_read_b128 v[184:187], v174 offset:34816
	ds_read_b128 v[188:191], v174 offset:35840
	ds_read_b128 v[206:209], v174 offset:36864
	ds_read_b128 v[210:213], v174 offset:37888
	ds_read_b128 v[214:217], v174 offset:38912
	ds_read_b128 v[218:221], v174 offset:39936
	s_nop 0
	global_load_lds_dwordx4 v34, s[20:21]
	v_mov_b32_e32 v34, v171
	s_mov_b32 m0, s44
	s_nop 0
	global_load_lds_dwordx4 v34, s[20:21]
	s_waitcnt vmcnt(8)
	s_waitcnt lgkmcnt(0)
	s_barrier
	s_waitcnt lgkmcnt(0)
	v_mfma_scale_f32_16x16x128_f8f6f4 v[160:163], v[2:9], v[176:183], v[160:163], v1, v1 op_sel_hi:[0,0,0]
	v_mfma_scale_f32_16x16x128_f8f6f4 v[156:159], v[18:25], v[176:183], v[156:159], v1, v1 op_sel_hi:[0,0,0]
	v_mfma_scale_f32_16x16x128_f8f6f4 v[144:147], v[2:9], v[184:191], v[144:147], v1, v1 op_sel_hi:[0,0,0]
	v_mfma_scale_f32_16x16x128_f8f6f4 v[140:143], v[18:25], v[184:191], v[140:143], v1, v1 op_sel_hi:[0,0,0]
	v_mfma_scale_f32_16x16x128_f8f6f4 v[128:131], v[2:9], v[206:213], v[128:131], v1, v1 op_sel_hi:[0,0,0]
	v_mfma_scale_f32_16x16x128_f8f6f4 v[124:127], v[18:25], v[206:213], v[124:127], v1, v1 op_sel_hi:[0,0,0]
	v_mfma_scale_f32_16x16x128_f8f6f4 v[112:115], v[2:9], v[214:221], v[112:115], v1, v1 op_sel_hi:[0,0,0]
	v_mfma_scale_f32_16x16x128_f8f6f4 v[108:111], v[18:25], v[214:221], v[108:111], v1, v1 op_sel_hi:[0,0,0]
	v_mfma_scale_f32_16x16x128_f8f6f4 v[152:155], v[10:17], v[176:183], v[152:155], v1, v1 op_sel_hi:[0,0,0]
	v_mfma_scale_f32_16x16x128_f8f6f4 v[148:151], v[26:33], v[176:183], v[148:151], v1, v1 op_sel_hi:[0,0,0]
	v_mfma_scale_f32_16x16x128_f8f6f4 v[136:139], v[10:17], v[184:191], v[136:139], v1, v1 op_sel_hi:[0,0,0]
	v_mfma_scale_f32_16x16x128_f8f6f4 v[132:135], v[26:33], v[184:191], v[132:135], v1, v1 op_sel_hi:[0,0,0]
	v_mfma_scale_f32_16x16x128_f8f6f4 v[120:123], v[10:17], v[206:213], v[120:123], v1, v1 op_sel_hi:[0,0,0]
	v_mfma_scale_f32_16x16x128_f8f6f4 v[116:119], v[26:33], v[206:213], v[116:119], v1, v1 op_sel_hi:[0,0,0]
	v_mfma_scale_f32_16x16x128_f8f6f4 v[104:107], v[10:17], v[214:221], v[104:107], v1, v1 op_sel_hi:[0,0,0]
	v_mfma_scale_f32_16x16x128_f8f6f4 v[100:103], v[26:33], v[214:221], v[100:103], v1, v1 op_sel_hi:[0,0,0]
	s_barrier
	v_mov_b32_e32 v34, v165
	ds_read_b128 v[176:179], v174 offset:49152
	ds_read_b128 v[180:183], v174 offset:50176
	ds_read_b128 v[184:187], v174 offset:51200
	ds_read_b128 v[188:191], v174 offset:52224
	ds_read_b128 v[206:209], v174 offset:53248
	ds_read_b128 v[210:213], v174 offset:54272
	ds_read_b128 v[214:217], v174 offset:55296
	ds_read_b128 v[218:221], v174 offset:56320
	s_mov_b32 m0, s47
	v_lshl_add_u64 v[192:193], s[22:23], 0, v[34:35]
	v_lshl_add_u64 v[192:193], v[192:193], 0, s[80:81]
	v_mov_b32_e32 v34, v167
	global_load_lds_dwordx4 v[192:193], off
	s_mov_b32 m0, s48
	v_lshl_add_u64 v[192:193], s[22:23], 0, v[34:35]
	v_lshl_add_u64 v[192:193], v[192:193], 0, s[80:81]
	v_mov_b32_e32 v34, v168
	global_load_lds_dwordx4 v[192:193], off
	s_mov_b32 m0, s52
	v_lshl_add_u64 v[192:193], s[22:23], 0, v[34:35]
	v_lshl_add_u64 v[192:193], v[192:193], 0, s[80:81]
	v_mov_b32_e32 v34, v169
	global_load_lds_dwordx4 v[192:193], off
	s_mov_b32 m0, s53
	v_lshl_add_u64 v[192:193], s[22:23], 0, v[34:35]
	v_lshl_add_u64 v[192:193], v[192:193], 0, s[80:81]
	v_mov_b32_e32 v34, v164
	global_load_lds_dwordx4 v[192:193], off
	s_mov_b32 m0, s49
	v_lshl_add_u64 v[192:193], s[20:21], 0, v[34:35]
	v_lshl_add_u64 v[192:193], v[192:193], 0, s[80:81]
	v_mov_b32_e32 v34, v166
	global_load_lds_dwordx4 v[192:193], off
	s_mov_b32 m0, s50
	v_lshl_add_u64 v[192:193], s[20:21], 0, v[34:35]
	v_lshl_add_u64 v[192:193], v[192:193], 0, s[80:81]
	global_load_lds_dwordx4 v[192:193], off
	s_waitcnt vmcnt(8)
	s_waitcnt lgkmcnt(0)
	s_barrier
	s_waitcnt lgkmcnt(0)
	v_mfma_scale_f32_16x16x128_f8f6f4 v[96:99], v[2:9], v[176:183], v[96:99], v1, v1 op_sel_hi:[0,0,0]
	v_mfma_scale_f32_16x16x128_f8f6f4 v[92:95], v[18:25], v[176:183], v[92:95], v1, v1 op_sel_hi:[0,0,0]
	v_mfma_scale_f32_16x16x128_f8f6f4 v[80:83], v[2:9], v[184:191], v[80:83], v1, v1 op_sel_hi:[0,0,0]
	v_mfma_scale_f32_16x16x128_f8f6f4 v[76:79], v[18:25], v[184:191], v[76:79], v1, v1 op_sel_hi:[0,0,0]
	v_mfma_scale_f32_16x16x128_f8f6f4 v[64:67], v[2:9], v[206:213], v[64:67], v1, v1 op_sel_hi:[0,0,0]
	v_mfma_scale_f32_16x16x128_f8f6f4 v[60:63], v[18:25], v[206:213], v[60:63], v1, v1 op_sel_hi:[0,0,0]
	v_mfma_scale_f32_16x16x128_f8f6f4 v[48:51], v[2:9], v[214:221], v[48:51], v1, v1 op_sel_hi:[0,0,0]
	v_mfma_scale_f32_16x16x128_f8f6f4 v[44:47], v[18:25], v[214:221], v[44:47], v1, v1 op_sel_hi:[0,0,0]
	v_mfma_scale_f32_16x16x128_f8f6f4 v[88:91], v[10:17], v[176:183], v[88:91], v1, v1 op_sel_hi:[0,0,0]
	v_mfma_scale_f32_16x16x128_f8f6f4 v[84:87], v[26:33], v[176:183], v[84:87], v1, v1 op_sel_hi:[0,0,0]
	v_mfma_scale_f32_16x16x128_f8f6f4 v[72:75], v[10:17], v[184:191], v[72:75], v1, v1 op_sel_hi:[0,0,0]
	v_mfma_scale_f32_16x16x128_f8f6f4 v[68:71], v[26:33], v[184:191], v[68:71], v1, v1 op_sel_hi:[0,0,0]
	v_mfma_scale_f32_16x16x128_f8f6f4 v[56:59], v[10:17], v[206:213], v[56:59], v1, v1 op_sel_hi:[0,0,0]
	v_mfma_scale_f32_16x16x128_f8f6f4 v[52:55], v[26:33], v[206:213], v[52:55], v1, v1 op_sel_hi:[0,0,0]
	v_mfma_scale_f32_16x16x128_f8f6f4 v[40:43], v[10:17], v[214:221], v[40:43], v1, v1 op_sel_hi:[0,0,0]
	v_mfma_scale_f32_16x16x128_f8f6f4 v[36:39], v[26:33], v[214:221], v[36:39], v1, v1 op_sel_hi:[0,0,0]
	s_barrier
	s_add_u32 s18, s18, 0x100
	s_addc_u32 s19, s19, 0
	s_add_u32 s60, s60, 0x100
	s_addc_u32 s61, s61, 0
	s_cmp_ge_i32 s62, s45
	s_mov_b32 s20, s62
	s_cbranch_scc0 .LBB0_697

; #define PG8_STAGE(...) PG8_STAGE_(__VA_ARGS__, 0u)
; #define PG8_WAIT_V(n) asm volatile("s_waitcnt vmcnt(" #n ")" ::: "memory")
; #define PG8_WAIT_L(n) asm volatile("s_waitcnt lgkmcnt(" #n ")" ::: "memory")
; #define PG8_BAR __builtin_amdgcn_s_barrier()
; #define PG8_SCHED __builtin_amdgcn_sched_barrier(0)
; template <class Epi, class Sched, bool ALIGN_EPI = true, bool SP2 = true>
; __device__ __forceinline__ void gemm_phase(LAS unsigned char* lds, const Gemm g, const Sched& S, const Epi& E) {
;     ...
;         const char* nA = has_next ? (const char*)g.A + (size_t)nxt.pm * tstepA + (size_t)nxt.ak * ESZ : cA; const char* nB = has_next ? (const char*)g.Bt + (size_t)nxt.pn * tstepB : cB;
;         for (int t = 0; t < nt; t += 2) {
;             const bool last = (t == nt - 2);
;             const char* a1 = cA + (size_t)(t + 1) * kstep;
;             const char* a2 = last ? nA : cA + (size_t)(t + 2) * kstep; const char* b2 = last ? nB : cB + (size_t)(t + 2) * kstep;
;             const char* a3 = a2 + kstep; const char* b3 = b2 + kstep;
;             if constexpr (SP2) {
;             PG8_LDB(B0, 0, 0); PG8_LDB(B1, 0, 1); PG8_SCHED; PG8_LDA(At, 0, 0); PG8_STAGE(PG8_SA(1, 1), a1, voffAh);
;             PG8_WAIT_V(8); PG8_WAIT_L(0); PG8_BAR; PG8_MMA(0, 0, At, B0); PG8_MMA(0, 1, At, B1); PG8_BAR; PG8_SCHED;
;             if constexpr (!Epi::HALF_M) PG8_LDA(At, 0, 1); PG8_STAGE(PG8_SB(0, 0), b2, voffB); PG8_STAGE(PG8_SB(0, 1), b2, voffBh); PG8_STAGE(PG8_SA(0, 0), a2, voffA);
;             PG8_WAIT_V(8); PG8_WAIT_L(0); PG8_BAR; if constexpr (!Epi::HALF_M) { PG8_MMA(1, 0, At, B0); PG8_MMA(1, 1, At, B1); } PG8_BAR; PG8_SCHED;
.LBB0_775:
	v_add_u32_e32 v34, s30, v144
	s_add_i32 s53, s18, 2
	ds_read_b128 v[146:149], v34
	ds_read_b128 v[150:153], v34 offset:1024
	ds_read_b128 v[154:157], v34 offset:2048
	ds_read_b128 v[158:161], v34 offset:3072
	v_add_u32_e32 v34, s34, v144
	s_add_u32 s19, s16, 0xda9ffc80
	ds_read_b128 v[162:165], v34
	ds_read_b128 v[166:169], v34 offset:1024
	ds_read_b128 v[170:173], v34 offset:2048
	ds_read_b128 v[174:177], v34 offset:3072
	s_addc_u32 s20, s17, -1
	s_cmp_lg_u32 s50, s18
	s_cselect_b32 s21, s20, 0
	s_cselect_b32 s20, s19, 0
	s_add_u32 s18, s4, s20
	s_addc_u32 s19, s5, s21
	s_add_u32 s20, s0, s20
	s_addc_u32 s21, s1, s21
	s_add_i32 m0, s37, 0xc000
	v_mov_b32_e32 v34, v142
	s_add_u32 s54, s51, s16
	ds_read_b128 v[178:181], v145
	ds_read_b128 v[182:185], v145 offset:1024
	ds_read_b128 v[186:189], v145 offset:2048
	ds_read_b128 v[190:193], v145 offset:3072
	ds_read_b128 v[206:209], v145 offset:4096
	ds_read_b128 v[210:213], v145 offset:5120
	ds_read_b128 v[214:217], v145 offset:6144
	ds_read_b128 v[218:221], v145 offset:7168
	s_addc_u32 s55, s52, s17
	global_load_lds_dwordx4 v34, s[54:55]
	v_mov_b32_e32 v34, v143
	s_add_i32 m0, s37, 0xe000
	s_nop 0
	global_load_lds_dwordx4 v34, s[54:55]
	s_waitcnt vmcnt(8)
	s_waitcnt lgkmcnt(0)
	s_barrier
	s_waitcnt lgkmcnt(0)
	v_mfma_f32_16x16x32_bf16 v[128:131], v[146:149], v[178:181], v[128:131]
	v_mfma_f32_16x16x32_bf16 v[124:127], v[154:157], v[178:181], v[124:127]
	v_mfma_f32_16x16x32_bf16 v[120:123], v[146:149], v[186:189], v[120:123]
	v_mfma_f32_16x16x32_bf16 v[116:119], v[154:157], v[186:189], v[116:119]
	v_mfma_f32_16x16x32_bf16 v[112:115], v[146:149], v[206:209], v[112:115]
	v_mfma_f32_16x16x32_bf16 v[108:111], v[154:157], v[206:209], v[108:111]
	v_mfma_f32_16x16x32_bf16 v[104:107], v[146:149], v[214:217], v[104:107]
	v_mfma_f32_16x16x32_bf16 v[100:103], v[154:157], v[214:217], v[100:103]
	v_mfma_f32_16x16x32_bf16 v[128:131], v[150:153], v[182:185], v[128:131]
	v_mfma_f32_16x16x32_bf16 v[124:127], v[158:161], v[182:185], v[124:127]
	v_mfma_f32_16x16x32_bf16 v[120:123], v[150:153], v[190:193], v[120:123]
	v_mfma_f32_16x16x32_bf16 v[116:119], v[158:161], v[190:193], v[116:119]
	v_mfma_f32_16x16x32_bf16 v[112:115], v[150:153], v[210:213], v[112:115]
	v_mfma_f32_16x16x32_bf16 v[108:111], v[158:161], v[210:213], v[108:111]
	v_mfma_f32_16x16x32_bf16 v[104:107], v[150:153], v[218:221], v[104:107]
	v_mfma_f32_16x16x32_bf16 v[100:103], v[158:161], v[218:221], v[100:103]
	v_mfma_f32_16x16x32_bf16 v[64:67], v[162:165], v[178:181], v[64:67]
	v_mfma_f32_16x16x32_bf16 v[60:63], v[170:173], v[178:181], v[60:63]
	v_mfma_f32_16x16x32_bf16 v[56:59], v[162:165], v[186:189], v[56:59]
	v_mfma_f32_16x16x32_bf16 v[52:55], v[170:173], v[186:189], v[52:55]
	v_mfma_f32_16x16x32_bf16 v[48:51], v[162:165], v[206:209], v[48:51]
	v_mfma_f32_16x16x32_bf16 v[44:47], v[170:173], v[206:209], v[44:47]
	v_mfma_f32_16x16x32_bf16 v[40:43], v[162:165], v[214:217], v[40:43]
	v_mfma_f32_16x16x32_bf16 v[36:39], v[170:173], v[214:217], v[36:39]
	v_mfma_f32_16x16x32_bf16 v[64:67], v[166:169], v[182:185], v[64:67]
	v_mfma_f32_16x16x32_bf16 v[60:63], v[174:177], v[182:185], v[60:63]
	v_mfma_f32_16x16x32_bf16 v[56:59], v[166:169], v[190:193], v[56:59]
	v_mfma_f32_16x16x32_bf16 v[52:55], v[174:177], v[190:193], v[52:55]
	v_mfma_f32_16x16x32_bf16 v[48:51], v[166:169], v[210:213], v[48:51]
	v_mfma_f32_16x16x32_bf16 v[44:47], v[174:177], v[210:213], v[44:47]
	v_mfma_f32_16x16x32_bf16 v[40:43], v[166:169], v[218:221], v[40:43]
	v_mfma_f32_16x16x32_bf16 v[36:39], v[174:177], v[218:221], v[36:39]
	s_barrier
	v_mov_b32_e32 v34, v134
	s_mov_b32 m0, s31
	ds_read_b128 v[178:181], v145 offset:16384
	ds_read_b128 v[182:185], v145 offset:17408
	ds_read_b128 v[186:189], v145 offset:18432
	ds_read_b128 v[190:193], v145 offset:19456
	ds_read_b128 v[206:209], v145 offset:20480
	ds_read_b128 v[210:213], v145 offset:21504
	ds_read_b128 v[214:217], v145 offset:22528
	ds_read_b128 v[218:221], v145 offset:23552
	s_nop 0
	global_load_lds_dwordx4 v34, s[20:21]
	v_mov_b32_e32 v34, v138
	s_mov_b32 m0, s33
	s_nop 0
	global_load_lds_dwordx4 v34, s[20:21]
	v_mov_b32_e32 v34, v139
	s_mov_b32 m0, s35
	s_nop 0
	global_load_lds_dwordx4 v34, s[20:21]
	v_mov_b32_e32 v34, v141
	s_mov_b32 m0, s36
	s_nop 0
	global_load_lds_dwordx4 v34, s[20:21]
	v_mov_b32_e32 v34, v132
	s_mov_b32 m0, s37
	s_nop 0
	global_load_lds_dwordx4 v34, s[18:19]
	v_mov_b32_e32 v34, v136
	s_mov_b32 m0, s38
	s_nop 0
	global_load_lds_dwordx4 v34, s[18:19]
	s_waitcnt vmcnt(8)
	s_waitcnt lgkmcnt(0)
	s_barrier
	s_waitcnt lgkmcnt(0)
	v_mfma_f32_16x16x32_bf16 v[96:99], v[146:149], v[178:181], v[96:99]
	v_mfma_f32_16x16x32_bf16 v[92:95], v[154:157], v[178:181], v[92:95]
	v_mfma_f32_16x16x32_bf16 v[88:91], v[146:149], v[186:189], v[88:91]
	v_mfma_f32_16x16x32_bf16 v[84:87], v[154:157], v[186:189], v[84:87]
	v_mfma_f32_16x16x32_bf16 v[80:83], v[146:149], v[206:209], v[80:83]
	v_mfma_f32_16x16x32_bf16 v[76:79], v[154:157], v[206:209], v[76:79]
	v_mfma_f32_16x16x32_bf16 v[72:75], v[146:149], v[214:217], v[72:75]
	v_mfma_f32_16x16x32_bf16 v[68:71], v[154:157], v[214:217], v[68:71]
	v_mfma_f32_16x16x32_bf16 v[96:99], v[150:153], v[182:185], v[96:99]
	v_mfma_f32_16x16x32_bf16 v[92:95], v[158:161], v[182:185], v[92:95]
	v_mfma_f32_16x16x32_bf16 v[88:91], v[150:153], v[190:193], v[88:91]
	v_mfma_f32_16x16x32_bf16 v[84:87], v[158:161], v[190:193], v[84:87]
	v_mfma_f32_16x16x32_bf16 v[80:83], v[150:153], v[210:213], v[80:83]
	v_mfma_f32_16x16x32_bf16 v[76:79], v[158:161], v[210:213], v[76:79]
	v_mfma_f32_16x16x32_bf16 v[72:75], v[150:153], v[218:221], v[72:75]
	v_mfma_f32_16x16x32_bf16 v[68:71], v[158:161], v[218:221], v[68:71]
	v_mfma_f32_16x16x32_bf16 v[30:33], v[162:165], v[178:181], v[30:33]
	v_mfma_f32_16x16x32_bf16 v[26:29], v[170:173], v[178:181], v[26:29]
	v_mfma_f32_16x16x32_bf16 v[22:25], v[162:165], v[186:189], v[22:25]
	v_mfma_f32_16x16x32_bf16 v[18:21], v[170:173], v[186:189], v[18:21]
	v_mfma_f32_16x16x32_bf16 v[14:17], v[162:165], v[206:209], v[14:17]
	v_mfma_f32_16x16x32_bf16 v[10:13], v[170:173], v[206:209], v[10:13]
	v_mfma_f32_16x16x32_bf16 v[6:9], v[162:165], v[214:217], v[6:9]
	v_mfma_f32_16x16x32_bf16 v[2:5], v[170:173], v[214:217], v[2:5]
	v_mfma_f32_16x16x32_bf16 v[30:33], v[166:169], v[182:185], v[30:33]
	v_mfma_f32_16x16x32_bf16 v[26:29], v[174:177], v[182:185], v[26:29]
	v_mfma_f32_16x16x32_bf16 v[22:25], v[166:169], v[190:193], v[22:25]
	v_mfma_f32_16x16x32_bf16 v[18:21], v[174:177], v[190:193], v[18:21]
	v_mfma_f32_16x16x32_bf16 v[14:17], v[166:169], v[210:213], v[14:17]
	v_mfma_f32_16x16x32_bf16 v[10:13], v[174:177], v[210:213], v[10:13]
	v_mfma_f32_16x16x32_bf16 v[6:9], v[166:169], v[218:221], v[6:9]
	v_mfma_f32_16x16x32_bf16 v[2:5], v[174:177], v[218:221], v[2:5]
	s_barrier
; #define PG8_STAGE(...) PG8_STAGE_(__VA_ARGS__, 0u)
; #define PG8_WAIT_V(n) asm volatile("s_waitcnt vmcnt(" #n ")" ::: "memory")
; #define PG8_WAIT_L(n) asm volatile("s_waitcnt lgkmcnt(" #n ")" ::: "memory")
; #define PG8_BAR __builtin_amdgcn_s_barrier()
; #define PG8_SCHED __builtin_amdgcn_sched_barrier(0)
; template <class Epi, class Sched, bool ALIGN_EPI = true, bool SP2 = true>
; __device__ __forceinline__ void gemm_phase(LAS unsigned char* lds, const Gemm g, const Sched& S, const Epi& E) {
;     ...
;             PG8_LDB(B0, 1, 0); PG8_LDB(B1, 1, 1); PG8_SCHED; PG8_LDA(At, 1, 0); PG8_STAGE(PG8_SA(0, 1), a2, voffAh);
;             PG8_WAIT_V(8); PG8_WAIT_L(0); PG8_BAR; PG8_MMA(0, 0, At, B0); PG8_MMA(0, 1, At, B1); PG8_BAR; PG8_SCHED;
	v_add_u32_e32 v34, s41, v144
	ds_read_b128 v[146:149], v34
	ds_read_b128 v[150:153], v34 offset:1024
	ds_read_b128 v[154:157], v34 offset:2048
	ds_read_b128 v[158:161], v34 offset:3072
	v_add_u32_e32 v34, s46, v144
	ds_read_b128 v[162:165], v34
	ds_read_b128 v[166:169], v34 offset:1024
	ds_read_b128 v[170:173], v34 offset:2048
	ds_read_b128 v[174:177], v34 offset:3072
	v_mov_b32_e32 v34, v142
	s_mov_b32 m0, s39
	ds_read_b128 v[178:181], v145 offset:32768
	ds_read_b128 v[182:185], v145 offset:33792
	ds_read_b128 v[186:189], v145 offset:34816
	ds_read_b128 v[190:193], v145 offset:35840
	ds_read_b128 v[206:209], v145 offset:36864
	ds_read_b128 v[210:213], v145 offset:37888
	ds_read_b128 v[214:217], v145 offset:38912
	ds_read_b128 v[218:221], v145 offset:39936
	s_nop 0
	global_load_lds_dwordx4 v34, s[18:19]
	v_mov_b32_e32 v34, v143
	s_mov_b32 m0, s40
	s_nop 0
	global_load_lds_dwordx4 v34, s[18:19]
	s_waitcnt vmcnt(8)
	s_waitcnt lgkmcnt(0)
	s_barrier
	s_waitcnt lgkmcnt(0)
	v_mfma_f32_16x16x32_bf16 v[128:131], v[146:149], v[178:181], v[128:131]
	v_mfma_f32_16x16x32_bf16 v[124:127], v[154:157], v[178:181], v[124:127]
	v_mfma_f32_16x16x32_bf16 v[120:123], v[146:149], v[186:189], v[120:123]
	v_mfma_f32_16x16x32_bf16 v[116:119], v[154:157], v[186:189], v[116:119]
	v_mfma_f32_16x16x32_bf16 v[112:115], v[146:149], v[206:209], v[112:115]
	v_mfma_f32_16x16x32_bf16 v[108:111], v[154:157], v[206:209], v[108:111]
	v_mfma_f32_16x16x32_bf16 v[104:107], v[146:149], v[214:217], v[104:107]
	v_mfma_f32_16x16x32_bf16 v[100:103], v[154:157], v[214:217], v[100:103]
	v_mfma_f32_16x16x32_bf16 v[128:131], v[150:153], v[182:185], v[128:131]
	v_mfma_f32_16x16x32_bf16 v[124:127], v[158:161], v[182:185], v[124:127]
	v_mfma_f32_16x16x32_bf16 v[120:123], v[150:153], v[190:193], v[120:123]
	v_mfma_f32_16x16x32_bf16 v[116:119], v[158:161], v[190:193], v[116:119]
	v_mfma_f32_16x16x32_bf16 v[112:115], v[150:153], v[210:213], v[112:115]
	v_mfma_f32_16x16x32_bf16 v[108:111], v[158:161], v[210:213], v[108:111]
	v_mfma_f32_16x16x32_bf16 v[104:107], v[150:153], v[218:221], v[104:107]
	v_mfma_f32_16x16x32_bf16 v[100:103], v[158:161], v[218:221], v[100:103]
	v_mfma_f32_16x16x32_bf16 v[64:67], v[162:165], v[178:181], v[64:67]
	v_mfma_f32_16x16x32_bf16 v[60:63], v[170:173], v[178:181], v[60:63]
	v_mfma_f32_16x16x32_bf16 v[56:59], v[162:165], v[186:189], v[56:59]
	v_mfma_f32_16x16x32_bf16 v[52:55], v[170:173], v[186:189], v[52:55]
	v_mfma_f32_16x16x32_bf16 v[48:51], v[162:165], v[206:209], v[48:51]
	v_mfma_f32_16x16x32_bf16 v[44:47], v[170:173], v[206:209], v[44:47]
	v_mfma_f32_16x16x32_bf16 v[40:43], v[162:165], v[214:217], v[40:43]
	v_mfma_f32_16x16x32_bf16 v[36:39], v[170:173], v[214:217], v[36:39]
	v_mfma_f32_16x16x32_bf16 v[64:67], v[166:169], v[182:185], v[64:67]
	v_mfma_f32_16x16x32_bf16 v[60:63], v[174:177], v[182:185], v[60:63]
	v_mfma_f32_16x16x32_bf16 v[56:59], v[166:169], v[190:193], v[56:59]
	v_mfma_f32_16x16x32_bf16 v[52:55], v[174:177], v[190:193], v[52:55]
	v_mfma_f32_16x16x32_bf16 v[48:51], v[166:169], v[210:213], v[48:51]
	v_mfma_f32_16x16x32_bf16 v[44:47], v[174:177], v[210:213], v[44:47]
	v_mfma_f32_16x16x32_bf16 v[40:43], v[166:169], v[218:221], v[40:43]
	v_mfma_f32_16x16x32_bf16 v[36:39], v[174:177], v[218:221], v[36:39]
	s_barrier
; #define PG8_STAGE(...) PG8_STAGE_(__VA_ARGS__, 0u)
; #define PG8_WAIT_V(n) asm volatile("s_waitcnt vmcnt(" #n ")" ::: "memory")
; #define PG8_WAIT_L(n) asm volatile("s_waitcnt lgkmcnt(" #n ")" ::: "memory")
; #define PG8_BAR __builtin_amdgcn_s_barrier()
; #define PG8_SCHED __builtin_amdgcn_sched_barrier(0)
; template <class Epi, class Sched, bool ALIGN_EPI = true, bool SP2 = true>
; __device__ __forceinline__ void gemm_phase(LAS unsigned char* lds, const Gemm g, const Sched& S, const Epi& E) {
;     ...
;             if constexpr (!Epi::HALF_M) PG8_LDA(At, 1, 1); PG8_STAGE(PG8_SB(1, 0), b3, voffB); PG8_STAGE(PG8_SB(1, 1), b3, voffBh); PG8_STAGE(PG8_SA(1, 0), a3, voffA);
;             PG8_WAIT_V(8); PG8_WAIT_L(0); PG8_BAR; if constexpr (!Epi::HALF_M) { PG8_MMA(1, 0, At, B0); PG8_MMA(1, 1, At, B1); } PG8_BAR; PG8_SCHED;
	v_mov_b32_e32 v34, v134
	ds_read_b128 v[178:181], v145 offset:49152
	ds_read_b128 v[182:185], v145 offset:50176
	ds_read_b128 v[186:189], v145 offset:51200
	ds_read_b128 v[190:193], v145 offset:52224
	ds_read_b128 v[206:209], v145 offset:53248
	ds_read_b128 v[210:213], v145 offset:54272
	ds_read_b128 v[214:217], v145 offset:55296
	ds_read_b128 v[218:221], v145 offset:56320
	s_mov_b32 m0, s42
	v_lshl_add_u64 v[194:195], s[20:21], 0, v[34:35]
	v_lshl_add_u64 v[194:195], v[194:195], 0, s[80:81]
	v_mov_b32_e32 v34, v138
	global_load_lds_dwordx4 v[194:195], off
	s_mov_b32 m0, s43
	v_lshl_add_u64 v[194:195], s[20:21], 0, v[34:35]
	v_lshl_add_u64 v[194:195], v[194:195], 0, s[80:81]
	v_mov_b32_e32 v34, v139
	global_load_lds_dwordx4 v[194:195], off
	s_mov_b32 m0, s47
	v_lshl_add_u64 v[194:195], s[20:21], 0, v[34:35]
	v_lshl_add_u64 v[194:195], v[194:195], 0, s[80:81]
	v_mov_b32_e32 v34, v141
	global_load_lds_dwordx4 v[194:195], off
	s_mov_b32 m0, s48
	v_lshl_add_u64 v[194:195], s[20:21], 0, v[34:35]
	v_lshl_add_u64 v[194:195], v[194:195], 0, s[80:81]
	v_mov_b32_e32 v34, v132
	global_load_lds_dwordx4 v[194:195], off
	s_mov_b32 m0, s44
	v_lshl_add_u64 v[194:195], s[18:19], 0, v[34:35]
	v_lshl_add_u64 v[194:195], v[194:195], 0, s[80:81]
	v_mov_b32_e32 v34, v136
	global_load_lds_dwordx4 v[194:195], off
	s_mov_b32 m0, s45
	v_lshl_add_u64 v[194:195], s[18:19], 0, v[34:35]
	v_lshl_add_u64 v[194:195], v[194:195], 0, s[80:81]
	global_load_lds_dwordx4 v[194:195], off
	s_waitcnt vmcnt(8)
	s_waitcnt lgkmcnt(0)
	s_barrier
	s_waitcnt lgkmcnt(0)
	v_mfma_f32_16x16x32_bf16 v[96:99], v[146:149], v[178:181], v[96:99]
	v_mfma_f32_16x16x32_bf16 v[92:95], v[154:157], v[178:181], v[92:95]
	v_mfma_f32_16x16x32_bf16 v[88:91], v[146:149], v[186:189], v[88:91]
	v_mfma_f32_16x16x32_bf16 v[84:87], v[154:157], v[186:189], v[84:87]
	v_mfma_f32_16x16x32_bf16 v[80:83], v[146:149], v[206:209], v[80:83]
	v_mfma_f32_16x16x32_bf16 v[76:79], v[154:157], v[206:209], v[76:79]
	v_mfma_f32_16x16x32_bf16 v[72:75], v[146:149], v[214:217], v[72:75]
	v_mfma_f32_16x16x32_bf16 v[68:71], v[154:157], v[214:217], v[68:71]
	v_mfma_f32_16x16x32_bf16 v[96:99], v[150:153], v[182:185], v[96:99]
	v_mfma_f32_16x16x32_bf16 v[92:95], v[158:161], v[182:185], v[92:95]
	v_mfma_f32_16x16x32_bf16 v[88:91], v[150:153], v[190:193], v[88:91]
	v_mfma_f32_16x16x32_bf16 v[84:87], v[158:161], v[190:193], v[84:87]
	v_mfma_f32_16x16x32_bf16 v[80:83], v[150:153], v[210:213], v[80:83]
	v_mfma_f32_16x16x32_bf16 v[76:79], v[158:161], v[210:213], v[76:79]
	v_mfma_f32_16x16x32_bf16 v[72:75], v[150:153], v[218:221], v[72:75]
	v_mfma_f32_16x16x32_bf16 v[68:71], v[158:161], v[218:221], v[68:71]
	v_mfma_f32_16x16x32_bf16 v[30:33], v[162:165], v[178:181], v[30:33]
	v_mfma_f32_16x16x32_bf16 v[26:29], v[170:173], v[178:181], v[26:29]
	v_mfma_f32_16x16x32_bf16 v[22:25], v[162:165], v[186:189], v[22:25]
	v_mfma_f32_16x16x32_bf16 v[18:21], v[170:173], v[186:189], v[18:21]
	v_mfma_f32_16x16x32_bf16 v[14:17], v[162:165], v[206:209], v[14:17]
	v_mfma_f32_16x16x32_bf16 v[10:13], v[170:173], v[206:209], v[10:13]
	v_mfma_f32_16x16x32_bf16 v[6:9], v[162:165], v[214:217], v[6:9]
	v_mfma_f32_16x16x32_bf16 v[2:5], v[170:173], v[214:217], v[2:5]
	v_mfma_f32_16x16x32_bf16 v[30:33], v[166:169], v[182:185], v[30:33]
	v_mfma_f32_16x16x32_bf16 v[26:29], v[174:177], v[182:185], v[26:29]
	v_mfma_f32_16x16x32_bf16 v[22:25], v[166:169], v[190:193], v[22:25]
	v_mfma_f32_16x16x32_bf16 v[18:21], v[174:177], v[190:193], v[18:21]
	v_mfma_f32_16x16x32_bf16 v[14:17], v[166:169], v[210:213], v[14:17]
	v_mfma_f32_16x16x32_bf16 v[10:13], v[174:177], v[210:213], v[10:13]
	v_mfma_f32_16x16x32_bf16 v[6:9], v[166:169], v[218:221], v[6:9]
	v_mfma_f32_16x16x32_bf16 v[2:5], v[174:177], v[218:221], v[2:5]
	s_barrier
	s_add_u32 s16, s16, 0x100
	s_addc_u32 s17, s17, 0
	s_cmp_ge_i32 s53, s49
	s_mov_b32 s18, s53
	s_cbranch_scc0 .LBB0_775

; #define PG8_STAGE(...) PG8_STAGE_(__VA_ARGS__, 0u)
; #define PG8_WAIT_V(n) asm volatile("s_waitcnt vmcnt(" #n ")" ::: "memory")
; #define PG8_WAIT_L(n) asm volatile("s_waitcnt lgkmcnt(" #n ")" ::: "memory")
; #define PG8_BAR __builtin_amdgcn_s_barrier()
; #define PG8_SCHED __builtin_amdgcn_sched_barrier(0)
; template <class Epi, class Sched, bool ALIGN_EPI = true, bool SP2 = true>
; __device__ __forceinline__ void gemm_phase(LAS unsigned char* lds, const Gemm g, const Sched& S, const Epi& E) {
;     ...
;         const char* nA = has_next ? (const char*)g.A + (size_t)nxt.pm * tstepA + (size_t)nxt.ak * ESZ : cA; const char* nB = has_next ? (const char*)g.Bt + (size_t)nxt.pn * tstepB : cB;
;         for (int t = 0; t < nt; t += 2) {
;             const bool last = (t == nt - 2);
;             const char* a1 = cA + (size_t)(t + 1) * kstep;
;             const char* a2 = last ? nA : cA + (size_t)(t + 2) * kstep; const char* b2 = last ? nB : cB + (size_t)(t + 2) * kstep;
;             const char* a3 = a2 + kstep; const char* b3 = b2 + kstep;
;             if constexpr (SP2) {
;             PG8_LDB(B0, 0, 0); PG8_LDB(B1, 0, 1); PG8_SCHED; PG8_LDA(At, 0, 0); PG8_STAGE(PG8_SA(1, 1), a1, voffAh);
;             PG8_WAIT_V(8); PG8_WAIT_L(0); PG8_BAR; PG8_MMA(0, 0, At, B0); PG8_MMA(0, 1, At, B1); PG8_BAR; PG8_SCHED;
;             if constexpr (!Epi::HALF_M) PG8_LDA(At, 0, 1); PG8_STAGE(PG8_SB(0, 0), b2, voffB); PG8_STAGE(PG8_SB(0, 1), b2, voffBh); PG8_STAGE(PG8_SA(0, 0), a2, voffA);
;             PG8_WAIT_V(8); PG8_WAIT_L(0); PG8_BAR; if constexpr (!Epi::HALF_M) { PG8_MMA(1, 0, At, B0); PG8_MMA(1, 1, At, B1); } PG8_BAR; PG8_SCHED;
.LBB0_852:
	v_add_u32_e32 v34, s28, v143
	s_add_i32 s49, s16, 2
	ds_read_b128 v[146:149], v34
	ds_read_b128 v[150:153], v34 offset:1024
	ds_read_b128 v[154:157], v34 offset:2048
	ds_read_b128 v[158:161], v34 offset:3072
	v_add_u32_e32 v34, s31, v143
	s_add_u32 s17, s6, 0xda9ffe80
	ds_read_b128 v[162:165], v34
	ds_read_b128 v[166:169], v34 offset:1024
	ds_read_b128 v[170:173], v34 offset:2048
	ds_read_b128 v[174:177], v34 offset:3072
	s_addc_u32 s18, s7, -1
	s_cmp_lg_u32 s48, s16
	s_cselect_b32 s19, s18, 0
	s_cselect_b32 s18, s17, 0
	s_add_u32 s16, s4, s18
	s_addc_u32 s17, s5, s19
	s_add_u32 s18, s0, s18
	s_addc_u32 s19, s1, s19
	s_add_i32 m0, s35, 0xc000
	v_mov_b32_e32 v34, v141
	s_add_u32 s50, s15, s6
	ds_read_b128 v[178:181], v144
	ds_read_b128 v[182:185], v144 offset:1024
	ds_read_b128 v[186:189], v144 offset:2048
	ds_read_b128 v[190:193], v144 offset:3072
	ds_read_b128 v[206:209], v144 offset:4096
	ds_read_b128 v[210:213], v144 offset:5120
	ds_read_b128 v[214:217], v144 offset:6144
	ds_read_b128 v[218:221], v144 offset:7168
	s_addc_u32 s51, s27, s7
	global_load_lds_dwordx4 v34, s[50:51]
	v_mov_b32_e32 v34, v142
	s_add_i32 m0, s35, 0xe000
	s_nop 0
	global_load_lds_dwordx4 v34, s[50:51]
	s_waitcnt vmcnt(8)
	s_waitcnt lgkmcnt(0)
	s_barrier
	s_waitcnt lgkmcnt(0)
	v_mfma_f32_16x16x32_bf16 v[128:131], v[146:149], v[178:181], v[128:131]
	v_mfma_f32_16x16x32_bf16 v[124:127], v[154:157], v[178:181], v[124:127]
	v_mfma_f32_16x16x32_bf16 v[120:123], v[146:149], v[186:189], v[120:123]
	v_mfma_f32_16x16x32_bf16 v[116:119], v[154:157], v[186:189], v[116:119]
	v_mfma_f32_16x16x32_bf16 v[112:115], v[146:149], v[206:209], v[112:115]
	v_mfma_f32_16x16x32_bf16 v[108:111], v[154:157], v[206:209], v[108:111]
	v_mfma_f32_16x16x32_bf16 v[104:107], v[146:149], v[214:217], v[104:107]
	v_mfma_f32_16x16x32_bf16 v[100:103], v[154:157], v[214:217], v[100:103]
	v_mfma_f32_16x16x32_bf16 v[128:131], v[150:153], v[182:185], v[128:131]
	v_mfma_f32_16x16x32_bf16 v[124:127], v[158:161], v[182:185], v[124:127]
	v_mfma_f32_16x16x32_bf16 v[120:123], v[150:153], v[190:193], v[120:123]
	v_mfma_f32_16x16x32_bf16 v[116:119], v[158:161], v[190:193], v[116:119]
	v_mfma_f32_16x16x32_bf16 v[112:115], v[150:153], v[210:213], v[112:115]
	v_mfma_f32_16x16x32_bf16 v[108:111], v[158:161], v[210:213], v[108:111]
	v_mfma_f32_16x16x32_bf16 v[104:107], v[150:153], v[218:221], v[104:107]
	v_mfma_f32_16x16x32_bf16 v[100:103], v[158:161], v[218:221], v[100:103]
	v_mfma_f32_16x16x32_bf16 v[64:67], v[162:165], v[178:181], v[64:67]
	v_mfma_f32_16x16x32_bf16 v[60:63], v[170:173], v[178:181], v[60:63]
	v_mfma_f32_16x16x32_bf16 v[56:59], v[162:165], v[186:189], v[56:59]
	v_mfma_f32_16x16x32_bf16 v[52:55], v[170:173], v[186:189], v[52:55]
	v_mfma_f32_16x16x32_bf16 v[48:51], v[162:165], v[206:209], v[48:51]
	v_mfma_f32_16x16x32_bf16 v[44:47], v[170:173], v[206:209], v[44:47]
	v_mfma_f32_16x16x32_bf16 v[40:43], v[162:165], v[214:217], v[40:43]
	v_mfma_f32_16x16x32_bf16 v[36:39], v[170:173], v[214:217], v[36:39]
	v_mfma_f32_16x16x32_bf16 v[64:67], v[166:169], v[182:185], v[64:67]
	v_mfma_f32_16x16x32_bf16 v[60:63], v[174:177], v[182:185], v[60:63]
	v_mfma_f32_16x16x32_bf16 v[56:59], v[166:169], v[190:193], v[56:59]
	v_mfma_f32_16x16x32_bf16 v[52:55], v[174:177], v[190:193], v[52:55]
	v_mfma_f32_16x16x32_bf16 v[48:51], v[166:169], v[210:213], v[48:51]
	v_mfma_f32_16x16x32_bf16 v[44:47], v[174:177], v[210:213], v[44:47]
	v_mfma_f32_16x16x32_bf16 v[40:43], v[166:169], v[218:221], v[40:43]
	v_mfma_f32_16x16x32_bf16 v[36:39], v[174:177], v[218:221], v[36:39]
	s_barrier
	v_mov_b32_e32 v34, v134
	s_mov_b32 m0, s29
	ds_read_b128 v[178:181], v144 offset:16384
	ds_read_b128 v[182:185], v144 offset:17408
	ds_read_b128 v[186:189], v144 offset:18432
	ds_read_b128 v[190:193], v144 offset:19456
	ds_read_b128 v[206:209], v144 offset:20480
	ds_read_b128 v[210:213], v144 offset:21504
	ds_read_b128 v[214:217], v144 offset:22528
	ds_read_b128 v[218:221], v144 offset:23552
	s_nop 0
	global_load_lds_dwordx4 v34, s[18:19]
	v_mov_b32_e32 v34, v138
	s_mov_b32 m0, s30
	s_nop 0
	global_load_lds_dwordx4 v34, s[18:19]
	v_mov_b32_e32 v34, v139
	s_mov_b32 m0, s33
	s_nop 0
	global_load_lds_dwordx4 v34, s[18:19]
	v_mov_b32_e32 v34, v140
	s_mov_b32 m0, s34
	s_nop 0
	global_load_lds_dwordx4 v34, s[18:19]
	v_mov_b32_e32 v34, v132
	s_mov_b32 m0, s35
	s_nop 0
	global_load_lds_dwordx4 v34, s[16:17]
	v_mov_b32_e32 v34, v136
	s_mov_b32 m0, s36
	s_nop 0
	global_load_lds_dwordx4 v34, s[16:17]
	s_waitcnt vmcnt(8)
	s_waitcnt lgkmcnt(0)
	s_barrier
	s_waitcnt lgkmcnt(0)
	v_mfma_f32_16x16x32_bf16 v[96:99], v[146:149], v[178:181], v[96:99]
	v_mfma_f32_16x16x32_bf16 v[92:95], v[154:157], v[178:181], v[92:95]
	v_mfma_f32_16x16x32_bf16 v[88:91], v[146:149], v[186:189], v[88:91]
	v_mfma_f32_16x16x32_bf16 v[84:87], v[154:157], v[186:189], v[84:87]
	v_mfma_f32_16x16x32_bf16 v[80:83], v[146:149], v[206:209], v[80:83]
	v_mfma_f32_16x16x32_bf16 v[76:79], v[154:157], v[206:209], v[76:79]
	v_mfma_f32_16x16x32_bf16 v[72:75], v[146:149], v[214:217], v[72:75]
	v_mfma_f32_16x16x32_bf16 v[68:71], v[154:157], v[214:217], v[68:71]
	v_mfma_f32_16x16x32_bf16 v[96:99], v[150:153], v[182:185], v[96:99]
	v_mfma_f32_16x16x32_bf16 v[92:95], v[158:161], v[182:185], v[92:95]
	v_mfma_f32_16x16x32_bf16 v[88:91], v[150:153], v[190:193], v[88:91]
	v_mfma_f32_16x16x32_bf16 v[84:87], v[158:161], v[190:193], v[84:87]
	v_mfma_f32_16x16x32_bf16 v[80:83], v[150:153], v[210:213], v[80:83]
	v_mfma_f32_16x16x32_bf16 v[76:79], v[158:161], v[210:213], v[76:79]
	v_mfma_f32_16x16x32_bf16 v[72:75], v[150:153], v[218:221], v[72:75]
	v_mfma_f32_16x16x32_bf16 v[68:71], v[158:161], v[218:221], v[68:71]
	v_mfma_f32_16x16x32_bf16 v[30:33], v[162:165], v[178:181], v[30:33]
	v_mfma_f32_16x16x32_bf16 v[26:29], v[170:173], v[178:181], v[26:29]
	v_mfma_f32_16x16x32_bf16 v[22:25], v[162:165], v[186:189], v[22:25]
	v_mfma_f32_16x16x32_bf16 v[18:21], v[170:173], v[186:189], v[18:21]
	v_mfma_f32_16x16x32_bf16 v[14:17], v[162:165], v[206:209], v[14:17]
	v_mfma_f32_16x16x32_bf16 v[10:13], v[170:173], v[206:209], v[10:13]
	v_mfma_f32_16x16x32_bf16 v[6:9], v[162:165], v[214:217], v[6:9]
	v_mfma_f32_16x16x32_bf16 v[2:5], v[170:173], v[214:217], v[2:5]
	v_mfma_f32_16x16x32_bf16 v[30:33], v[166:169], v[182:185], v[30:33]
	v_mfma_f32_16x16x32_bf16 v[26:29], v[174:177], v[182:185], v[26:29]
	v_mfma_f32_16x16x32_bf16 v[22:25], v[166:169], v[190:193], v[22:25]
	v_mfma_f32_16x16x32_bf16 v[18:21], v[174:177], v[190:193], v[18:21]
	v_mfma_f32_16x16x32_bf16 v[14:17], v[166:169], v[210:213], v[14:17]
	v_mfma_f32_16x16x32_bf16 v[10:13], v[174:177], v[210:213], v[10:13]
	v_mfma_f32_16x16x32_bf16 v[6:9], v[166:169], v[218:221], v[6:9]
	v_mfma_f32_16x16x32_bf16 v[2:5], v[174:177], v[218:221], v[2:5]
	s_barrier
; #define PG8_STAGE(...) PG8_STAGE_(__VA_ARGS__, 0u)
; #define PG8_WAIT_V(n) asm volatile("s_waitcnt vmcnt(" #n ")" ::: "memory")
; #define PG8_WAIT_L(n) asm volatile("s_waitcnt lgkmcnt(" #n ")" ::: "memory")
; #define PG8_BAR __builtin_amdgcn_s_barrier()
; #define PG8_SCHED __builtin_amdgcn_sched_barrier(0)
; template <class Epi, class Sched, bool ALIGN_EPI = true, bool SP2 = true>
; __device__ __forceinline__ void gemm_phase(LAS unsigned char* lds, const Gemm g, const Sched& S, const Epi& E) {
;     ...
;             PG8_LDB(B0, 1, 0); PG8_LDB(B1, 1, 1); PG8_SCHED; PG8_LDA(At, 1, 0); PG8_STAGE(PG8_SA(0, 1), a2, voffAh);
;             PG8_WAIT_V(8); PG8_WAIT_L(0); PG8_BAR; PG8_MMA(0, 0, At, B0); PG8_MMA(0, 1, At, B1); PG8_BAR; PG8_SCHED;
	v_add_u32_e32 v34, s39, v143
	ds_read_b128 v[146:149], v34
	ds_read_b128 v[150:153], v34 offset:1024
	ds_read_b128 v[154:157], v34 offset:2048
	ds_read_b128 v[158:161], v34 offset:3072
	v_add_u32_e32 v34, s44, v143
	ds_read_b128 v[162:165], v34
	ds_read_b128 v[166:169], v34 offset:1024
	ds_read_b128 v[170:173], v34 offset:2048
	ds_read_b128 v[174:177], v34 offset:3072
	v_mov_b32_e32 v34, v141
	s_mov_b32 m0, s37
	ds_read_b128 v[178:181], v144 offset:32768
	ds_read_b128 v[182:185], v144 offset:33792
	ds_read_b128 v[186:189], v144 offset:34816
	ds_read_b128 v[190:193], v144 offset:35840
	ds_read_b128 v[206:209], v144 offset:36864
	ds_read_b128 v[210:213], v144 offset:37888
	ds_read_b128 v[214:217], v144 offset:38912
	ds_read_b128 v[218:221], v144 offset:39936
	s_nop 0
	global_load_lds_dwordx4 v34, s[16:17]
	v_mov_b32_e32 v34, v142
	s_mov_b32 m0, s38
	s_nop 0
	global_load_lds_dwordx4 v34, s[16:17]
	s_waitcnt vmcnt(8)
	s_waitcnt lgkmcnt(0)
	s_barrier
	s_waitcnt lgkmcnt(0)
	v_mfma_f32_16x16x32_bf16 v[128:131], v[146:149], v[178:181], v[128:131]
	v_mfma_f32_16x16x32_bf16 v[124:127], v[154:157], v[178:181], v[124:127]
	v_mfma_f32_16x16x32_bf16 v[120:123], v[146:149], v[186:189], v[120:123]
	v_mfma_f32_16x16x32_bf16 v[116:119], v[154:157], v[186:189], v[116:119]
	v_mfma_f32_16x16x32_bf16 v[112:115], v[146:149], v[206:209], v[112:115]
	v_mfma_f32_16x16x32_bf16 v[108:111], v[154:157], v[206:209], v[108:111]
	v_mfma_f32_16x16x32_bf16 v[104:107], v[146:149], v[214:217], v[104:107]
	v_mfma_f32_16x16x32_bf16 v[100:103], v[154:157], v[214:217], v[100:103]
	v_mfma_f32_16x16x32_bf16 v[128:131], v[150:153], v[182:185], v[128:131]
	v_mfma_f32_16x16x32_bf16 v[124:127], v[158:161], v[182:185], v[124:127]
	v_mfma_f32_16x16x32_bf16 v[120:123], v[150:153], v[190:193], v[120:123]
	v_mfma_f32_16x16x32_bf16 v[116:119], v[158:161], v[190:193], v[116:119]
	v_mfma_f32_16x16x32_bf16 v[112:115], v[150:153], v[210:213], v[112:115]
	v_mfma_f32_16x16x32_bf16 v[108:111], v[158:161], v[210:213], v[108:111]
	v_mfma_f32_16x16x32_bf16 v[104:107], v[150:153], v[218:221], v[104:107]
	v_mfma_f32_16x16x32_bf16 v[100:103], v[158:161], v[218:221], v[100:103]
	v_mfma_f32_16x16x32_bf16 v[64:67], v[162:165], v[178:181], v[64:67]
	v_mfma_f32_16x16x32_bf16 v[60:63], v[170:173], v[178:181], v[60:63]
	v_mfma_f32_16x16x32_bf16 v[56:59], v[162:165], v[186:189], v[56:59]
	v_mfma_f32_16x16x32_bf16 v[52:55], v[170:173], v[186:189], v[52:55]
	v_mfma_f32_16x16x32_bf16 v[48:51], v[162:165], v[206:209], v[48:51]
	v_mfma_f32_16x16x32_bf16 v[44:47], v[170:173], v[206:209], v[44:47]
	v_mfma_f32_16x16x32_bf16 v[40:43], v[162:165], v[214:217], v[40:43]
	v_mfma_f32_16x16x32_bf16 v[36:39], v[170:173], v[214:217], v[36:39]
	v_mfma_f32_16x16x32_bf16 v[64:67], v[166:169], v[182:185], v[64:67]
	v_mfma_f32_16x16x32_bf16 v[60:63], v[174:177], v[182:185], v[60:63]
	v_mfma_f32_16x16x32_bf16 v[56:59], v[166:169], v[190:193], v[56:59]
	v_mfma_f32_16x16x32_bf16 v[52:55], v[174:177], v[190:193], v[52:55]
	v_mfma_f32_16x16x32_bf16 v[48:51], v[166:169], v[210:213], v[48:51]
	v_mfma_f32_16x16x32_bf16 v[44:47], v[174:177], v[210:213], v[44:47]
	v_mfma_f32_16x16x32_bf16 v[40:43], v[166:169], v[218:221], v[40:43]
	v_mfma_f32_16x16x32_bf16 v[36:39], v[174:177], v[218:221], v[36:39]
	s_barrier
; #define PG8_STAGE(...) PG8_STAGE_(__VA_ARGS__, 0u)
; #define PG8_WAIT_V(n) asm volatile("s_waitcnt vmcnt(" #n ")" ::: "memory")
; #define PG8_WAIT_L(n) asm volatile("s_waitcnt lgkmcnt(" #n ")" ::: "memory")
; #define PG8_BAR __builtin_amdgcn_s_barrier()
; #define PG8_SCHED __builtin_amdgcn_sched_barrier(0)
; template <class Epi, class Sched, bool ALIGN_EPI = true, bool SP2 = true>
; __device__ __forceinline__ void gemm_phase(LAS unsigned char* lds, const Gemm g, const Sched& S, const Epi& E) {
;     ...
;             if constexpr (!Epi::HALF_M) PG8_LDA(At, 1, 1); PG8_STAGE(PG8_SB(1, 0), b3, voffB); PG8_STAGE(PG8_SB(1, 1), b3, voffBh); PG8_STAGE(PG8_SA(1, 0), a3, voffA);
;             PG8_WAIT_V(8); PG8_WAIT_L(0); PG8_BAR; if constexpr (!Epi::HALF_M) { PG8_MMA(1, 0, At, B0); PG8_MMA(1, 1, At, B1); } PG8_BAR; PG8_SCHED;
	v_mov_b32_e32 v34, v134
	ds_read_b128 v[178:181], v144 offset:49152
	ds_read_b128 v[182:185], v144 offset:50176
	ds_read_b128 v[186:189], v144 offset:51200
	ds_read_b128 v[190:193], v144 offset:52224
	ds_read_b128 v[206:209], v144 offset:53248
	ds_read_b128 v[210:213], v144 offset:54272
	ds_read_b128 v[214:217], v144 offset:55296
	ds_read_b128 v[218:221], v144 offset:56320
	s_mov_b32 m0, s40
	v_lshl_add_u64 v[194:195], s[18:19], 0, v[34:35]
	v_lshl_add_u64 v[194:195], v[194:195], 0, s[80:81]
	v_mov_b32_e32 v34, v138
	global_load_lds_dwordx4 v[194:195], off
	s_mov_b32 m0, s41
	v_lshl_add_u64 v[194:195], s[18:19], 0, v[34:35]
	v_lshl_add_u64 v[194:195], v[194:195], 0, s[80:81]
	v_mov_b32_e32 v34, v139
	global_load_lds_dwordx4 v[194:195], off
	s_mov_b32 m0, s45
	v_lshl_add_u64 v[194:195], s[18:19], 0, v[34:35]
	v_lshl_add_u64 v[194:195], v[194:195], 0, s[80:81]
	v_mov_b32_e32 v34, v140
	global_load_lds_dwordx4 v[194:195], off
	s_mov_b32 m0, s46
	v_lshl_add_u64 v[194:195], s[18:19], 0, v[34:35]
	v_lshl_add_u64 v[194:195], v[194:195], 0, s[80:81]
	v_mov_b32_e32 v34, v132
	global_load_lds_dwordx4 v[194:195], off
	s_mov_b32 m0, s42
	v_lshl_add_u64 v[194:195], s[16:17], 0, v[34:35]
	v_lshl_add_u64 v[194:195], v[194:195], 0, s[80:81]
	v_mov_b32_e32 v34, v136
	global_load_lds_dwordx4 v[194:195], off
	s_mov_b32 m0, s43
	v_lshl_add_u64 v[194:195], s[16:17], 0, v[34:35]
	v_lshl_add_u64 v[194:195], v[194:195], 0, s[80:81]
	global_load_lds_dwordx4 v[194:195], off
	s_waitcnt vmcnt(8)
	s_waitcnt lgkmcnt(0)
	s_barrier
	s_waitcnt lgkmcnt(0)
	v_mfma_f32_16x16x32_bf16 v[96:99], v[146:149], v[178:181], v[96:99]
	v_mfma_f32_16x16x32_bf16 v[92:95], v[154:157], v[178:181], v[92:95]
	v_mfma_f32_16x16x32_bf16 v[88:91], v[146:149], v[186:189], v[88:91]
	v_mfma_f32_16x16x32_bf16 v[84:87], v[154:157], v[186:189], v[84:87]
	v_mfma_f32_16x16x32_bf16 v[80:83], v[146:149], v[206:209], v[80:83]
	v_mfma_f32_16x16x32_bf16 v[76:79], v[154:157], v[206:209], v[76:79]
	v_mfma_f32_16x16x32_bf16 v[72:75], v[146:149], v[214:217], v[72:75]
	v_mfma_f32_16x16x32_bf16 v[68:71], v[154:157], v[214:217], v[68:71]
	v_mfma_f32_16x16x32_bf16 v[96:99], v[150:153], v[182:185], v[96:99]
	v_mfma_f32_16x16x32_bf16 v[92:95], v[158:161], v[182:185], v[92:95]
	v_mfma_f32_16x16x32_bf16 v[88:91], v[150:153], v[190:193], v[88:91]
	v_mfma_f32_16x16x32_bf16 v[84:87], v[158:161], v[190:193], v[84:87]
	v_mfma_f32_16x16x32_bf16 v[80:83], v[150:153], v[210:213], v[80:83]
	v_mfma_f32_16x16x32_bf16 v[76:79], v[158:161], v[210:213], v[76:79]
	v_mfma_f32_16x16x32_bf16 v[72:75], v[150:153], v[218:221], v[72:75]
	v_mfma_f32_16x16x32_bf16 v[68:71], v[158:161], v[218:221], v[68:71]
	v_mfma_f32_16x16x32_bf16 v[30:33], v[162:165], v[178:181], v[30:33]
	v_mfma_f32_16x16x32_bf16 v[26:29], v[170:173], v[178:181], v[26:29]
	v_mfma_f32_16x16x32_bf16 v[22:25], v[162:165], v[186:189], v[22:25]
	v_mfma_f32_16x16x32_bf16 v[18:21], v[170:173], v[186:189], v[18:21]
	v_mfma_f32_16x16x32_bf16 v[14:17], v[162:165], v[206:209], v[14:17]
	v_mfma_f32_16x16x32_bf16 v[10:13], v[170:173], v[206:209], v[10:13]
	v_mfma_f32_16x16x32_bf16 v[6:9], v[162:165], v[214:217], v[6:9]
	v_mfma_f32_16x16x32_bf16 v[2:5], v[170:173], v[214:217], v[2:5]
	v_mfma_f32_16x16x32_bf16 v[30:33], v[166:169], v[182:185], v[30:33]
	v_mfma_f32_16x16x32_bf16 v[26:29], v[174:177], v[182:185], v[26:29]
	v_mfma_f32_16x16x32_bf16 v[22:25], v[166:169], v[190:193], v[22:25]
	v_mfma_f32_16x16x32_bf16 v[18:21], v[174:177], v[190:193], v[18:21]
	v_mfma_f32_16x16x32_bf16 v[14:17], v[166:169], v[210:213], v[14:17]
	v_mfma_f32_16x16x32_bf16 v[10:13], v[174:177], v[210:213], v[10:13]
	v_mfma_f32_16x16x32_bf16 v[6:9], v[166:169], v[218:221], v[6:9]
	v_mfma_f32_16x16x32_bf16 v[2:5], v[174:177], v[218:221], v[2:5]
	s_barrier
	s_add_u32 s6, s6, 0x100
	s_addc_u32 s7, s7, 0
	s_cmp_ge_i32 s49, s47
	s_mov_b32 s16, s49
	s_cbranch_scc0 .LBB0_852

; #define PG8_STAGE(...) PG8_STAGE_(__VA_ARGS__, 0u)
; #define PG8_WAIT_V(n) asm volatile("s_waitcnt vmcnt(" #n ")" ::: "memory")
; #define PG8_WAIT_L(n) asm volatile("s_waitcnt lgkmcnt(" #n ")" ::: "memory")
; #define PG8_BAR __builtin_amdgcn_s_barrier()
; #define PG8_SCHED __builtin_amdgcn_sched_barrier(0)
; template <class Epi, class Sched, bool ALIGN_EPI = true, bool SP2 = true>
; __device__ __forceinline__ void gemm_phase(LAS unsigned char* lds, const Gemm g, const Sched& S, const Epi& E) {
;     ...
;         const char* nA = has_next ? (const char*)g.A + (size_t)nxt.pm * tstepA + (size_t)nxt.ak * ESZ : cA; const char* nB = has_next ? (const char*)g.Bt + (size_t)nxt.pn * tstepB : cB;
;         for (int t = 0; t < nt; t += 2) {
;             const bool last = (t == nt - 2);
;             const char* a1 = cA + (size_t)(t + 1) * kstep;
;             const char* a2 = last ? nA : cA + (size_t)(t + 2) * kstep; const char* b2 = last ? nB : cB + (size_t)(t + 2) * kstep;
;             const char* a3 = a2 + kstep; const char* b3 = b2 + kstep;
;             if constexpr (SP2) {
;             PG8_LDB(B0, 0, 0); PG8_LDB(B1, 0, 1); PG8_SCHED; PG8_LDA(At, 0, 0); PG8_STAGE(PG8_SA(1, 1), a1, voffAh);
;             PG8_WAIT_V(8); PG8_WAIT_L(0); PG8_BAR; PG8_MMA(0, 0, At, B0); PG8_MMA(0, 1, At, B1); PG8_BAR; PG8_SCHED;
;             if constexpr (!Epi::HALF_M) PG8_LDA(At, 0, 1); PG8_STAGE(PG8_SB(0, 0), b2, voffB); PG8_STAGE(PG8_SB(0, 1), b2, voffBh); PG8_STAGE(PG8_SA(0, 0), a2, voffA);
;             PG8_WAIT_V(8); PG8_WAIT_L(0); PG8_BAR; if constexpr (!Epi::HALF_M) { PG8_MMA(1, 0, At, B0); PG8_MMA(1, 1, At, B1); } PG8_BAR; PG8_SCHED;
.LBB0_1044:
	v_add_u32_e32 v34, s31, v143
	ds_read_b128 v[146:149], v34
	ds_read_b128 v[150:153], v34 offset:1024
	ds_read_b128 v[154:157], v34 offset:2048
	ds_read_b128 v[158:161], v34 offset:3072
	v_add_u32_e32 v34, s35, v143
	ds_read_b128 v[162:165], v34
	ds_read_b128 v[166:169], v34 offset:1024
	ds_read_b128 v[170:173], v34 offset:2048
	ds_read_b128 v[174:177], v34 offset:3072
	s_add_i32 s60, s22, 2
	s_add_u32 s24, s20, 0x80
	s_addc_u32 s23, s21, 0
	s_cmp_eq_u32 s52, s22
	s_cselect_b32 s22, s13, s24
	s_cselect_b32 s23, s11, s23
	s_cselect_b32 s25, s56, s59
	s_cselect_b32 s24, s57, s58
	v_mov_b32_e32 v34, v140
	ds_read_b128 v[178:181], v145
	ds_read_b128 v[182:185], v145 offset:1024
	ds_read_b128 v[186:189], v145 offset:2048
	ds_read_b128 v[190:193], v145 offset:3072
	ds_read_b128 v[206:209], v145 offset:4096
	ds_read_b128 v[210:213], v145 offset:5120
	ds_read_b128 v[214:217], v145 offset:6144
	ds_read_b128 v[218:221], v145 offset:7168
	s_add_i32 m0, s38, 0xc000
	s_nop 0
	global_load_lds_dwordx4 v34, s[20:21]
	v_mov_b32_e32 v34, v141
	s_add_i32 m0, s38, 0xe000
	s_nop 0
	global_load_lds_dwordx4 v34, s[20:21]
	s_waitcnt vmcnt(8)
	s_waitcnt lgkmcnt(0)
	s_barrier
	s_waitcnt lgkmcnt(0)
	v_mfma_f32_16x16x32_bf16 v[128:131], v[146:149], v[178:181], v[128:131]
	v_mfma_f32_16x16x32_bf16 v[124:127], v[154:157], v[178:181], v[124:127]
	v_mfma_f32_16x16x32_bf16 v[112:115], v[146:149], v[186:189], v[112:115]
	v_mfma_f32_16x16x32_bf16 v[108:111], v[154:157], v[186:189], v[108:111]
	v_mfma_f32_16x16x32_bf16 v[96:99], v[146:149], v[206:209], v[96:99]
	v_mfma_f32_16x16x32_bf16 v[92:95], v[154:157], v[206:209], v[92:95]
	v_mfma_f32_16x16x32_bf16 v[80:83], v[146:149], v[214:217], v[80:83]
	v_mfma_f32_16x16x32_bf16 v[76:79], v[154:157], v[214:217], v[76:79]
	v_mfma_f32_16x16x32_bf16 v[128:131], v[150:153], v[182:185], v[128:131]
	v_mfma_f32_16x16x32_bf16 v[124:127], v[158:161], v[182:185], v[124:127]
	v_mfma_f32_16x16x32_bf16 v[112:115], v[150:153], v[190:193], v[112:115]
	v_mfma_f32_16x16x32_bf16 v[108:111], v[158:161], v[190:193], v[108:111]
	v_mfma_f32_16x16x32_bf16 v[96:99], v[150:153], v[210:213], v[96:99]
	v_mfma_f32_16x16x32_bf16 v[92:95], v[158:161], v[210:213], v[92:95]
	v_mfma_f32_16x16x32_bf16 v[80:83], v[150:153], v[218:221], v[80:83]
	v_mfma_f32_16x16x32_bf16 v[76:79], v[158:161], v[218:221], v[76:79]
	v_mfma_f32_16x16x32_bf16 v[120:123], v[162:165], v[178:181], v[120:123]
	v_mfma_f32_16x16x32_bf16 v[116:119], v[170:173], v[178:181], v[116:119]
	v_mfma_f32_16x16x32_bf16 v[104:107], v[162:165], v[186:189], v[104:107]
	v_mfma_f32_16x16x32_bf16 v[100:103], v[170:173], v[186:189], v[100:103]
	v_mfma_f32_16x16x32_bf16 v[88:91], v[162:165], v[206:209], v[88:91]
	v_mfma_f32_16x16x32_bf16 v[84:87], v[170:173], v[206:209], v[84:87]
	v_mfma_f32_16x16x32_bf16 v[68:71], v[162:165], v[214:217], v[68:71]
	v_mfma_f32_16x16x32_bf16 v[60:63], v[170:173], v[214:217], v[60:63]
	v_mfma_f32_16x16x32_bf16 v[120:123], v[166:169], v[182:185], v[120:123]
	v_mfma_f32_16x16x32_bf16 v[116:119], v[174:177], v[182:185], v[116:119]
	v_mfma_f32_16x16x32_bf16 v[104:107], v[166:169], v[190:193], v[104:107]
	v_mfma_f32_16x16x32_bf16 v[100:103], v[174:177], v[190:193], v[100:103]
	v_mfma_f32_16x16x32_bf16 v[88:91], v[166:169], v[210:213], v[88:91]
	v_mfma_f32_16x16x32_bf16 v[84:87], v[174:177], v[210:213], v[84:87]
	v_mfma_f32_16x16x32_bf16 v[68:71], v[166:169], v[218:221], v[68:71]
	v_mfma_f32_16x16x32_bf16 v[60:63], v[174:177], v[218:221], v[60:63]
	s_barrier
	v_mov_b32_e32 v34, v135
	s_mov_b32 m0, s33
	ds_read_b128 v[178:181], v145 offset:16384
	ds_read_b128 v[182:185], v145 offset:17408
	ds_read_b128 v[186:189], v145 offset:18432
	ds_read_b128 v[190:193], v145 offset:19456
	ds_read_b128 v[206:209], v145 offset:20480
	ds_read_b128 v[210:213], v145 offset:21504
	ds_read_b128 v[214:217], v145 offset:22528
	ds_read_b128 v[218:221], v145 offset:23552
	s_nop 0
	global_load_lds_dwordx4 v34, s[24:25]
	v_mov_b32_e32 v34, v137
	s_mov_b32 m0, s34
	s_nop 0
	global_load_lds_dwordx4 v34, s[24:25]
	v_mov_b32_e32 v34, v138
	s_mov_b32 m0, s36
	s_nop 0
	global_load_lds_dwordx4 v34, s[24:25]
	v_mov_b32_e32 v34, v139
	s_mov_b32 m0, s37
	s_nop 0
	global_load_lds_dwordx4 v34, s[24:25]
	v_mov_b32_e32 v34, v134
	s_mov_b32 m0, s38
	s_nop 0
	global_load_lds_dwordx4 v34, s[22:23]
	v_mov_b32_e32 v34, v136
	s_mov_b32 m0, s39
	s_nop 0
	global_load_lds_dwordx4 v34, s[22:23]
	s_waitcnt vmcnt(8)
	s_waitcnt lgkmcnt(0)
	s_barrier
	s_waitcnt lgkmcnt(0)
	v_mfma_f32_16x16x32_bf16 v[72:75], v[146:149], v[178:181], v[72:75]
	v_mfma_f32_16x16x32_bf16 v[64:67], v[154:157], v[178:181], v[64:67]
	v_mfma_f32_16x16x32_bf16 v[48:51], v[146:149], v[186:189], v[48:51]
	v_mfma_f32_16x16x32_bf16 v[44:47], v[154:157], v[186:189], v[44:47]
	v_mfma_f32_16x16x32_bf16 v[30:33], v[146:149], v[206:209], v[30:33]
	v_mfma_f32_16x16x32_bf16 v[26:29], v[154:157], v[206:209], v[26:29]
	v_mfma_f32_16x16x32_bf16 v[14:17], v[146:149], v[214:217], v[14:17]
	v_mfma_f32_16x16x32_bf16 v[10:13], v[154:157], v[214:217], v[10:13]
	v_mfma_f32_16x16x32_bf16 v[72:75], v[150:153], v[182:185], v[72:75]
	v_mfma_f32_16x16x32_bf16 v[64:67], v[158:161], v[182:185], v[64:67]
	v_mfma_f32_16x16x32_bf16 v[48:51], v[150:153], v[190:193], v[48:51]
	v_mfma_f32_16x16x32_bf16 v[44:47], v[158:161], v[190:193], v[44:47]
	v_mfma_f32_16x16x32_bf16 v[30:33], v[150:153], v[210:213], v[30:33]
	v_mfma_f32_16x16x32_bf16 v[26:29], v[158:161], v[210:213], v[26:29]
	v_mfma_f32_16x16x32_bf16 v[14:17], v[150:153], v[218:221], v[14:17]
	v_mfma_f32_16x16x32_bf16 v[10:13], v[158:161], v[218:221], v[10:13]
	v_mfma_f32_16x16x32_bf16 v[56:59], v[162:165], v[178:181], v[56:59]
	v_mfma_f32_16x16x32_bf16 v[52:55], v[170:173], v[178:181], v[52:55]
	v_mfma_f32_16x16x32_bf16 v[40:43], v[162:165], v[186:189], v[40:43]
	v_mfma_f32_16x16x32_bf16 v[36:39], v[170:173], v[186:189], v[36:39]
	v_mfma_f32_16x16x32_bf16 v[22:25], v[162:165], v[206:209], v[22:25]
	v_mfma_f32_16x16x32_bf16 v[18:21], v[170:173], v[206:209], v[18:21]
	v_mfma_f32_16x16x32_bf16 v[6:9], v[162:165], v[214:217], v[6:9]
	v_mfma_f32_16x16x32_bf16 v[2:5], v[170:173], v[214:217], v[2:5]
	v_mfma_f32_16x16x32_bf16 v[56:59], v[166:169], v[182:185], v[56:59]
	v_mfma_f32_16x16x32_bf16 v[52:55], v[174:177], v[182:185], v[52:55]
	v_mfma_f32_16x16x32_bf16 v[40:43], v[166:169], v[190:193], v[40:43]
	v_mfma_f32_16x16x32_bf16 v[36:39], v[174:177], v[190:193], v[36:39]
	v_mfma_f32_16x16x32_bf16 v[22:25], v[166:169], v[210:213], v[22:25]
	v_mfma_f32_16x16x32_bf16 v[18:21], v[174:177], v[210:213], v[18:21]
	v_mfma_f32_16x16x32_bf16 v[6:9], v[166:169], v[218:221], v[6:9]
	v_mfma_f32_16x16x32_bf16 v[2:5], v[174:177], v[218:221], v[2:5]
	s_barrier
; #define PG8_STAGE(...) PG8_STAGE_(__VA_ARGS__, 0u)
; #define PG8_WAIT_V(n) asm volatile("s_waitcnt vmcnt(" #n ")" ::: "memory")
; #define PG8_WAIT_L(n) asm volatile("s_waitcnt lgkmcnt(" #n ")" ::: "memory")
; #define PG8_BAR __builtin_amdgcn_s_barrier()
; #define PG8_SCHED __builtin_amdgcn_sched_barrier(0)
; template <class Epi, class Sched, bool ALIGN_EPI = true, bool SP2 = true>
; __device__ __forceinline__ void gemm_phase(LAS unsigned char* lds, const Gemm g, const Sched& S, const Epi& E) {
;     ...
;             PG8_LDB(B0, 1, 0); PG8_LDB(B1, 1, 1); PG8_SCHED; PG8_LDA(At, 1, 0); PG8_STAGE(PG8_SA(0, 1), a2, voffAh);
;             PG8_WAIT_V(8); PG8_WAIT_L(0); PG8_BAR; PG8_MMA(0, 0, At, B0); PG8_MMA(0, 1, At, B1); PG8_BAR; PG8_SCHED;
	v_add_u32_e32 v34, s44, v143
	ds_read_b128 v[146:149], v34
	ds_read_b128 v[150:153], v34 offset:1024
	ds_read_b128 v[154:157], v34 offset:2048
	ds_read_b128 v[158:161], v34 offset:3072
	v_add_u32_e32 v34, s49, v143
	ds_read_b128 v[162:165], v34
	ds_read_b128 v[166:169], v34 offset:1024
	ds_read_b128 v[170:173], v34 offset:2048
	ds_read_b128 v[174:177], v34 offset:3072
	v_mov_b32_e32 v34, v140
	s_mov_b32 m0, s40
	ds_read_b128 v[178:181], v145 offset:32768
	ds_read_b128 v[182:185], v145 offset:33792
	ds_read_b128 v[186:189], v145 offset:34816
	ds_read_b128 v[190:193], v145 offset:35840
	ds_read_b128 v[206:209], v145 offset:36864
	ds_read_b128 v[210:213], v145 offset:37888
	ds_read_b128 v[214:217], v145 offset:38912
	ds_read_b128 v[218:221], v145 offset:39936
	s_nop 0
	global_load_lds_dwordx4 v34, s[22:23]
	v_mov_b32_e32 v34, v141
	s_mov_b32 m0, s41
	s_nop 0
	global_load_lds_dwordx4 v34, s[22:23]
	s_waitcnt vmcnt(8)
	s_waitcnt lgkmcnt(0)
	s_barrier
	s_waitcnt lgkmcnt(0)
	v_mfma_f32_16x16x32_bf16 v[128:131], v[146:149], v[178:181], v[128:131]
	v_mfma_f32_16x16x32_bf16 v[124:127], v[154:157], v[178:181], v[124:127]
	v_mfma_f32_16x16x32_bf16 v[112:115], v[146:149], v[186:189], v[112:115]
	v_mfma_f32_16x16x32_bf16 v[108:111], v[154:157], v[186:189], v[108:111]
	v_mfma_f32_16x16x32_bf16 v[96:99], v[146:149], v[206:209], v[96:99]
	v_mfma_f32_16x16x32_bf16 v[92:95], v[154:157], v[206:209], v[92:95]
	v_mfma_f32_16x16x32_bf16 v[80:83], v[146:149], v[214:217], v[80:83]
	v_mfma_f32_16x16x32_bf16 v[76:79], v[154:157], v[214:217], v[76:79]
	v_mfma_f32_16x16x32_bf16 v[128:131], v[150:153], v[182:185], v[128:131]
	v_mfma_f32_16x16x32_bf16 v[124:127], v[158:161], v[182:185], v[124:127]
	v_mfma_f32_16x16x32_bf16 v[112:115], v[150:153], v[190:193], v[112:115]
	v_mfma_f32_16x16x32_bf16 v[108:111], v[158:161], v[190:193], v[108:111]
	v_mfma_f32_16x16x32_bf16 v[96:99], v[150:153], v[210:213], v[96:99]
	v_mfma_f32_16x16x32_bf16 v[92:95], v[158:161], v[210:213], v[92:95]
	v_mfma_f32_16x16x32_bf16 v[80:83], v[150:153], v[218:221], v[80:83]
	v_mfma_f32_16x16x32_bf16 v[76:79], v[158:161], v[218:221], v[76:79]
	v_mfma_f32_16x16x32_bf16 v[120:123], v[162:165], v[178:181], v[120:123]
	v_mfma_f32_16x16x32_bf16 v[116:119], v[170:173], v[178:181], v[116:119]
	v_mfma_f32_16x16x32_bf16 v[104:107], v[162:165], v[186:189], v[104:107]
	v_mfma_f32_16x16x32_bf16 v[100:103], v[170:173], v[186:189], v[100:103]
	v_mfma_f32_16x16x32_bf16 v[88:91], v[162:165], v[206:209], v[88:91]
	v_mfma_f32_16x16x32_bf16 v[84:87], v[170:173], v[206:209], v[84:87]
	v_mfma_f32_16x16x32_bf16 v[68:71], v[162:165], v[214:217], v[68:71]
	v_mfma_f32_16x16x32_bf16 v[60:63], v[170:173], v[214:217], v[60:63]
	v_mfma_f32_16x16x32_bf16 v[120:123], v[166:169], v[182:185], v[120:123]
	v_mfma_f32_16x16x32_bf16 v[116:119], v[174:177], v[182:185], v[116:119]
	v_mfma_f32_16x16x32_bf16 v[104:107], v[166:169], v[190:193], v[104:107]
	v_mfma_f32_16x16x32_bf16 v[100:103], v[174:177], v[190:193], v[100:103]
	v_mfma_f32_16x16x32_bf16 v[88:91], v[166:169], v[210:213], v[88:91]
	v_mfma_f32_16x16x32_bf16 v[84:87], v[174:177], v[210:213], v[84:87]
	v_mfma_f32_16x16x32_bf16 v[68:71], v[166:169], v[218:221], v[68:71]
	v_mfma_f32_16x16x32_bf16 v[60:63], v[174:177], v[218:221], v[60:63]
	s_barrier
; #define PG8_STAGE(...) PG8_STAGE_(__VA_ARGS__, 0u)
; #define PG8_WAIT_V(n) asm volatile("s_waitcnt vmcnt(" #n ")" ::: "memory")
; #define PG8_WAIT_L(n) asm volatile("s_waitcnt lgkmcnt(" #n ")" ::: "memory")
; #define PG8_BAR __builtin_amdgcn_s_barrier()
; #define PG8_SCHED __builtin_amdgcn_sched_barrier(0)
; template <class Epi, class Sched, bool ALIGN_EPI = true, bool SP2 = true>
; __device__ __forceinline__ void gemm_phase(LAS unsigned char* lds, const Gemm g, const Sched& S, const Epi& E) {
;     ...
;             if constexpr (!Epi::HALF_M) PG8_LDA(At, 1, 1); PG8_STAGE(PG8_SB(1, 0), b3, voffB); PG8_STAGE(PG8_SB(1, 1), b3, voffBh); PG8_STAGE(PG8_SA(1, 0), a3, voffA);
;             PG8_WAIT_V(8); PG8_WAIT_L(0); PG8_BAR; if constexpr (!Epi::HALF_M) { PG8_MMA(1, 0, At, B0); PG8_MMA(1, 1, At, B1); } PG8_BAR; PG8_SCHED;
	v_mov_b32_e32 v34, v135
	ds_read_b128 v[178:181], v145 offset:49152
	ds_read_b128 v[182:185], v145 offset:50176
	ds_read_b128 v[186:189], v145 offset:51200
	ds_read_b128 v[190:193], v145 offset:52224
	ds_read_b128 v[206:209], v145 offset:53248
	ds_read_b128 v[210:213], v145 offset:54272
	ds_read_b128 v[214:217], v145 offset:55296
	ds_read_b128 v[218:221], v145 offset:56320
	s_mov_b32 m0, s45
	v_lshl_add_u64 v[132:133], s[24:25], 0, v[34:35]
	v_lshl_add_u64 v[132:133], v[132:133], 0, s[80:81]
	v_mov_b32_e32 v34, v137
	global_load_lds_dwordx4 v[132:133], off
	s_mov_b32 m0, s46
	v_lshl_add_u64 v[132:133], s[24:25], 0, v[34:35]
	v_lshl_add_u64 v[132:133], v[132:133], 0, s[80:81]
	v_mov_b32_e32 v34, v138
	global_load_lds_dwordx4 v[132:133], off
	s_mov_b32 m0, s50
	v_lshl_add_u64 v[132:133], s[24:25], 0, v[34:35]
	v_lshl_add_u64 v[132:133], v[132:133], 0, s[80:81]
	v_mov_b32_e32 v34, v139
	global_load_lds_dwordx4 v[132:133], off
	s_mov_b32 m0, s51
	v_lshl_add_u64 v[132:133], s[24:25], 0, v[34:35]
	v_lshl_add_u64 v[132:133], v[132:133], 0, s[80:81]
	v_mov_b32_e32 v34, v134
	global_load_lds_dwordx4 v[132:133], off
	s_mov_b32 m0, s47
	v_lshl_add_u64 v[132:133], s[22:23], 0, v[34:35]
	v_lshl_add_u64 v[132:133], v[132:133], 0, s[80:81]
	v_mov_b32_e32 v34, v136
	global_load_lds_dwordx4 v[132:133], off
	s_mov_b32 m0, s48
	v_lshl_add_u64 v[132:133], s[22:23], 0, v[34:35]
	v_lshl_add_u64 v[132:133], v[132:133], 0, s[80:81]
	global_load_lds_dwordx4 v[132:133], off
	s_waitcnt vmcnt(8)
	s_waitcnt lgkmcnt(0)
	s_barrier
	s_waitcnt lgkmcnt(0)
	v_mfma_f32_16x16x32_bf16 v[72:75], v[146:149], v[178:181], v[72:75]
	v_mfma_f32_16x16x32_bf16 v[64:67], v[154:157], v[178:181], v[64:67]
	v_mfma_f32_16x16x32_bf16 v[48:51], v[146:149], v[186:189], v[48:51]
	v_mfma_f32_16x16x32_bf16 v[44:47], v[154:157], v[186:189], v[44:47]
	v_mfma_f32_16x16x32_bf16 v[30:33], v[146:149], v[206:209], v[30:33]
	v_mfma_f32_16x16x32_bf16 v[26:29], v[154:157], v[206:209], v[26:29]
	v_mfma_f32_16x16x32_bf16 v[14:17], v[146:149], v[214:217], v[14:17]
	v_mfma_f32_16x16x32_bf16 v[10:13], v[154:157], v[214:217], v[10:13]
	v_mfma_f32_16x16x32_bf16 v[72:75], v[150:153], v[182:185], v[72:75]
	v_mfma_f32_16x16x32_bf16 v[64:67], v[158:161], v[182:185], v[64:67]
	v_mfma_f32_16x16x32_bf16 v[48:51], v[150:153], v[190:193], v[48:51]
	v_mfma_f32_16x16x32_bf16 v[44:47], v[158:161], v[190:193], v[44:47]
	v_mfma_f32_16x16x32_bf16 v[30:33], v[150:153], v[210:213], v[30:33]
	v_mfma_f32_16x16x32_bf16 v[26:29], v[158:161], v[210:213], v[26:29]
	v_mfma_f32_16x16x32_bf16 v[14:17], v[150:153], v[218:221], v[14:17]
	v_mfma_f32_16x16x32_bf16 v[10:13], v[158:161], v[218:221], v[10:13]
	v_mfma_f32_16x16x32_bf16 v[56:59], v[162:165], v[178:181], v[56:59]
	v_mfma_f32_16x16x32_bf16 v[52:55], v[170:173], v[178:181], v[52:55]
	v_mfma_f32_16x16x32_bf16 v[40:43], v[162:165], v[186:189], v[40:43]
	v_mfma_f32_16x16x32_bf16 v[36:39], v[170:173], v[186:189], v[36:39]
	v_mfma_f32_16x16x32_bf16 v[22:25], v[162:165], v[206:209], v[22:25]
	v_mfma_f32_16x16x32_bf16 v[18:21], v[170:173], v[206:209], v[18:21]
	v_mfma_f32_16x16x32_bf16 v[6:9], v[162:165], v[214:217], v[6:9]
	v_mfma_f32_16x16x32_bf16 v[2:5], v[170:173], v[214:217], v[2:5]
	v_mfma_f32_16x16x32_bf16 v[56:59], v[166:169], v[182:185], v[56:59]
	v_mfma_f32_16x16x32_bf16 v[52:55], v[174:177], v[182:185], v[52:55]
	v_mfma_f32_16x16x32_bf16 v[40:43], v[166:169], v[190:193], v[40:43]
	v_mfma_f32_16x16x32_bf16 v[36:39], v[174:177], v[190:193], v[36:39]
	v_mfma_f32_16x16x32_bf16 v[22:25], v[166:169], v[210:213], v[22:25]
	v_mfma_f32_16x16x32_bf16 v[18:21], v[174:177], v[210:213], v[18:21]
	v_mfma_f32_16x16x32_bf16 v[6:9], v[166:169], v[218:221], v[6:9]
	v_mfma_f32_16x16x32_bf16 v[2:5], v[174:177], v[218:221], v[2:5]
	s_barrier
	s_add_u32 s20, s20, 0x100
	s_addc_u32 s21, s21, 0
	s_add_u32 s58, s58, 0x100
	s_addc_u32 s59, s59, 0
	s_cmp_ge_i32 s60, s42
	s_mov_b32 s22, s60
	s_cbranch_scc0 .LBB0_1044

; #define PG8_STAGE(...) PG8_STAGE_(__VA_ARGS__, 0u)
; #define PG8_WAIT_V(n) asm volatile("s_waitcnt vmcnt(" #n ")" ::: "memory")
; #define PG8_WAIT_L(n) asm volatile("s_waitcnt lgkmcnt(" #n ")" ::: "memory")
; #define PG8_BAR __builtin_amdgcn_s_barrier()
; #define PG8_SCHED __builtin_amdgcn_sched_barrier(0)
; template <class Epi, class Sched, bool ALIGN_EPI = true, bool SP2 = true>
; __device__ __forceinline__ void gemm_phase(LAS unsigned char* lds, const Gemm g, const Sched& S, const Epi& E) {
;     ...
;         const char* nA = has_next ? (const char*)g.A + (size_t)nxt.pm * tstepA + (size_t)nxt.ak * ESZ : cA; const char* nB = has_next ? (const char*)g.Bt + (size_t)nxt.pn * tstepB : cB;
;         for (int t = 0; t < nt; t += 2) {
;             const bool last = (t == nt - 2);
;             const char* a1 = cA + (size_t)(t + 1) * kstep;
;             const char* a2 = last ? nA : cA + (size_t)(t + 2) * kstep; const char* b2 = last ? nB : cB + (size_t)(t + 2) * kstep;
;             const char* a3 = a2 + kstep; const char* b3 = b2 + kstep;
;             if constexpr (SP2) {
;             PG8_LDB(B0, 0, 0); PG8_LDB(B1, 0, 1); PG8_SCHED; PG8_LDA(At, 0, 0); PG8_STAGE(PG8_SA(1, 1), a1, voffAh);
;             PG8_WAIT_V(8); PG8_WAIT_L(0); PG8_BAR; PG8_MMA(0, 0, At, B0); PG8_MMA(0, 1, At, B1); PG8_BAR; PG8_SCHED;
;             if constexpr (!Epi::HALF_M) PG8_LDA(At, 0, 1); PG8_STAGE(PG8_SB(0, 0), b2, voffB); PG8_STAGE(PG8_SB(0, 1), b2, voffBh); PG8_STAGE(PG8_SA(0, 0), a2, voffA);
;             PG8_WAIT_V(8); PG8_WAIT_L(0); PG8_BAR; if constexpr (!Epi::HALF_M) { PG8_MMA(1, 0, At, B0); PG8_MMA(1, 1, At, B1); } PG8_BAR; PG8_SCHED;
.LBB0_1266:
	s_add_i32 s50, s20, 2
	s_add_u32 s18, s16, 0x100
	v_add_u32_e32 v34, s23, v249
	s_addc_u32 s19, s17, 0
	ds_read_b128 v[48:51], v34
	ds_read_b128 v[60:63], v34 offset:1024
	ds_read_b128 v[72:75], v34 offset:2048
	ds_read_b128 v[84:87], v34 offset:3072
	v_add_u32_e32 v34, s26, v249
	s_add_u32 s52, s4, s16
	ds_read_b128 v[96:99], v34
	ds_read_b128 v[108:111], v34 offset:1024
	ds_read_b128 v[120:123], v34 offset:2048
	ds_read_b128 v[132:135], v34 offset:3072
	s_addc_u32 s53, s5, s17
	s_add_u32 s16, s52, 0x100
	s_addc_u32 s17, s53, 0
	s_cmp_eq_u32 s45, s20
	s_cselect_b32 s20, 0, s18
	s_cselect_b32 s17, s48, s17
	s_cselect_b32 s16, s49, s16
	s_cselect_b32 s21, 0, s19
	s_add_u32 s20, s2, s20
	s_addc_u32 s21, s3, s21
	v_mov_b32_e32 v34, v246
	ds_read_b128 v[144:147], v250
	ds_read_b128 v[156:159], v250 offset:1024
	ds_read_b128 v[164:167], v250 offset:2048
	ds_read_b128 v[168:171], v250 offset:3072
	ds_read_b128 v[180:183], v250 offset:4096
	ds_read_b128 v[184:187], v250 offset:5120
	ds_read_b128 v[188:191], v250 offset:6144
	ds_read_b128 v[192:195], v250 offset:7168
	s_add_i32 m0, s29, 0xc000
	v_lshl_add_u64 v[210:211], s[52:53], 0, v[34:35]
	v_lshl_add_u64 v[210:211], v[210:211], 0, s[80:81]
	v_mov_b32_e32 v34, v247
	global_load_lds_dwordx4 v[210:211], off
	s_add_i32 m0, s29, 0xe000
	v_lshl_add_u64 v[210:211], s[52:53], 0, v[34:35]
	v_lshl_add_u64 v[210:211], v[210:211], 0, s[80:81]
	global_load_lds_dwordx4 v[210:211], off
	s_waitcnt vmcnt(8)
	s_waitcnt lgkmcnt(0)
	s_barrier
	s_waitcnt lgkmcnt(0)
	v_mfma_f32_16x16x32_bf16 v[176:179], v[48:51], v[144:147], v[176:179]
	v_mfma_f32_16x16x32_bf16 v[172:175], v[72:75], v[144:147], v[172:175]
	v_mfma_f32_16x16x32_bf16 v[148:151], v[48:51], v[164:167], v[148:151]
	v_mfma_f32_16x16x32_bf16 v[140:143], v[72:75], v[164:167], v[140:143]
	v_mfma_f32_16x16x32_bf16 v[124:127], v[48:51], v[180:183], v[124:127]
	v_mfma_f32_16x16x32_bf16 v[116:119], v[72:75], v[180:183], v[116:119]
	v_mfma_f32_16x16x32_bf16 v[100:103], v[48:51], v[188:191], v[100:103]
	v_mfma_f32_16x16x32_bf16 v[92:95], v[72:75], v[188:191], v[92:95]
	v_mfma_f32_16x16x32_bf16 v[176:179], v[60:63], v[156:159], v[176:179]
	v_mfma_f32_16x16x32_bf16 v[172:175], v[84:87], v[156:159], v[172:175]
	v_mfma_f32_16x16x32_bf16 v[148:151], v[60:63], v[168:171], v[148:151]
	v_mfma_f32_16x16x32_bf16 v[140:143], v[84:87], v[168:171], v[140:143]
	v_mfma_f32_16x16x32_bf16 v[124:127], v[60:63], v[184:187], v[124:127]
	v_mfma_f32_16x16x32_bf16 v[116:119], v[84:87], v[184:187], v[116:119]
	v_mfma_f32_16x16x32_bf16 v[100:103], v[60:63], v[192:195], v[100:103]
	v_mfma_f32_16x16x32_bf16 v[92:95], v[84:87], v[192:195], v[92:95]
	v_mfma_f32_16x16x32_bf16 v[160:163], v[96:99], v[144:147], v[160:163]
	v_mfma_f32_16x16x32_bf16 v[136:139], v[96:99], v[164:167], v[136:139]
	v_mfma_f32_16x16x32_bf16 v[128:131], v[120:123], v[164:167], v[128:131]
	v_mfma_f32_16x16x32_bf16 v[112:115], v[96:99], v[180:183], v[112:115]
	v_mfma_f32_16x16x32_bf16 v[104:107], v[120:123], v[180:183], v[104:107]
	v_mfma_f32_16x16x32_bf16 v[88:91], v[96:99], v[188:191], v[88:91]
	v_mfma_f32_16x16x32_bf16 v[80:83], v[120:123], v[188:191], v[80:83]
	v_mfma_f32_16x16x32_bf16 v[160:163], v[108:111], v[156:159], v[160:163]
	v_mfma_f32_16x16x32_bf16 v[144:147], v[120:123], v[144:147], v[152:155]
	v_mfma_f32_16x16x32_bf16 v[136:139], v[108:111], v[168:171], v[136:139]
	v_mfma_f32_16x16x32_bf16 v[128:131], v[132:135], v[168:171], v[128:131]
	v_mfma_f32_16x16x32_bf16 v[112:115], v[108:111], v[184:187], v[112:115]
	v_mfma_f32_16x16x32_bf16 v[104:107], v[132:135], v[184:187], v[104:107]
	v_mfma_f32_16x16x32_bf16 v[88:91], v[108:111], v[192:195], v[88:91]
	v_mfma_f32_16x16x32_bf16 v[80:83], v[132:135], v[192:195], v[80:83]
	v_mfma_f32_16x16x32_bf16 v[144:147], v[132:135], v[156:159], v[144:147]
	s_barrier
	v_mov_b32_e32 v34, v241
	s_mov_b32 m0, s24
	ds_read_b128 v[152:155], v250 offset:16384
	ds_read_b128 v[156:159], v250 offset:17408
	ds_read_b128 v[164:167], v250 offset:18432
	ds_read_b128 v[168:171], v250 offset:19456
	ds_read_b128 v[180:183], v250 offset:20480
	ds_read_b128 v[184:187], v250 offset:21504
	ds_read_b128 v[188:191], v250 offset:22528
	ds_read_b128 v[192:195], v250 offset:23552
	s_nop 0
	global_load_lds_dwordx4 v34, s[20:21]
	v_mov_b32_e32 v34, v243
	s_mov_b32 m0, s25
	s_nop 0
	global_load_lds_dwordx4 v34, s[20:21]
	v_mov_b32_e32 v34, v244
	s_mov_b32 m0, s27
	s_nop 0
	global_load_lds_dwordx4 v34, s[20:21]
	v_mov_b32_e32 v34, v245
	s_mov_b32 m0, s28
	s_nop 0
	global_load_lds_dwordx4 v34, s[20:21]
	v_mov_b32_e32 v34, v197
	s_mov_b32 m0, s29
	s_nop 0
	global_load_lds_dwordx4 v34, s[16:17]
	v_mov_b32_e32 v34, v242
	s_mov_b32 m0, s30
	s_nop 0
	global_load_lds_dwordx4 v34, s[16:17]
	s_waitcnt vmcnt(8)
	s_waitcnt lgkmcnt(0)
	s_barrier
; #define PG8_STAGE(...) PG8_STAGE_(__VA_ARGS__, 0u)
; #define PG8_WAIT_V(n) asm volatile("s_waitcnt vmcnt(" #n ")" ::: "memory")
; #define PG8_WAIT_L(n) asm volatile("s_waitcnt lgkmcnt(" #n ")" ::: "memory")
; #define PG8_BAR __builtin_amdgcn_s_barrier()
; #define PG8_SCHED __builtin_amdgcn_sched_barrier(0)
; template <class Epi, class Sched, bool ALIGN_EPI = true, bool SP2 = true>
; __device__ __forceinline__ void gemm_phase(LAS unsigned char* lds, const Gemm g, const Sched& S, const Epi& E) {
;     ...
;             PG8_WAIT_V(8); PG8_WAIT_L(0); PG8_BAR; if constexpr (!Epi::HALF_M) { PG8_MMA(1, 0, At, B0); PG8_MMA(1, 1, At, B1); } PG8_BAR; PG8_SCHED;
;             PG8_LDB(B0, 1, 0); PG8_LDB(B1, 1, 1); PG8_SCHED; PG8_LDA(At, 1, 0); PG8_STAGE(PG8_SA(0, 1), a2, voffAh);
;             PG8_WAIT_V(8); PG8_WAIT_L(0); PG8_BAR; PG8_MMA(0, 0, At, B0); PG8_MMA(0, 1, At, B1); PG8_BAR; PG8_SCHED;
	s_waitcnt lgkmcnt(0)
	v_mfma_f32_16x16x32_bf16 v[76:79], v[48:51], v[152:155], v[76:79]
	v_mfma_f32_16x16x32_bf16 v[68:71], v[72:75], v[152:155], v[68:71]
	v_mfma_f32_16x16x32_bf16 v[52:55], v[48:51], v[164:167], v[52:55]
	v_mfma_f32_16x16x32_bf16 v[44:47], v[72:75], v[164:167], v[44:47]
	v_mfma_f32_16x16x32_bf16 v[30:33], v[48:51], v[180:183], v[30:33]
	v_mfma_f32_16x16x32_bf16 v[26:29], v[72:75], v[180:183], v[26:29]
	v_mfma_f32_16x16x32_bf16 v[14:17], v[48:51], v[188:191], v[14:17]
	v_mfma_f32_16x16x32_bf16 v[10:13], v[72:75], v[188:191], v[10:13]
	v_mfma_f32_16x16x32_bf16 v[76:79], v[60:63], v[156:159], v[76:79]
	v_mfma_f32_16x16x32_bf16 v[68:71], v[84:87], v[156:159], v[68:71]
	v_mfma_f32_16x16x32_bf16 v[52:55], v[60:63], v[168:171], v[52:55]
	v_mfma_f32_16x16x32_bf16 v[44:47], v[84:87], v[168:171], v[44:47]
	v_mfma_f32_16x16x32_bf16 v[30:33], v[60:63], v[184:187], v[30:33]
	v_mfma_f32_16x16x32_bf16 v[26:29], v[84:87], v[184:187], v[26:29]
	v_mfma_f32_16x16x32_bf16 v[14:17], v[60:63], v[192:195], v[14:17]
	v_mfma_f32_16x16x32_bf16 v[10:13], v[84:87], v[192:195], v[10:13]
	v_mfma_f32_16x16x32_bf16 v[56:59], v[120:123], v[152:155], v[56:59]
	v_mfma_f32_16x16x32_bf16 v[40:43], v[96:99], v[164:167], v[40:43]
	v_mfma_f32_16x16x32_bf16 v[36:39], v[120:123], v[164:167], v[36:39]
	v_mfma_f32_16x16x32_bf16 v[22:25], v[96:99], v[180:183], v[22:25]
	v_mfma_f32_16x16x32_bf16 v[18:21], v[120:123], v[180:183], v[18:21]
	v_mfma_f32_16x16x32_bf16 v[6:9], v[96:99], v[188:191], v[6:9]
	v_mfma_f32_16x16x32_bf16 v[2:5], v[120:123], v[188:191], v[2:5]
	v_mfma_f32_16x16x32_bf16 v[48:51], v[96:99], v[152:155], v[64:67]
	v_mfma_f32_16x16x32_bf16 v[56:59], v[132:135], v[156:159], v[56:59]
	v_mfma_f32_16x16x32_bf16 v[40:43], v[108:111], v[168:171], v[40:43]
	v_mfma_f32_16x16x32_bf16 v[36:39], v[132:135], v[168:171], v[36:39]
	v_mfma_f32_16x16x32_bf16 v[22:25], v[108:111], v[184:187], v[22:25]
	v_mfma_f32_16x16x32_bf16 v[18:21], v[132:135], v[184:187], v[18:21]
	v_mfma_f32_16x16x32_bf16 v[6:9], v[108:111], v[192:195], v[6:9]
	v_mfma_f32_16x16x32_bf16 v[2:5], v[132:135], v[192:195], v[2:5]
	v_mfma_f32_16x16x32_bf16 v[48:51], v[108:111], v[156:159], v[48:51]
	s_barrier
	v_add_u32_e32 v34, s35, v249
	ds_read_b128 v[60:63], v34
	ds_read_b128 v[64:67], v34 offset:1024
	ds_read_b128 v[72:75], v34 offset:2048
	ds_read_b128 v[84:87], v34 offset:3072
	v_add_u32_e32 v34, s40, v249
	ds_read_b128 v[96:99], v34
	ds_read_b128 v[108:111], v34 offset:1024
	ds_read_b128 v[120:123], v34 offset:2048
	ds_read_b128 v[132:135], v34 offset:3072
	v_mov_b32_e32 v34, v246
	s_mov_b32 m0, s31
	ds_read_b128 v[152:155], v250 offset:32768
	ds_read_b128 v[156:159], v250 offset:33792
	ds_read_b128 v[164:167], v250 offset:34816
	ds_read_b128 v[168:171], v250 offset:35840
	ds_read_b128 v[180:183], v250 offset:36864
	ds_read_b128 v[184:187], v250 offset:37888
	ds_read_b128 v[188:191], v250 offset:38912
	ds_read_b128 v[192:195], v250 offset:39936
	s_nop 0
	global_load_lds_dwordx4 v34, s[16:17]
	v_mov_b32_e32 v34, v247
	s_mov_b32 m0, s34
	s_nop 0
	global_load_lds_dwordx4 v34, s[16:17]
	s_waitcnt vmcnt(8)
	s_waitcnt lgkmcnt(0)
	s_barrier
	s_waitcnt lgkmcnt(0)
	v_mfma_f32_16x16x32_bf16 v[176:179], v[60:63], v[152:155], v[176:179]
	v_mfma_f32_16x16x32_bf16 v[172:175], v[72:75], v[152:155], v[172:175]
	v_mfma_f32_16x16x32_bf16 v[148:151], v[60:63], v[164:167], v[148:151]
	v_mfma_f32_16x16x32_bf16 v[140:143], v[72:75], v[164:167], v[140:143]
	v_mfma_f32_16x16x32_bf16 v[124:127], v[60:63], v[180:183], v[124:127]
	v_mfma_f32_16x16x32_bf16 v[116:119], v[72:75], v[180:183], v[116:119]
	v_mfma_f32_16x16x32_bf16 v[100:103], v[60:63], v[188:191], v[100:103]
	v_mfma_f32_16x16x32_bf16 v[92:95], v[72:75], v[188:191], v[92:95]
	v_mfma_f32_16x16x32_bf16 v[176:179], v[64:67], v[156:159], v[176:179]
	v_mfma_f32_16x16x32_bf16 v[172:175], v[84:87], v[156:159], v[172:175]
	v_mfma_f32_16x16x32_bf16 v[148:151], v[64:67], v[168:171], v[148:151]
	v_mfma_f32_16x16x32_bf16 v[140:143], v[84:87], v[168:171], v[140:143]
	v_mfma_f32_16x16x32_bf16 v[124:127], v[64:67], v[184:187], v[124:127]
	v_mfma_f32_16x16x32_bf16 v[116:119], v[84:87], v[184:187], v[116:119]
	v_mfma_f32_16x16x32_bf16 v[100:103], v[64:67], v[192:195], v[100:103]
	v_mfma_f32_16x16x32_bf16 v[92:95], v[84:87], v[192:195], v[92:95]
	v_mfma_f32_16x16x32_bf16 v[160:163], v[96:99], v[152:155], v[160:163]
	v_mfma_f32_16x16x32_bf16 v[144:147], v[120:123], v[152:155], v[144:147]
	v_mfma_f32_16x16x32_bf16 v[136:139], v[96:99], v[164:167], v[136:139]
	v_mfma_f32_16x16x32_bf16 v[128:131], v[120:123], v[164:167], v[128:131]
	v_mfma_f32_16x16x32_bf16 v[112:115], v[96:99], v[180:183], v[112:115]
	v_mfma_f32_16x16x32_bf16 v[104:107], v[120:123], v[180:183], v[104:107]
	v_mfma_f32_16x16x32_bf16 v[88:91], v[96:99], v[188:191], v[88:91]
	v_mfma_f32_16x16x32_bf16 v[80:83], v[120:123], v[188:191], v[80:83]
	v_mfma_f32_16x16x32_bf16 v[160:163], v[108:111], v[156:159], v[160:163]
	v_mfma_f32_16x16x32_bf16 v[152:155], v[132:135], v[156:159], v[144:147]
	v_mfma_f32_16x16x32_bf16 v[136:139], v[108:111], v[168:171], v[136:139]
	v_mfma_f32_16x16x32_bf16 v[128:131], v[132:135], v[168:171], v[128:131]
	v_mfma_f32_16x16x32_bf16 v[112:115], v[108:111], v[184:187], v[112:115]
	v_mfma_f32_16x16x32_bf16 v[104:107], v[132:135], v[184:187], v[104:107]
	v_mfma_f32_16x16x32_bf16 v[88:91], v[108:111], v[192:195], v[88:91]
	v_mfma_f32_16x16x32_bf16 v[80:83], v[132:135], v[192:195], v[80:83]
	s_barrier
; #define PG8_STAGE(...) PG8_STAGE_(__VA_ARGS__, 0u)
; #define PG8_WAIT_V(n) asm volatile("s_waitcnt vmcnt(" #n ")" ::: "memory")
; #define PG8_WAIT_L(n) asm volatile("s_waitcnt lgkmcnt(" #n ")" ::: "memory")
; #define PG8_BAR __builtin_amdgcn_s_barrier()
; #define PG8_SCHED __builtin_amdgcn_sched_barrier(0)
; template <class Epi, class Sched, bool ALIGN_EPI = true, bool SP2 = true>
; __device__ __forceinline__ void gemm_phase(LAS unsigned char* lds, const Gemm g, const Sched& S, const Epi& E) {
;     ...
;             if constexpr (!Epi::HALF_M) PG8_LDA(At, 1, 1); PG8_STAGE(PG8_SB(1, 0), b3, voffB); PG8_STAGE(PG8_SB(1, 1), b3, voffBh); PG8_STAGE(PG8_SA(1, 0), a3, voffA);
;             PG8_WAIT_V(8); PG8_WAIT_L(0); PG8_BAR; if constexpr (!Epi::HALF_M) { PG8_MMA(1, 0, At, B0); PG8_MMA(1, 1, At, B1); } PG8_BAR; PG8_SCHED;
	v_mov_b32_e32 v34, v241
	ds_read_b128 v[144:147], v250 offset:49152
	ds_read_b128 v[156:159], v250 offset:50176
	ds_read_b128 v[164:167], v250 offset:51200
	ds_read_b128 v[168:171], v250 offset:52224
	ds_read_b128 v[180:183], v250 offset:53248
	ds_read_b128 v[184:187], v250 offset:54272
	ds_read_b128 v[188:191], v250 offset:55296
	ds_read_b128 v[192:195], v250 offset:56320
	s_mov_b32 m0, s36
	v_lshl_add_u64 v[210:211], s[20:21], 0, v[34:35]
	v_lshl_add_u64 v[210:211], v[210:211], 0, s[80:81]
	v_mov_b32_e32 v34, v243
	global_load_lds_dwordx4 v[210:211], off
	s_mov_b32 m0, s37
	v_lshl_add_u64 v[210:211], s[20:21], 0, v[34:35]
	v_lshl_add_u64 v[210:211], v[210:211], 0, s[80:81]
	v_mov_b32_e32 v34, v244
	global_load_lds_dwordx4 v[210:211], off
	s_mov_b32 m0, s41
	v_lshl_add_u64 v[210:211], s[20:21], 0, v[34:35]
	v_lshl_add_u64 v[210:211], v[210:211], 0, s[80:81]
	v_mov_b32_e32 v34, v245
	global_load_lds_dwordx4 v[210:211], off
	s_mov_b32 m0, s42
	v_lshl_add_u64 v[210:211], s[20:21], 0, v[34:35]
	v_lshl_add_u64 v[210:211], v[210:211], 0, s[80:81]
	v_mov_b32_e32 v34, v197
	global_load_lds_dwordx4 v[210:211], off
	s_mov_b32 m0, s38
	v_lshl_add_u64 v[210:211], s[16:17], 0, v[34:35]
	v_lshl_add_u64 v[210:211], v[210:211], 0, s[80:81]
	v_mov_b32_e32 v34, v242
	global_load_lds_dwordx4 v[210:211], off
	s_mov_b32 m0, s39
	v_lshl_add_u64 v[210:211], s[16:17], 0, v[34:35]
	v_lshl_add_u64 v[210:211], v[210:211], 0, s[80:81]
	global_load_lds_dwordx4 v[210:211], off
	s_waitcnt vmcnt(8)
	s_waitcnt lgkmcnt(0)
	s_barrier
	s_waitcnt lgkmcnt(0)
	v_mfma_f32_16x16x32_bf16 v[76:79], v[60:63], v[144:147], v[76:79]
	v_mfma_f32_16x16x32_bf16 v[68:71], v[72:75], v[144:147], v[68:71]
	v_mfma_f32_16x16x32_bf16 v[52:55], v[60:63], v[164:167], v[52:55]
	v_mfma_f32_16x16x32_bf16 v[44:47], v[72:75], v[164:167], v[44:47]
	v_mfma_f32_16x16x32_bf16 v[30:33], v[60:63], v[180:183], v[30:33]
	v_mfma_f32_16x16x32_bf16 v[26:29], v[72:75], v[180:183], v[26:29]
	v_mfma_f32_16x16x32_bf16 v[14:17], v[60:63], v[188:191], v[14:17]
	v_mfma_f32_16x16x32_bf16 v[10:13], v[72:75], v[188:191], v[10:13]
	v_mfma_f32_16x16x32_bf16 v[76:79], v[64:67], v[156:159], v[76:79]
	v_mfma_f32_16x16x32_bf16 v[68:71], v[84:87], v[156:159], v[68:71]
	v_mfma_f32_16x16x32_bf16 v[52:55], v[64:67], v[168:171], v[52:55]
	v_mfma_f32_16x16x32_bf16 v[44:47], v[84:87], v[168:171], v[44:47]
	v_mfma_f32_16x16x32_bf16 v[30:33], v[64:67], v[184:187], v[30:33]
	v_mfma_f32_16x16x32_bf16 v[26:29], v[84:87], v[184:187], v[26:29]
	v_mfma_f32_16x16x32_bf16 v[14:17], v[64:67], v[192:195], v[14:17]
	v_mfma_f32_16x16x32_bf16 v[10:13], v[84:87], v[192:195], v[10:13]
	v_mfma_f32_16x16x32_bf16 v[48:51], v[96:99], v[144:147], v[48:51]
	v_mfma_f32_16x16x32_bf16 v[64:67], v[108:111], v[156:159], v[48:51]
	v_mfma_f32_16x16x32_bf16 v[48:51], v[120:123], v[144:147], v[56:59]
	v_mfma_f32_16x16x32_bf16 v[40:43], v[96:99], v[164:167], v[40:43]
	v_mfma_f32_16x16x32_bf16 v[36:39], v[120:123], v[164:167], v[36:39]
	v_mfma_f32_16x16x32_bf16 v[22:25], v[96:99], v[180:183], v[22:25]
	v_mfma_f32_16x16x32_bf16 v[18:21], v[120:123], v[180:183], v[18:21]
	v_mfma_f32_16x16x32_bf16 v[6:9], v[96:99], v[188:191], v[6:9]
	v_mfma_f32_16x16x32_bf16 v[2:5], v[120:123], v[188:191], v[2:5]
	v_mfma_f32_16x16x32_bf16 v[56:59], v[132:135], v[156:159], v[48:51]
	v_mfma_f32_16x16x32_bf16 v[40:43], v[108:111], v[168:171], v[40:43]
	v_mfma_f32_16x16x32_bf16 v[36:39], v[132:135], v[168:171], v[36:39]
	v_mfma_f32_16x16x32_bf16 v[22:25], v[108:111], v[184:187], v[22:25]
	v_mfma_f32_16x16x32_bf16 v[18:21], v[132:135], v[184:187], v[18:21]
	v_mfma_f32_16x16x32_bf16 v[6:9], v[108:111], v[192:195], v[6:9]
	v_mfma_f32_16x16x32_bf16 v[2:5], v[132:135], v[192:195], v[2:5]
	s_barrier
	s_cmp_ge_i32 s50, s44
	s_mov_b64 s[16:17], s[18:19]
	s_mov_b32 s20, s50
	s_cbranch_scc0 .LBB0_1266

; #define PG8_STAGE(...) PG8_STAGE_(__VA_ARGS__, 0u)
; #define PG8_WAIT_V(n) asm volatile("s_waitcnt vmcnt(" #n ")" ::: "memory")
; #define PG8_WAIT_L(n) asm volatile("s_waitcnt lgkmcnt(" #n ")" ::: "memory")
; #define PG8_BAR __builtin_amdgcn_s_barrier()
; #define PG8_SCHED __builtin_amdgcn_sched_barrier(0)
; template <class Epi, class Sched, bool ALIGN_EPI = true, bool SP2 = true>
; __device__ __forceinline__ void gemm_phase(LAS unsigned char* lds, const Gemm g, const Sched& S, const Epi& E) {
;     ...
;             PG8_LDB(B0, 0, 0); PG8_LDB(B1, 0, 1); PG8_SCHED; PG8_LDA(At, 0, 0); PG8_STAGE(PG8_SA(1, 1), a1, voffAh);
;             PG8_WAIT_V(8); PG8_WAIT_L(0); PG8_BAR; PG8_MMA(0, 0, At, B0); PG8_MMA(0, 1, At, B1); PG8_BAR; PG8_SCHED;
;             if constexpr (!Epi::HALF_M) PG8_LDA(At, 0, 1); PG8_STAGE(PG8_SB(0, 0), b2, voffB); PG8_STAGE(PG8_SB(0, 1), b2, voffBh); PG8_STAGE(PG8_SA(0, 0), a2, voffA);
;             PG8_WAIT_V(8); PG8_WAIT_L(0); PG8_BAR; if constexpr (!Epi::HALF_M) { PG8_MMA(1, 0, At, B0); PG8_MMA(1, 1, At, B1); } PG8_BAR; PG8_SCHED;
.LBB0_1336:
	v_add_u32_e32 v34, s27, v174
	ds_read_b128 v[148:151], v34
	ds_read_b128 v[152:155], v34 offset:1024
	ds_read_b128 v[156:159], v34 offset:2048
	ds_read_b128 v[160:163], v34 offset:3072
	v_add_u32_e32 v34, s30, v174
	ds_read_b128 v[178:181], v34
	ds_read_b128 v[182:185], v34 offset:1024
	ds_read_b128 v[186:189], v34 offset:2048
	ds_read_b128 v[190:193], v34 offset:3072
	s_add_i32 s64, s18, 2
	s_add_u32 s20, s0, 0x80
	s_addc_u32 s19, s1, 0
	s_cmp_eq_u32 s51, s18
	s_cselect_b32 s18, s59, s20
	s_cselect_b32 s19, s3, s19
	s_cselect_b32 s21, s60, s63
	s_cselect_b32 s20, s61, s62
	v_mov_b32_e32 v34, v166
	ds_read_b128 v[206:209], v176
	ds_read_b128 v[210:213], v176 offset:1024
	ds_read_b128 v[214:217], v176 offset:2048
	ds_read_b128 v[218:221], v176 offset:3072
	ds_read_b128 v[222:225], v176 offset:4096
	ds_read_b128 v[242:245], v176 offset:5120
	ds_read_b128 v[246:249], v176 offset:6144
	ds_read_b128 v[250:253], v176 offset:7168
	s_add_i32 m0, s34, 0xc000
	s_nop 0
	v_mov_b32_e32 v34, v168
	s_add_i32 m0, s34, 0xe000
	s_nop 0
	s_waitcnt vmcnt(6)
	s_waitcnt lgkmcnt(0)
	s_barrier
	s_waitcnt lgkmcnt(0)
	v_mfma_f32_16x16x32_bf16 v[144:147], v[148:151], v[206:209], v[144:147]
	v_mfma_f32_16x16x32_bf16 v[140:143], v[156:159], v[206:209], v[140:143]
	v_mfma_f32_16x16x32_bf16 v[128:131], v[148:151], v[214:217], v[128:131]
	v_mfma_f32_16x16x32_bf16 v[124:127], v[156:159], v[214:217], v[124:127]
	v_mfma_f32_16x16x32_bf16 v[112:115], v[148:151], v[222:225], v[112:115]
	v_mfma_f32_16x16x32_bf16 v[108:111], v[156:159], v[222:225], v[108:111]
	v_mfma_f32_16x16x32_bf16 v[96:99], v[148:151], v[246:249], v[96:99]
	v_mfma_f32_16x16x32_bf16 v[92:95], v[156:159], v[246:249], v[92:95]
	v_mfma_f32_16x16x32_bf16 v[144:147], v[152:155], v[210:213], v[144:147]
	v_mfma_f32_16x16x32_bf16 v[140:143], v[160:163], v[210:213], v[140:143]
	v_mfma_f32_16x16x32_bf16 v[128:131], v[152:155], v[218:221], v[128:131]
	v_mfma_f32_16x16x32_bf16 v[124:127], v[160:163], v[218:221], v[124:127]
	v_mfma_f32_16x16x32_bf16 v[112:115], v[152:155], v[242:245], v[112:115]
	v_mfma_f32_16x16x32_bf16 v[108:111], v[160:163], v[242:245], v[108:111]
	v_mfma_f32_16x16x32_bf16 v[96:99], v[152:155], v[250:253], v[96:99]
	v_mfma_f32_16x16x32_bf16 v[92:95], v[160:163], v[250:253], v[92:95]
	v_mfma_f32_16x16x32_bf16 v[136:139], v[178:181], v[206:209], v[136:139]
	v_mfma_f32_16x16x32_bf16 v[132:135], v[186:189], v[206:209], v[132:135]
	v_mfma_f32_16x16x32_bf16 v[120:123], v[178:181], v[214:217], v[120:123]
	v_mfma_f32_16x16x32_bf16 v[116:119], v[186:189], v[214:217], v[116:119]
	v_mfma_f32_16x16x32_bf16 v[104:107], v[178:181], v[222:225], v[104:107]
	v_mfma_f32_16x16x32_bf16 v[100:103], v[186:189], v[222:225], v[100:103]
	v_mfma_f32_16x16x32_bf16 v[88:91], v[178:181], v[246:249], v[88:91]
	v_mfma_f32_16x16x32_bf16 v[84:87], v[186:189], v[246:249], v[84:87]
	v_mfma_f32_16x16x32_bf16 v[136:139], v[182:185], v[210:213], v[136:139]
	v_mfma_f32_16x16x32_bf16 v[132:135], v[190:193], v[210:213], v[132:135]
	v_mfma_f32_16x16x32_bf16 v[120:123], v[182:185], v[218:221], v[120:123]
	v_mfma_f32_16x16x32_bf16 v[116:119], v[190:193], v[218:221], v[116:119]
	v_mfma_f32_16x16x32_bf16 v[104:107], v[182:185], v[242:245], v[104:107]
	v_mfma_f32_16x16x32_bf16 v[100:103], v[190:193], v[242:245], v[100:103]
	v_mfma_f32_16x16x32_bf16 v[88:91], v[182:185], v[250:253], v[88:91]
	v_mfma_f32_16x16x32_bf16 v[84:87], v[190:193], v[250:253], v[84:87]
	s_barrier
	v_mov_b32_e32 v34, v167
	s_mov_b32 m0, s28
	s_nop 0
	global_load_lds_dwordx4 v34, s[20:21]
	v_mov_b32_e32 v34, v169
	s_mov_b32 m0, s29
	s_nop 0
	global_load_lds_dwordx4 v34, s[20:21]
	v_mov_b32_e32 v34, v170
	s_mov_b32 m0, s31
	s_nop 0
	global_load_lds_dwordx4 v34, s[20:21]
	v_mov_b32_e32 v34, v171
	s_mov_b32 m0, s33
	s_nop 0
	global_load_lds_dwordx4 v34, s[20:21]
	v_mov_b32_e32 v34, v166
	s_mov_b32 m0, s34
	s_nop 0
	global_load_lds_dwordx4 v34, s[18:19]
	v_mov_b32_e32 v34, v168
	s_mov_b32 m0, s35
	s_nop 0
	global_load_lds_dwordx4 v34, s[18:19]
	s_waitcnt vmcnt(6)
	s_waitcnt lgkmcnt(0)
	s_barrier
	s_barrier
; #define PG8_STAGE(...) PG8_STAGE_(__VA_ARGS__, 0u)
; #define PG8_WAIT_V(n) asm volatile("s_waitcnt vmcnt(" #n ")" ::: "memory")
; #define PG8_WAIT_L(n) asm volatile("s_waitcnt lgkmcnt(" #n ")" ::: "memory")
; #define PG8_BAR __builtin_amdgcn_s_barrier()
; #define PG8_SCHED __builtin_amdgcn_sched_barrier(0)
; template <class Epi, class Sched, bool ALIGN_EPI = true, bool SP2 = true>
; __device__ __forceinline__ void gemm_phase(LAS unsigned char* lds, const Gemm g, const Sched& S, const Epi& E) {
;     ...
;             PG8_LDB(B0, 1, 0); PG8_LDB(B1, 1, 1); PG8_SCHED; PG8_LDA(At, 1, 0); PG8_STAGE(PG8_SA(0, 1), a2, voffAh);
;             PG8_WAIT_V(8); PG8_WAIT_L(0); PG8_BAR; PG8_MMA(0, 0, At, B0); PG8_MMA(0, 1, At, B1); PG8_BAR; PG8_SCHED;
;             if constexpr (!Epi::HALF_M) PG8_LDA(At, 1, 1); PG8_STAGE(PG8_SB(1, 0), b3, voffB); PG8_STAGE(PG8_SB(1, 1), b3, voffBh); PG8_STAGE(PG8_SA(1, 0), a3, voffA);
;             PG8_WAIT_V(8); PG8_WAIT_L(0); PG8_BAR; if constexpr (!Epi::HALF_M) { PG8_MMA(1, 0, At, B0); PG8_MMA(1, 1, At, B1); } PG8_BAR; PG8_SCHED;
	v_add_u32_e32 v34, s41, v174
	ds_read_b128 v[148:151], v34
	ds_read_b128 v[152:155], v34 offset:1024
	ds_read_b128 v[156:159], v34 offset:2048
	ds_read_b128 v[160:163], v34 offset:3072
	v_add_u32_e32 v34, s46, v174
	ds_read_b128 v[178:181], v34
	ds_read_b128 v[182:185], v34 offset:1024
	ds_read_b128 v[186:189], v34 offset:2048
	ds_read_b128 v[190:193], v34 offset:3072
	v_mov_b32_e32 v34, v166
	s_mov_b32 m0, s36
	ds_read_b128 v[206:209], v176 offset:32768
	ds_read_b128 v[210:213], v176 offset:33792
	ds_read_b128 v[214:217], v176 offset:34816
	ds_read_b128 v[218:221], v176 offset:35840
	ds_read_b128 v[222:225], v176 offset:36864
	ds_read_b128 v[242:245], v176 offset:37888
	ds_read_b128 v[246:249], v176 offset:38912
	ds_read_b128 v[250:253], v176 offset:39936
	s_nop 0
	v_mov_b32_e32 v34, v168
	s_mov_b32 m0, s37
	s_nop 0
	s_waitcnt vmcnt(6)
	s_waitcnt lgkmcnt(0)
	s_barrier
	s_waitcnt lgkmcnt(0)
	v_mfma_f32_16x16x32_bf16 v[144:147], v[148:151], v[206:209], v[144:147]
	v_mfma_f32_16x16x32_bf16 v[140:143], v[156:159], v[206:209], v[140:143]
	v_mfma_f32_16x16x32_bf16 v[128:131], v[148:151], v[214:217], v[128:131]
	v_mfma_f32_16x16x32_bf16 v[124:127], v[156:159], v[214:217], v[124:127]
	v_mfma_f32_16x16x32_bf16 v[112:115], v[148:151], v[222:225], v[112:115]
	v_mfma_f32_16x16x32_bf16 v[108:111], v[156:159], v[222:225], v[108:111]
	v_mfma_f32_16x16x32_bf16 v[96:99], v[148:151], v[246:249], v[96:99]
	v_mfma_f32_16x16x32_bf16 v[92:95], v[156:159], v[246:249], v[92:95]
	v_mfma_f32_16x16x32_bf16 v[144:147], v[152:155], v[210:213], v[144:147]
	v_mfma_f32_16x16x32_bf16 v[140:143], v[160:163], v[210:213], v[140:143]
	v_mfma_f32_16x16x32_bf16 v[128:131], v[152:155], v[218:221], v[128:131]
	v_mfma_f32_16x16x32_bf16 v[124:127], v[160:163], v[218:221], v[124:127]
	v_mfma_f32_16x16x32_bf16 v[112:115], v[152:155], v[242:245], v[112:115]
	v_mfma_f32_16x16x32_bf16 v[108:111], v[160:163], v[242:245], v[108:111]
	v_mfma_f32_16x16x32_bf16 v[96:99], v[152:155], v[250:253], v[96:99]
	v_mfma_f32_16x16x32_bf16 v[92:95], v[160:163], v[250:253], v[92:95]
	v_mfma_f32_16x16x32_bf16 v[136:139], v[178:181], v[206:209], v[136:139]
	v_mfma_f32_16x16x32_bf16 v[132:135], v[186:189], v[206:209], v[132:135]
	v_mfma_f32_16x16x32_bf16 v[120:123], v[178:181], v[214:217], v[120:123]
	v_mfma_f32_16x16x32_bf16 v[116:119], v[186:189], v[214:217], v[116:119]
	v_mfma_f32_16x16x32_bf16 v[104:107], v[178:181], v[222:225], v[104:107]
	v_mfma_f32_16x16x32_bf16 v[100:103], v[186:189], v[222:225], v[100:103]
	v_mfma_f32_16x16x32_bf16 v[88:91], v[178:181], v[246:249], v[88:91]
	v_mfma_f32_16x16x32_bf16 v[84:87], v[186:189], v[246:249], v[84:87]
	v_mfma_f32_16x16x32_bf16 v[136:139], v[182:185], v[210:213], v[136:139]
	v_mfma_f32_16x16x32_bf16 v[132:135], v[190:193], v[210:213], v[132:135]
	v_mfma_f32_16x16x32_bf16 v[120:123], v[182:185], v[218:221], v[120:123]
	v_mfma_f32_16x16x32_bf16 v[116:119], v[190:193], v[218:221], v[116:119]
	v_mfma_f32_16x16x32_bf16 v[104:107], v[182:185], v[242:245], v[104:107]
	v_mfma_f32_16x16x32_bf16 v[100:103], v[190:193], v[242:245], v[100:103]
	v_mfma_f32_16x16x32_bf16 v[88:91], v[182:185], v[250:253], v[88:91]
	v_mfma_f32_16x16x32_bf16 v[84:87], v[190:193], v[250:253], v[84:87]
	s_barrier
	v_mov_b32_e32 v34, v167
	s_mov_b32 m0, s42
	v_lshl_add_u64 v[148:149], s[20:21], 0, v[34:35]
	v_lshl_add_u64 v[148:149], v[148:149], 0, s[80:81]
	v_mov_b32_e32 v34, v169
	global_load_lds_dwordx4 v[148:149], off
	s_mov_b32 m0, s43
	v_lshl_add_u64 v[148:149], s[20:21], 0, v[34:35]
	v_lshl_add_u64 v[148:149], v[148:149], 0, s[80:81]
	v_mov_b32_e32 v34, v170
	global_load_lds_dwordx4 v[148:149], off
	s_mov_b32 m0, s47
	v_lshl_add_u64 v[148:149], s[20:21], 0, v[34:35]
	v_lshl_add_u64 v[148:149], v[148:149], 0, s[80:81]
	v_mov_b32_e32 v34, v171
	global_load_lds_dwordx4 v[148:149], off
	s_mov_b32 m0, s48
	v_lshl_add_u64 v[148:149], s[20:21], 0, v[34:35]
	v_lshl_add_u64 v[148:149], v[148:149], 0, s[80:81]
	v_mov_b32_e32 v34, v166
	global_load_lds_dwordx4 v[148:149], off
	s_mov_b32 m0, s44
	v_lshl_add_u64 v[148:149], s[18:19], 0, v[34:35]
	v_lshl_add_u64 v[148:149], v[148:149], 0, s[80:81]
	v_mov_b32_e32 v34, v168
	global_load_lds_dwordx4 v[148:149], off
	s_mov_b32 m0, s45
	v_lshl_add_u64 v[148:149], s[18:19], 0, v[34:35]
	v_lshl_add_u64 v[148:149], v[148:149], 0, s[80:81]
	global_load_lds_dwordx4 v[148:149], off
	s_waitcnt vmcnt(6)
	s_waitcnt lgkmcnt(0)
	s_barrier
	s_barrier
	s_add_u32 s0, s0, 0x100
	s_addc_u32 s1, s1, 0
	s_add_u32 s62, s62, 0x100
	s_addc_u32 s63, s63, 0
	s_cmp_ge_i32 s64, s49
	s_mov_b32 s18, s64
	s_cbranch_scc0 .LBB0_1336

; #define PG8_STAGE(...) PG8_STAGE_(__VA_ARGS__, 0u)
; #define PG8_WAIT_V(n) asm volatile("s_waitcnt vmcnt(" #n ")" ::: "memory")
; #define PG8_WAIT_L(n) asm volatile("s_waitcnt lgkmcnt(" #n ")" ::: "memory")
; #define PG8_BAR __builtin_amdgcn_s_barrier()
; #define PG8_SCHED __builtin_amdgcn_sched_barrier(0)
; template <class Epi, class Sched, bool ALIGN_EPI = true, bool SP2 = true>
; __device__ __forceinline__ void gemm_phase(LAS unsigned char* lds, const Gemm g, const Sched& S, const Epi& E) {
;     ...
;         const char* nA = has_next ? (const char*)g.A + (size_t)nxt.pm * tstepA + (size_t)nxt.ak * ESZ : cA; const char* nB = has_next ? (const char*)g.Bt + (size_t)nxt.pn * tstepB : cB;
;         for (int t = 0; t < nt; t += 2) {
;             const bool last = (t == nt - 2);
;             const char* a1 = cA + (size_t)(t + 1) * kstep;
;             const char* a2 = last ? nA : cA + (size_t)(t + 2) * kstep; const char* b2 = last ? nB : cB + (size_t)(t + 2) * kstep;
;             const char* a3 = a2 + kstep; const char* b3 = b2 + kstep;
;             if constexpr (SP2) {
;             PG8_LDB(B0, 0, 0); PG8_LDB(B1, 0, 1); PG8_SCHED; PG8_LDA(At, 0, 0); PG8_STAGE(PG8_SA(1, 1), a1, voffAh);
;             PG8_WAIT_V(8); PG8_WAIT_L(0); PG8_BAR; PG8_MMA(0, 0, At, B0); PG8_MMA(0, 1, At, B1); PG8_BAR; PG8_SCHED;
;             if constexpr (!Epi::HALF_M) PG8_LDA(At, 0, 1); PG8_STAGE(PG8_SB(0, 0), b2, voffB); PG8_STAGE(PG8_SB(0, 1), b2, voffBh); PG8_STAGE(PG8_SA(0, 0), a2, voffA);
;             PG8_WAIT_V(8); PG8_WAIT_L(0); PG8_BAR; if constexpr (!Epi::HALF_M) { PG8_MMA(1, 0, At, B0); PG8_MMA(1, 1, At, B1); } PG8_BAR; PG8_SCHED;
.LBB0_1435:
	v_add_u32_e32 v34, s41, v142
	ds_read_b128 v[144:147], v34
	ds_read_b128 v[148:151], v34 offset:1024
	ds_read_b128 v[152:155], v34 offset:2048
	ds_read_b128 v[156:159], v34 offset:3072
	v_add_u32_e32 v34, s44, v142
	ds_read_b128 v[160:163], v34
	ds_read_b128 v[164:167], v34 offset:1024
	ds_read_b128 v[168:171], v34 offset:2048
	ds_read_b128 v[172:175], v34 offset:3072
	s_add_i32 s69, s28, 2
	s_add_u32 s30, s26, 0x80
	s_addc_u32 s29, s27, 0
	s_cmp_eq_u32 s62, s28
	s_cselect_b32 s28, s21, s30
	s_cselect_b32 s29, s19, s29
	s_cselect_b32 s31, s65, s68
	s_cselect_b32 s30, s66, s67
	v_mov_b32_e32 v34, v138
	ds_read_b128 v[176:179], v143
	ds_read_b128 v[180:183], v143 offset:1024
	ds_read_b128 v[184:187], v143 offset:2048
	ds_read_b128 v[188:191], v143 offset:3072
	ds_read_b128 v[192:195], v143 offset:4096
	ds_read_b128 v[206:209], v143 offset:5120
	ds_read_b128 v[210:213], v143 offset:6144
	ds_read_b128 v[214:217], v143 offset:7168
	s_add_i32 m0, s47, 0xc000
	s_nop 0
	global_load_lds_dwordx4 v34, s[26:27]
	v_mov_b32_e32 v34, v139
	s_add_i32 m0, s47, 0xe000
	s_nop 0
	global_load_lds_dwordx4 v34, s[26:27]
	s_waitcnt vmcnt(8)
	s_waitcnt lgkmcnt(0)
	s_barrier
	s_waitcnt lgkmcnt(0)
	v_mfma_f32_16x16x32_bf16 v[30:33], v[144:147], v[176:179], v[30:33]
	v_mfma_f32_16x16x32_bf16 v[48:51], v[152:155], v[176:179], v[48:51]
	v_mfma_f32_16x16x32_bf16 v[68:71], v[144:147], v[184:187], v[68:71]
	v_mfma_f32_16x16x32_bf16 v[72:75], v[152:155], v[184:187], v[72:75]
	v_mfma_f32_16x16x32_bf16 v[80:83], v[144:147], v[192:195], v[80:83]
	v_mfma_f32_16x16x32_bf16 v[76:79], v[152:155], v[192:195], v[76:79]
	v_mfma_f32_16x16x32_bf16 v[96:99], v[144:147], v[210:213], v[96:99]
	v_mfma_f32_16x16x32_bf16 v[92:95], v[152:155], v[210:213], v[92:95]
	v_mfma_f32_16x16x32_bf16 v[30:33], v[148:151], v[180:183], v[30:33]
	v_mfma_f32_16x16x32_bf16 v[48:51], v[156:159], v[180:183], v[48:51]
	v_mfma_f32_16x16x32_bf16 v[68:71], v[148:151], v[188:191], v[68:71]
	v_mfma_f32_16x16x32_bf16 v[72:75], v[156:159], v[188:191], v[72:75]
	v_mfma_f32_16x16x32_bf16 v[80:83], v[148:151], v[206:209], v[80:83]
	v_mfma_f32_16x16x32_bf16 v[76:79], v[156:159], v[206:209], v[76:79]
	v_mfma_f32_16x16x32_bf16 v[96:99], v[148:151], v[214:217], v[96:99]
	v_mfma_f32_16x16x32_bf16 v[92:95], v[156:159], v[214:217], v[92:95]
	v_mfma_f32_16x16x32_bf16 v[6:9], v[160:163], v[176:179], v[6:9]
	v_mfma_f32_16x16x32_bf16 v[2:5], v[168:171], v[176:179], v[2:5]
	v_mfma_f32_16x16x32_bf16 v[14:17], v[160:163], v[184:187], v[14:17]
	v_mfma_f32_16x16x32_bf16 v[10:13], v[168:171], v[184:187], v[10:13]
	v_mfma_f32_16x16x32_bf16 v[22:25], v[160:163], v[192:195], v[22:25]
	v_mfma_f32_16x16x32_bf16 v[18:21], v[168:171], v[192:195], v[18:21]
	v_mfma_f32_16x16x32_bf16 v[132:135], v[160:163], v[210:213], v[132:135]
	v_mfma_f32_16x16x32_bf16 v[26:29], v[168:171], v[210:213], v[26:29]
	v_mfma_f32_16x16x32_bf16 v[6:9], v[164:167], v[180:183], v[6:9]
	v_mfma_f32_16x16x32_bf16 v[2:5], v[172:175], v[180:183], v[2:5]
	v_mfma_f32_16x16x32_bf16 v[14:17], v[164:167], v[188:191], v[14:17]
	v_mfma_f32_16x16x32_bf16 v[10:13], v[172:175], v[188:191], v[10:13]
	v_mfma_f32_16x16x32_bf16 v[22:25], v[164:167], v[206:209], v[22:25]
	v_mfma_f32_16x16x32_bf16 v[18:21], v[172:175], v[206:209], v[18:21]
	v_mfma_f32_16x16x32_bf16 v[132:135], v[164:167], v[214:217], v[132:135]
	v_mfma_f32_16x16x32_bf16 v[26:29], v[172:175], v[214:217], v[26:29]
	s_barrier
	v_mov_b32_e32 v34, v45
	s_mov_b32 m0, s42
	ds_read_b128 v[176:179], v143 offset:16384
	ds_read_b128 v[180:183], v143 offset:17408
	ds_read_b128 v[184:187], v143 offset:18432
	ds_read_b128 v[188:191], v143 offset:19456
	ds_read_b128 v[192:195], v143 offset:20480
	ds_read_b128 v[206:209], v143 offset:21504
	ds_read_b128 v[210:213], v143 offset:22528
	ds_read_b128 v[214:217], v143 offset:23552
	s_nop 0
	global_load_lds_dwordx4 v34, s[30:31]
	v_mov_b32_e32 v34, v47
	s_mov_b32 m0, s43
	s_nop 0
	global_load_lds_dwordx4 v34, s[30:31]
	v_mov_b32_e32 v34, v136
	s_mov_b32 m0, s45
	s_nop 0
	global_load_lds_dwordx4 v34, s[30:31]
	v_mov_b32_e32 v34, v137
	s_mov_b32 m0, s46
	s_nop 0
	global_load_lds_dwordx4 v34, s[30:31]
	v_mov_b32_e32 v34, v44
	s_mov_b32 m0, s47
	s_nop 0
	global_load_lds_dwordx4 v34, s[28:29]
	v_mov_b32_e32 v34, v46
	s_mov_b32 m0, s48
	s_nop 0
	global_load_lds_dwordx4 v34, s[28:29]
	s_waitcnt vmcnt(8)
	s_waitcnt lgkmcnt(0)
	s_barrier
	s_waitcnt lgkmcnt(0)
	v_mfma_f32_16x16x32_bf16 v[104:107], v[144:147], v[176:179], v[104:107]
	v_mfma_f32_16x16x32_bf16 v[100:103], v[152:155], v[176:179], v[100:103]
	v_mfma_f32_16x16x32_bf16 v[112:115], v[144:147], v[184:187], v[112:115]
	v_mfma_f32_16x16x32_bf16 v[108:111], v[152:155], v[184:187], v[108:111]
	v_mfma_f32_16x16x32_bf16 v[124:127], v[144:147], v[192:195], v[124:127]
	v_mfma_f32_16x16x32_bf16 v[116:119], v[152:155], v[192:195], v[116:119]
	v_mfma_f32_16x16x32_bf16 v[128:131], v[144:147], v[210:213], v[128:131]
	v_mfma_f32_16x16x32_bf16 v[120:123], v[152:155], v[210:213], v[120:123]
	v_mfma_f32_16x16x32_bf16 v[104:107], v[148:151], v[180:183], v[104:107]
	v_mfma_f32_16x16x32_bf16 v[100:103], v[156:159], v[180:183], v[100:103]
	v_mfma_f32_16x16x32_bf16 v[112:115], v[148:151], v[188:191], v[112:115]
	v_mfma_f32_16x16x32_bf16 v[108:111], v[156:159], v[188:191], v[108:111]
	v_mfma_f32_16x16x32_bf16 v[124:127], v[148:151], v[206:209], v[124:127]
	v_mfma_f32_16x16x32_bf16 v[116:119], v[156:159], v[206:209], v[116:119]
	v_mfma_f32_16x16x32_bf16 v[128:131], v[148:151], v[214:217], v[128:131]
	v_mfma_f32_16x16x32_bf16 v[120:123], v[156:159], v[214:217], v[120:123]
	v_mfma_f32_16x16x32_bf16 v[40:43], v[160:163], v[176:179], v[40:43]
	v_mfma_f32_16x16x32_bf16 v[36:39], v[168:171], v[176:179], v[36:39]
	v_mfma_f32_16x16x32_bf16 v[56:59], v[160:163], v[184:187], v[56:59]
	v_mfma_f32_16x16x32_bf16 v[52:55], v[168:171], v[184:187], v[52:55]
	v_mfma_f32_16x16x32_bf16 v[88:91], v[160:163], v[192:195], v[88:91]
	v_mfma_f32_16x16x32_bf16 v[84:87], v[168:171], v[192:195], v[84:87]
	v_mfma_f32_16x16x32_bf16 v[64:67], v[160:163], v[210:213], v[64:67]
	v_mfma_f32_16x16x32_bf16 v[60:63], v[168:171], v[210:213], v[60:63]
	v_mfma_f32_16x16x32_bf16 v[40:43], v[164:167], v[180:183], v[40:43]
	v_mfma_f32_16x16x32_bf16 v[36:39], v[172:175], v[180:183], v[36:39]
	v_mfma_f32_16x16x32_bf16 v[56:59], v[164:167], v[188:191], v[56:59]
	v_mfma_f32_16x16x32_bf16 v[52:55], v[172:175], v[188:191], v[52:55]
	v_mfma_f32_16x16x32_bf16 v[88:91], v[164:167], v[206:209], v[88:91]
	v_mfma_f32_16x16x32_bf16 v[84:87], v[172:175], v[206:209], v[84:87]
	v_mfma_f32_16x16x32_bf16 v[64:67], v[164:167], v[214:217], v[64:67]
	v_mfma_f32_16x16x32_bf16 v[60:63], v[172:175], v[214:217], v[60:63]
	s_barrier
; #define PG8_STAGE(...) PG8_STAGE_(__VA_ARGS__, 0u)
; #define PG8_WAIT_V(n) asm volatile("s_waitcnt vmcnt(" #n ")" ::: "memory")
; #define PG8_WAIT_L(n) asm volatile("s_waitcnt lgkmcnt(" #n ")" ::: "memory")
; #define PG8_BAR __builtin_amdgcn_s_barrier()
; #define PG8_SCHED __builtin_amdgcn_sched_barrier(0)
; template <class Epi, class Sched, bool ALIGN_EPI = true, bool SP2 = true>
; __device__ __forceinline__ void gemm_phase(LAS unsigned char* lds, const Gemm g, const Sched& S, const Epi& E) {
;     ...
;             PG8_LDB(B0, 1, 0); PG8_LDB(B1, 1, 1); PG8_SCHED; PG8_LDA(At, 1, 0); PG8_STAGE(PG8_SA(0, 1), a2, voffAh);
;             PG8_WAIT_V(8); PG8_WAIT_L(0); PG8_BAR; PG8_MMA(0, 0, At, B0); PG8_MMA(0, 1, At, B1); PG8_BAR; PG8_SCHED;
	v_add_u32_e32 v34, s51, v142
	ds_read_b128 v[144:147], v34
	ds_read_b128 v[148:151], v34 offset:1024
	ds_read_b128 v[152:155], v34 offset:2048
	ds_read_b128 v[156:159], v34 offset:3072
	v_add_u32_e32 v34, s57, v142
	ds_read_b128 v[160:163], v34
	ds_read_b128 v[164:167], v34 offset:1024
	ds_read_b128 v[168:171], v34 offset:2048
	ds_read_b128 v[172:175], v34 offset:3072
	v_mov_b32_e32 v34, v138
	s_mov_b32 m0, s49
	ds_read_b128 v[176:179], v143 offset:32768
	ds_read_b128 v[180:183], v143 offset:33792
	ds_read_b128 v[184:187], v143 offset:34816
	ds_read_b128 v[188:191], v143 offset:35840
	ds_read_b128 v[192:195], v143 offset:36864
	ds_read_b128 v[206:209], v143 offset:37888
	ds_read_b128 v[210:213], v143 offset:38912
	ds_read_b128 v[214:217], v143 offset:39936
	s_nop 0
	global_load_lds_dwordx4 v34, s[28:29]
	v_mov_b32_e32 v34, v139
	s_mov_b32 m0, s50
	s_nop 0
	global_load_lds_dwordx4 v34, s[28:29]
	s_waitcnt vmcnt(8)
	s_waitcnt lgkmcnt(0)
	s_barrier
	s_waitcnt lgkmcnt(0)
	v_mfma_f32_16x16x32_bf16 v[30:33], v[144:147], v[176:179], v[30:33]
	v_mfma_f32_16x16x32_bf16 v[48:51], v[152:155], v[176:179], v[48:51]
	v_mfma_f32_16x16x32_bf16 v[68:71], v[144:147], v[184:187], v[68:71]
	v_mfma_f32_16x16x32_bf16 v[72:75], v[152:155], v[184:187], v[72:75]
	v_mfma_f32_16x16x32_bf16 v[80:83], v[144:147], v[192:195], v[80:83]
	v_mfma_f32_16x16x32_bf16 v[76:79], v[152:155], v[192:195], v[76:79]
	v_mfma_f32_16x16x32_bf16 v[96:99], v[144:147], v[210:213], v[96:99]
	v_mfma_f32_16x16x32_bf16 v[92:95], v[152:155], v[210:213], v[92:95]
	v_mfma_f32_16x16x32_bf16 v[30:33], v[148:151], v[180:183], v[30:33]
	v_mfma_f32_16x16x32_bf16 v[48:51], v[156:159], v[180:183], v[48:51]
	v_mfma_f32_16x16x32_bf16 v[68:71], v[148:151], v[188:191], v[68:71]
	v_mfma_f32_16x16x32_bf16 v[72:75], v[156:159], v[188:191], v[72:75]
	v_mfma_f32_16x16x32_bf16 v[80:83], v[148:151], v[206:209], v[80:83]
	v_mfma_f32_16x16x32_bf16 v[76:79], v[156:159], v[206:209], v[76:79]
	v_mfma_f32_16x16x32_bf16 v[96:99], v[148:151], v[214:217], v[96:99]
	v_mfma_f32_16x16x32_bf16 v[92:95], v[156:159], v[214:217], v[92:95]
	v_mfma_f32_16x16x32_bf16 v[6:9], v[160:163], v[176:179], v[6:9]
	v_mfma_f32_16x16x32_bf16 v[2:5], v[168:171], v[176:179], v[2:5]
	v_mfma_f32_16x16x32_bf16 v[14:17], v[160:163], v[184:187], v[14:17]
	v_mfma_f32_16x16x32_bf16 v[10:13], v[168:171], v[184:187], v[10:13]
	v_mfma_f32_16x16x32_bf16 v[22:25], v[160:163], v[192:195], v[22:25]
	v_mfma_f32_16x16x32_bf16 v[18:21], v[168:171], v[192:195], v[18:21]
	v_mfma_f32_16x16x32_bf16 v[132:135], v[160:163], v[210:213], v[132:135]
	v_mfma_f32_16x16x32_bf16 v[26:29], v[168:171], v[210:213], v[26:29]
	v_mfma_f32_16x16x32_bf16 v[6:9], v[164:167], v[180:183], v[6:9]
	v_mfma_f32_16x16x32_bf16 v[2:5], v[172:175], v[180:183], v[2:5]
	v_mfma_f32_16x16x32_bf16 v[14:17], v[164:167], v[188:191], v[14:17]
	v_mfma_f32_16x16x32_bf16 v[10:13], v[172:175], v[188:191], v[10:13]
	v_mfma_f32_16x16x32_bf16 v[22:25], v[164:167], v[206:209], v[22:25]
	v_mfma_f32_16x16x32_bf16 v[18:21], v[172:175], v[206:209], v[18:21]
	v_mfma_f32_16x16x32_bf16 v[132:135], v[164:167], v[214:217], v[132:135]
	v_mfma_f32_16x16x32_bf16 v[26:29], v[172:175], v[214:217], v[26:29]
	s_barrier
; #define PG8_STAGE(...) PG8_STAGE_(__VA_ARGS__, 0u)
; #define PG8_WAIT_V(n) asm volatile("s_waitcnt vmcnt(" #n ")" ::: "memory")
; #define PG8_WAIT_L(n) asm volatile("s_waitcnt lgkmcnt(" #n ")" ::: "memory")
; #define PG8_BAR __builtin_amdgcn_s_barrier()
; #define PG8_SCHED __builtin_amdgcn_sched_barrier(0)
; template <class Epi, class Sched, bool ALIGN_EPI = true, bool SP2 = true>
; __device__ __forceinline__ void gemm_phase(LAS unsigned char* lds, const Gemm g, const Sched& S, const Epi& E) {
;     ...
;             if constexpr (!Epi::HALF_M) PG8_LDA(At, 1, 1); PG8_STAGE(PG8_SB(1, 0), b3, voffB); PG8_STAGE(PG8_SB(1, 1), b3, voffBh); PG8_STAGE(PG8_SA(1, 0), a3, voffA);
;             PG8_WAIT_V(8); PG8_WAIT_L(0); PG8_BAR; if constexpr (!Epi::HALF_M) { PG8_MMA(1, 0, At, B0); PG8_MMA(1, 1, At, B1); } PG8_BAR; PG8_SCHED;
	v_mov_b32_e32 v34, v45
	ds_read_b128 v[176:179], v143 offset:49152
	ds_read_b128 v[180:183], v143 offset:50176
	ds_read_b128 v[184:187], v143 offset:51200
	ds_read_b128 v[188:191], v143 offset:52224
	ds_read_b128 v[192:195], v143 offset:53248
	ds_read_b128 v[206:209], v143 offset:54272
	ds_read_b128 v[210:213], v143 offset:55296
	ds_read_b128 v[214:217], v143 offset:56320
	s_mov_b32 m0, s52
	v_lshl_add_u64 v[218:219], s[30:31], 0, v[34:35]
	v_lshl_add_u64 v[218:219], v[218:219], 0, s[80:81]
	v_mov_b32_e32 v34, v47
	global_load_lds_dwordx4 v[218:219], off
	s_mov_b32 m0, s53
	v_lshl_add_u64 v[218:219], s[30:31], 0, v[34:35]
	v_lshl_add_u64 v[218:219], v[218:219], 0, s[80:81]
	v_mov_b32_e32 v34, v136
	global_load_lds_dwordx4 v[218:219], off
	s_mov_b32 m0, s58
	v_lshl_add_u64 v[218:219], s[30:31], 0, v[34:35]
	v_lshl_add_u64 v[218:219], v[218:219], 0, s[80:81]
	v_mov_b32_e32 v34, v137
	global_load_lds_dwordx4 v[218:219], off
	s_mov_b32 m0, s59
	v_lshl_add_u64 v[218:219], s[30:31], 0, v[34:35]
	v_lshl_add_u64 v[218:219], v[218:219], 0, s[80:81]
	v_mov_b32_e32 v34, v44
	global_load_lds_dwordx4 v[218:219], off
	s_mov_b32 m0, s54
	v_lshl_add_u64 v[218:219], s[28:29], 0, v[34:35]
	v_lshl_add_u64 v[218:219], v[218:219], 0, s[80:81]
	v_mov_b32_e32 v34, v46
	global_load_lds_dwordx4 v[218:219], off
	s_mov_b32 m0, s56
	v_lshl_add_u64 v[218:219], s[28:29], 0, v[34:35]
	v_lshl_add_u64 v[218:219], v[218:219], 0, s[80:81]
	global_load_lds_dwordx4 v[218:219], off
	s_waitcnt vmcnt(8)
	s_waitcnt lgkmcnt(0)
	s_barrier
	s_waitcnt lgkmcnt(0)
	v_mfma_f32_16x16x32_bf16 v[104:107], v[144:147], v[176:179], v[104:107]
	v_mfma_f32_16x16x32_bf16 v[100:103], v[152:155], v[176:179], v[100:103]
	v_mfma_f32_16x16x32_bf16 v[112:115], v[144:147], v[184:187], v[112:115]
	v_mfma_f32_16x16x32_bf16 v[108:111], v[152:155], v[184:187], v[108:111]
	v_mfma_f32_16x16x32_bf16 v[124:127], v[144:147], v[192:195], v[124:127]
	v_mfma_f32_16x16x32_bf16 v[116:119], v[152:155], v[192:195], v[116:119]
	v_mfma_f32_16x16x32_bf16 v[128:131], v[144:147], v[210:213], v[128:131]
	v_mfma_f32_16x16x32_bf16 v[120:123], v[152:155], v[210:213], v[120:123]
	v_mfma_f32_16x16x32_bf16 v[104:107], v[148:151], v[180:183], v[104:107]
	v_mfma_f32_16x16x32_bf16 v[100:103], v[156:159], v[180:183], v[100:103]
	v_mfma_f32_16x16x32_bf16 v[112:115], v[148:151], v[188:191], v[112:115]
	v_mfma_f32_16x16x32_bf16 v[108:111], v[156:159], v[188:191], v[108:111]
	v_mfma_f32_16x16x32_bf16 v[124:127], v[148:151], v[206:209], v[124:127]
	v_mfma_f32_16x16x32_bf16 v[116:119], v[156:159], v[206:209], v[116:119]
	v_mfma_f32_16x16x32_bf16 v[128:131], v[148:151], v[214:217], v[128:131]
	v_mfma_f32_16x16x32_bf16 v[120:123], v[156:159], v[214:217], v[120:123]
	v_mfma_f32_16x16x32_bf16 v[40:43], v[160:163], v[176:179], v[40:43]
	v_mfma_f32_16x16x32_bf16 v[36:39], v[168:171], v[176:179], v[36:39]
	v_mfma_f32_16x16x32_bf16 v[56:59], v[160:163], v[184:187], v[56:59]
	v_mfma_f32_16x16x32_bf16 v[52:55], v[168:171], v[184:187], v[52:55]
	v_mfma_f32_16x16x32_bf16 v[88:91], v[160:163], v[192:195], v[88:91]
	v_mfma_f32_16x16x32_bf16 v[84:87], v[168:171], v[192:195], v[84:87]
	v_mfma_f32_16x16x32_bf16 v[64:67], v[160:163], v[210:213], v[64:67]
	v_mfma_f32_16x16x32_bf16 v[60:63], v[168:171], v[210:213], v[60:63]
	v_mfma_f32_16x16x32_bf16 v[40:43], v[164:167], v[180:183], v[40:43]
	v_mfma_f32_16x16x32_bf16 v[36:39], v[172:175], v[180:183], v[36:39]
	v_mfma_f32_16x16x32_bf16 v[56:59], v[164:167], v[188:191], v[56:59]
	v_mfma_f32_16x16x32_bf16 v[52:55], v[172:175], v[188:191], v[52:55]
	v_mfma_f32_16x16x32_bf16 v[88:91], v[164:167], v[206:209], v[88:91]
	v_mfma_f32_16x16x32_bf16 v[84:87], v[172:175], v[206:209], v[84:87]
	v_mfma_f32_16x16x32_bf16 v[64:67], v[164:167], v[214:217], v[64:67]
	v_mfma_f32_16x16x32_bf16 v[60:63], v[172:175], v[214:217], v[60:63]
	s_barrier
	s_add_u32 s26, s26, 0x100
	s_addc_u32 s27, s27, 0
	s_add_u32 s67, s67, 0x100
	s_addc_u32 s68, s68, 0
	s_cmp_ge_i32 s69, s61
	s_mov_b32 s28, s69
	s_cbranch_scc0 .LBB0_1435
	s_mov_b32 s68, 0x14000
	s_movk_i32 s69, 0x6000
	s_andn2_b64 vcc, exec, s[2:3]
	s_cbranch_vccnz .LBB0_1425

; #define PG8_STAGE(...) PG8_STAGE_(__VA_ARGS__, 0u)
; #define PG8_WAIT_V(n) asm volatile("s_waitcnt vmcnt(" #n ")" ::: "memory")
; #define PG8_WAIT_L(n) asm volatile("s_waitcnt lgkmcnt(" #n ")" ::: "memory")
; #define PG8_BAR __builtin_amdgcn_s_barrier()
; #define PG8_SCHED __builtin_amdgcn_sched_barrier(0)
; template <class Epi, class Sched, bool ALIGN_EPI = true, bool SP2 = true>
; __device__ __forceinline__ void gemm_phase(LAS unsigned char* lds, const Gemm g, const Sched& S, const Epi& E) {
;     ...
;             const bool last = (t == nt - 2);
;             const char* a1 = cA + (size_t)(t + 1) * kstep;
;             const char* a2 = last ? nA : cA + (size_t)(t + 2) * kstep; const char* b2 = last ? nB : cB + (size_t)(t + 2) * kstep;
;             const char* a3 = a2 + kstep; const char* b3 = b2 + kstep;
;             if constexpr (SP2) {
;             PG8_LDB(B0, 0, 0); PG8_LDB(B1, 0, 1); PG8_SCHED; PG8_LDA(At, 0, 0); PG8_STAGE(PG8_SA(1, 1), a1, voffAh);
;             PG8_WAIT_V(8); PG8_WAIT_L(0); PG8_BAR; PG8_MMA(0, 0, At, B0); PG8_MMA(0, 1, At, B1); PG8_BAR; PG8_SCHED;
;             if constexpr (!Epi::HALF_M) PG8_LDA(At, 0, 1); PG8_STAGE(PG8_SB(0, 0), b2, voffB); PG8_STAGE(PG8_SB(0, 1), b2, voffBh); PG8_STAGE(PG8_SA(0, 0), a2, voffA);
;             PG8_WAIT_V(8); PG8_WAIT_L(0); PG8_BAR; if constexpr (!Epi::HALF_M) { PG8_MMA(1, 0, At, B0); PG8_MMA(1, 1, At, B1); } PG8_BAR; PG8_SCHED;
.LBB0_1758:
	v_add_u32_e32 v34, s5, v247
	ds_read_b128 v[48:51], v34
	ds_read_b128 v[60:63], v34 offset:1024
	ds_read_b128 v[72:75], v34 offset:2048
	ds_read_b128 v[84:87], v34 offset:3072
	v_add_u32_e32 v34, s39, v247
	ds_read_b128 v[96:99], v34
	ds_read_b128 v[108:111], v34 offset:1024
	ds_read_b128 v[120:123], v34 offset:2048
	ds_read_b128 v[132:135], v34 offset:3072
	s_add_i32 s62, s24, 2
	s_add_u32 s26, s22, 0x80
	s_addc_u32 s25, s23, 0
	s_cmp_eq_u32 s55, s24
	s_cselect_b32 s24, s17, s26
	s_cselect_b32 s25, s15, s25
	s_cselect_b32 s27, s58, s61
	s_cselect_b32 s26, s59, s60
	v_mov_b32_e32 v34, v244
	ds_read_b128 v[144:147], v249
	ds_read_b128 v[156:159], v249 offset:1024
	ds_read_b128 v[164:167], v249 offset:2048
	ds_read_b128 v[172:175], v249 offset:3072
	ds_read_b128 v[180:183], v249 offset:4096
	ds_read_b128 v[184:187], v249 offset:5120
	ds_read_b128 v[188:191], v249 offset:6144
	ds_read_b128 v[192:195], v249 offset:7168
	s_add_i32 m0, s42, 0xc000
	s_nop 0
	global_load_lds_dwordx4 v34, s[22:23]
	v_mov_b32_e32 v34, v245
	s_add_i32 m0, s42, 0xe000
	s_nop 0
	global_load_lds_dwordx4 v34, s[22:23]
	s_waitcnt vmcnt(8)
	s_waitcnt lgkmcnt(0)
	s_barrier
	s_waitcnt lgkmcnt(0)
	v_mfma_f32_16x16x32_f16 v[176:179], v[48:51], v[144:147], v[176:179]
	v_mfma_f32_16x16x32_f16 v[168:171], v[72:75], v[144:147], v[168:171]
	v_mfma_f32_16x16x32_f16 v[148:151], v[48:51], v[164:167], v[148:151]
	v_mfma_f32_16x16x32_f16 v[140:143], v[72:75], v[164:167], v[140:143]
	v_mfma_f32_16x16x32_f16 v[124:127], v[48:51], v[180:183], v[124:127]
	v_mfma_f32_16x16x32_f16 v[116:119], v[72:75], v[180:183], v[116:119]
	v_mfma_f32_16x16x32_f16 v[100:103], v[48:51], v[188:191], v[100:103]
	v_mfma_f32_16x16x32_f16 v[92:95], v[72:75], v[188:191], v[92:95]
	v_mfma_f32_16x16x32_f16 v[176:179], v[60:63], v[156:159], v[176:179]
	v_mfma_f32_16x16x32_f16 v[168:171], v[84:87], v[156:159], v[168:171]
	v_mfma_f32_16x16x32_f16 v[148:151], v[60:63], v[172:175], v[148:151]
	v_mfma_f32_16x16x32_f16 v[140:143], v[84:87], v[172:175], v[140:143]
	v_mfma_f32_16x16x32_f16 v[124:127], v[60:63], v[184:187], v[124:127]
	v_mfma_f32_16x16x32_f16 v[116:119], v[84:87], v[184:187], v[116:119]
	v_mfma_f32_16x16x32_f16 v[100:103], v[60:63], v[192:195], v[100:103]
	v_mfma_f32_16x16x32_f16 v[92:95], v[84:87], v[192:195], v[92:95]
	v_mfma_f32_16x16x32_f16 v[160:163], v[96:99], v[144:147], v[160:163]
	v_mfma_f32_16x16x32_f16 v[136:139], v[96:99], v[164:167], v[136:139]
	v_mfma_f32_16x16x32_f16 v[128:131], v[120:123], v[164:167], v[128:131]
	v_mfma_f32_16x16x32_f16 v[112:115], v[96:99], v[180:183], v[112:115]
	v_mfma_f32_16x16x32_f16 v[104:107], v[120:123], v[180:183], v[104:107]
	v_mfma_f32_16x16x32_f16 v[88:91], v[96:99], v[188:191], v[88:91]
	v_mfma_f32_16x16x32_f16 v[80:83], v[120:123], v[188:191], v[80:83]
	v_mfma_f32_16x16x32_f16 v[160:163], v[108:111], v[156:159], v[160:163]
	v_mfma_f32_16x16x32_f16 v[144:147], v[120:123], v[144:147], v[152:155]
	v_mfma_f32_16x16x32_f16 v[136:139], v[108:111], v[172:175], v[136:139]
	v_mfma_f32_16x16x32_f16 v[128:131], v[132:135], v[172:175], v[128:131]
	v_mfma_f32_16x16x32_f16 v[112:115], v[108:111], v[184:187], v[112:115]
	v_mfma_f32_16x16x32_f16 v[104:107], v[132:135], v[184:187], v[104:107]
	v_mfma_f32_16x16x32_f16 v[88:91], v[108:111], v[192:195], v[88:91]
	v_mfma_f32_16x16x32_f16 v[80:83], v[132:135], v[192:195], v[80:83]
	v_mfma_f32_16x16x32_f16 v[144:147], v[132:135], v[156:159], v[144:147]
	s_barrier
	v_mov_b32_e32 v34, v224
	s_mov_b32 m0, s37
	ds_read_b128 v[152:155], v249 offset:16384
	ds_read_b128 v[156:159], v249 offset:17408
	ds_read_b128 v[164:167], v249 offset:18432
	ds_read_b128 v[172:175], v249 offset:19456
	ds_read_b128 v[180:183], v249 offset:20480
	ds_read_b128 v[184:187], v249 offset:21504
	ds_read_b128 v[188:191], v249 offset:22528
	ds_read_b128 v[192:195], v249 offset:23552
	s_nop 0
	global_load_lds_dwordx4 v34, s[26:27]
	v_mov_b32_e32 v34, v241
	s_mov_b32 m0, s38
	s_nop 0
	global_load_lds_dwordx4 v34, s[26:27]
	v_mov_b32_e32 v34, v242
	s_mov_b32 m0, s40
	s_nop 0
	global_load_lds_dwordx4 v34, s[26:27]
	v_mov_b32_e32 v34, v243
	s_mov_b32 m0, s41
	s_nop 0
	global_load_lds_dwordx4 v34, s[26:27]
	v_mov_b32_e32 v34, v197
	s_mov_b32 m0, s42
	s_nop 0
	global_load_lds_dwordx4 v34, s[24:25]
	v_mov_b32_e32 v34, v225
	s_mov_b32 m0, s43
	s_nop 0
	global_load_lds_dwordx4 v34, s[24:25]
	s_waitcnt vmcnt(8)
	s_waitcnt lgkmcnt(0)
	s_barrier
	s_waitcnt lgkmcnt(0)
	v_mfma_f32_16x16x32_f16 v[76:79], v[48:51], v[152:155], v[76:79]
	v_mfma_f32_16x16x32_f16 v[68:71], v[72:75], v[152:155], v[68:71]
	v_mfma_f32_16x16x32_f16 v[52:55], v[48:51], v[164:167], v[52:55]
	v_mfma_f32_16x16x32_f16 v[44:47], v[72:75], v[164:167], v[44:47]
	v_mfma_f32_16x16x32_f16 v[30:33], v[48:51], v[180:183], v[30:33]
	v_mfma_f32_16x16x32_f16 v[26:29], v[72:75], v[180:183], v[26:29]
	v_mfma_f32_16x16x32_f16 v[14:17], v[48:51], v[188:191], v[14:17]
	v_mfma_f32_16x16x32_f16 v[10:13], v[72:75], v[188:191], v[10:13]
	v_mfma_f32_16x16x32_f16 v[76:79], v[60:63], v[156:159], v[76:79]
	v_mfma_f32_16x16x32_f16 v[68:71], v[84:87], v[156:159], v[68:71]
	v_mfma_f32_16x16x32_f16 v[52:55], v[60:63], v[172:175], v[52:55]
	v_mfma_f32_16x16x32_f16 v[44:47], v[84:87], v[172:175], v[44:47]
	v_mfma_f32_16x16x32_f16 v[30:33], v[60:63], v[184:187], v[30:33]
	v_mfma_f32_16x16x32_f16 v[26:29], v[84:87], v[184:187], v[26:29]
	v_mfma_f32_16x16x32_f16 v[14:17], v[60:63], v[192:195], v[14:17]
	v_mfma_f32_16x16x32_f16 v[10:13], v[84:87], v[192:195], v[10:13]
	v_mfma_f32_16x16x32_f16 v[56:59], v[120:123], v[152:155], v[56:59]
	v_mfma_f32_16x16x32_f16 v[40:43], v[96:99], v[164:167], v[40:43]
	v_mfma_f32_16x16x32_f16 v[36:39], v[120:123], v[164:167], v[36:39]
	v_mfma_f32_16x16x32_f16 v[22:25], v[96:99], v[180:183], v[22:25]
	v_mfma_f32_16x16x32_f16 v[18:21], v[120:123], v[180:183], v[18:21]
	v_mfma_f32_16x16x32_f16 v[6:9], v[96:99], v[188:191], v[6:9]
	v_mfma_f32_16x16x32_f16 v[2:5], v[120:123], v[188:191], v[2:5]
	v_mfma_f32_16x16x32_f16 v[48:51], v[96:99], v[152:155], v[64:67]
	v_mfma_f32_16x16x32_f16 v[56:59], v[132:135], v[156:159], v[56:59]
	v_mfma_f32_16x16x32_f16 v[40:43], v[108:111], v[172:175], v[40:43]
	v_mfma_f32_16x16x32_f16 v[36:39], v[132:135], v[172:175], v[36:39]
	v_mfma_f32_16x16x32_f16 v[22:25], v[108:111], v[184:187], v[22:25]
	v_mfma_f32_16x16x32_f16 v[18:21], v[132:135], v[184:187], v[18:21]
	v_mfma_f32_16x16x32_f16 v[6:9], v[108:111], v[192:195], v[6:9]
	v_mfma_f32_16x16x32_f16 v[2:5], v[132:135], v[192:195], v[2:5]
	v_mfma_f32_16x16x32_f16 v[48:51], v[108:111], v[156:159], v[48:51]
	s_barrier
; #define PG8_STAGE(...) PG8_STAGE_(__VA_ARGS__, 0u)
; #define PG8_WAIT_V(n) asm volatile("s_waitcnt vmcnt(" #n ")" ::: "memory")
; #define PG8_WAIT_L(n) asm volatile("s_waitcnt lgkmcnt(" #n ")" ::: "memory")
; #define PG8_BAR __builtin_amdgcn_s_barrier()
; #define PG8_SCHED __builtin_amdgcn_sched_barrier(0)
; template <class Epi, class Sched, bool ALIGN_EPI = true, bool SP2 = true>
; __device__ __forceinline__ void gemm_phase(LAS unsigned char* lds, const Gemm g, const Sched& S, const Epi& E) {
;     ...
;             PG8_LDB(B0, 1, 0); PG8_LDB(B1, 1, 1); PG8_SCHED; PG8_LDA(At, 1, 0); PG8_STAGE(PG8_SA(0, 1), a2, voffAh);
;             PG8_WAIT_V(8); PG8_WAIT_L(0); PG8_BAR; PG8_MMA(0, 0, At, B0); PG8_MMA(0, 1, At, B1); PG8_BAR; PG8_SCHED;
	v_add_u32_e32 v34, s47, v247
	ds_read_b128 v[60:63], v34
	ds_read_b128 v[64:67], v34 offset:1024
	ds_read_b128 v[72:75], v34 offset:2048
	ds_read_b128 v[84:87], v34 offset:3072
	v_add_u32_e32 v34, s52, v247
	ds_read_b128 v[96:99], v34
	ds_read_b128 v[108:111], v34 offset:1024
	ds_read_b128 v[120:123], v34 offset:2048
	ds_read_b128 v[132:135], v34 offset:3072
	v_mov_b32_e32 v34, v244
	s_mov_b32 m0, s44
	ds_read_b128 v[152:155], v249 offset:32768
	ds_read_b128 v[156:159], v249 offset:33792
	ds_read_b128 v[164:167], v249 offset:34816
	ds_read_b128 v[172:175], v249 offset:35840
	ds_read_b128 v[180:183], v249 offset:36864
	ds_read_b128 v[184:187], v249 offset:37888
	ds_read_b128 v[188:191], v249 offset:38912
	ds_read_b128 v[192:195], v249 offset:39936
	s_nop 0
	global_load_lds_dwordx4 v34, s[24:25]
	v_mov_b32_e32 v34, v245
	s_mov_b32 m0, s45
	s_nop 0
	global_load_lds_dwordx4 v34, s[24:25]
	s_waitcnt vmcnt(8)
	s_waitcnt lgkmcnt(0)
	s_barrier
	s_waitcnt lgkmcnt(0)
	v_mfma_f32_16x16x32_f16 v[176:179], v[60:63], v[152:155], v[176:179]
	v_mfma_f32_16x16x32_f16 v[168:171], v[72:75], v[152:155], v[168:171]
	v_mfma_f32_16x16x32_f16 v[148:151], v[60:63], v[164:167], v[148:151]
	v_mfma_f32_16x16x32_f16 v[140:143], v[72:75], v[164:167], v[140:143]
	v_mfma_f32_16x16x32_f16 v[124:127], v[60:63], v[180:183], v[124:127]
	v_mfma_f32_16x16x32_f16 v[116:119], v[72:75], v[180:183], v[116:119]
	v_mfma_f32_16x16x32_f16 v[100:103], v[60:63], v[188:191], v[100:103]
	v_mfma_f32_16x16x32_f16 v[92:95], v[72:75], v[188:191], v[92:95]
	v_mfma_f32_16x16x32_f16 v[176:179], v[64:67], v[156:159], v[176:179]
	v_mfma_f32_16x16x32_f16 v[168:171], v[84:87], v[156:159], v[168:171]
	v_mfma_f32_16x16x32_f16 v[148:151], v[64:67], v[172:175], v[148:151]
	v_mfma_f32_16x16x32_f16 v[140:143], v[84:87], v[172:175], v[140:143]
	v_mfma_f32_16x16x32_f16 v[124:127], v[64:67], v[184:187], v[124:127]
	v_mfma_f32_16x16x32_f16 v[116:119], v[84:87], v[184:187], v[116:119]
	v_mfma_f32_16x16x32_f16 v[100:103], v[64:67], v[192:195], v[100:103]
	v_mfma_f32_16x16x32_f16 v[92:95], v[84:87], v[192:195], v[92:95]
	v_mfma_f32_16x16x32_f16 v[160:163], v[96:99], v[152:155], v[160:163]
	v_mfma_f32_16x16x32_f16 v[144:147], v[120:123], v[152:155], v[144:147]
	v_mfma_f32_16x16x32_f16 v[136:139], v[96:99], v[164:167], v[136:139]
	v_mfma_f32_16x16x32_f16 v[128:131], v[120:123], v[164:167], v[128:131]
	v_mfma_f32_16x16x32_f16 v[112:115], v[96:99], v[180:183], v[112:115]
	v_mfma_f32_16x16x32_f16 v[104:107], v[120:123], v[180:183], v[104:107]
	v_mfma_f32_16x16x32_f16 v[88:91], v[96:99], v[188:191], v[88:91]
	v_mfma_f32_16x16x32_f16 v[80:83], v[120:123], v[188:191], v[80:83]
	v_mfma_f32_16x16x32_f16 v[160:163], v[108:111], v[156:159], v[160:163]
	v_mfma_f32_16x16x32_f16 v[152:155], v[132:135], v[156:159], v[144:147]
	v_mfma_f32_16x16x32_f16 v[136:139], v[108:111], v[172:175], v[136:139]
	v_mfma_f32_16x16x32_f16 v[128:131], v[132:135], v[172:175], v[128:131]
	v_mfma_f32_16x16x32_f16 v[112:115], v[108:111], v[184:187], v[112:115]
	v_mfma_f32_16x16x32_f16 v[104:107], v[132:135], v[184:187], v[104:107]
	v_mfma_f32_16x16x32_f16 v[88:91], v[108:111], v[192:195], v[88:91]
	v_mfma_f32_16x16x32_f16 v[80:83], v[132:135], v[192:195], v[80:83]
	s_barrier
; #define PG8_STAGE(...) PG8_STAGE_(__VA_ARGS__, 0u)
; #define PG8_WAIT_V(n) asm volatile("s_waitcnt vmcnt(" #n ")" ::: "memory")
; #define PG8_WAIT_L(n) asm volatile("s_waitcnt lgkmcnt(" #n ")" ::: "memory")
; #define PG8_BAR __builtin_amdgcn_s_barrier()
; #define PG8_SCHED __builtin_amdgcn_sched_barrier(0)
; template <class Epi, class Sched, bool ALIGN_EPI = true, bool SP2 = true>
; __device__ __forceinline__ void gemm_phase(LAS unsigned char* lds, const Gemm g, const Sched& S, const Epi& E) {
;     ...
;             const char* a1 = cA + (size_t)(t + 1) * kstep;
;             const char* a2 = last ? nA : cA + (size_t)(t + 2) * kstep; const char* b2 = last ? nB : cB + (size_t)(t + 2) * kstep;
;             const char* a3 = a2 + kstep; const char* b3 = b2 + kstep;
;             if constexpr (SP2) {
;             PG8_LDB(B0, 0, 0); PG8_LDB(B1, 0, 1); PG8_SCHED; PG8_LDA(At, 0, 0); PG8_STAGE(PG8_SA(1, 1), a1, voffAh);
;             PG8_WAIT_V(8); PG8_WAIT_L(0); PG8_BAR; PG8_MMA(0, 0, At, B0); PG8_MMA(0, 1, At, B1); PG8_BAR; PG8_SCHED;
;             if constexpr (!Epi::HALF_M) PG8_LDA(At, 0, 1); PG8_STAGE(PG8_SB(0, 0), b2, voffB); PG8_STAGE(PG8_SB(0, 1), b2, voffBh); PG8_STAGE(PG8_SA(0, 0), a2, voffA);
;             PG8_WAIT_V(8); PG8_WAIT_L(0); PG8_BAR; if constexpr (!Epi::HALF_M) { PG8_MMA(1, 0, At, B0); PG8_MMA(1, 1, At, B1); } PG8_BAR; PG8_SCHED;
;             PG8_LDB(B0, 1, 0); PG8_LDB(B1, 1, 1); PG8_SCHED; PG8_LDA(At, 1, 0); PG8_STAGE(PG8_SA(0, 1), a2, voffAh);
;             PG8_WAIT_V(8); PG8_WAIT_L(0); PG8_BAR; PG8_MMA(0, 0, At, B0); PG8_MMA(0, 1, At, B1); PG8_BAR; PG8_SCHED;
;             if constexpr (!Epi::HALF_M) PG8_LDA(At, 1, 1); PG8_STAGE(PG8_SB(1, 0), b3, voffB); PG8_STAGE(PG8_SB(1, 1), b3, voffBh); PG8_STAGE(PG8_SA(1, 0), a3, voffA);
;             PG8_WAIT_V(8); PG8_WAIT_L(0); PG8_BAR; if constexpr (!Epi::HALF_M) { PG8_MMA(1, 0, At, B0); PG8_MMA(1, 1, At, B1); } PG8_BAR; PG8_SCHED;
	v_mov_b32_e32 v34, v224
	ds_read_b128 v[144:147], v249 offset:49152
	ds_read_b128 v[156:159], v249 offset:50176
	ds_read_b128 v[164:167], v249 offset:51200
	ds_read_b128 v[172:175], v249 offset:52224
	ds_read_b128 v[180:183], v249 offset:53248
	ds_read_b128 v[184:187], v249 offset:54272
	ds_read_b128 v[188:191], v249 offset:55296
	ds_read_b128 v[192:195], v249 offset:56320
	s_mov_b32 m0, s48
	v_lshl_add_u64 v[206:207], s[26:27], 0, v[34:35]
	v_lshl_add_u64 v[206:207], v[206:207], 0, s[80:81]
	v_mov_b32_e32 v34, v241
	global_load_lds_dwordx4 v[206:207], off
	s_mov_b32 m0, s49
	v_lshl_add_u64 v[206:207], s[26:27], 0, v[34:35]
	v_lshl_add_u64 v[206:207], v[206:207], 0, s[80:81]
	v_mov_b32_e32 v34, v242
	global_load_lds_dwordx4 v[206:207], off
	s_mov_b32 m0, s53
	v_lshl_add_u64 v[206:207], s[26:27], 0, v[34:35]
	v_lshl_add_u64 v[206:207], v[206:207], 0, s[80:81]
	v_mov_b32_e32 v34, v243
	global_load_lds_dwordx4 v[206:207], off
	s_mov_b32 m0, s54
	v_lshl_add_u64 v[206:207], s[26:27], 0, v[34:35]
	v_lshl_add_u64 v[206:207], v[206:207], 0, s[80:81]
	v_mov_b32_e32 v34, v197
	global_load_lds_dwordx4 v[206:207], off
	s_mov_b32 m0, s50
	v_lshl_add_u64 v[206:207], s[24:25], 0, v[34:35]
	v_lshl_add_u64 v[206:207], v[206:207], 0, s[80:81]
	v_mov_b32_e32 v34, v225
	global_load_lds_dwordx4 v[206:207], off
	s_mov_b32 m0, s51
	v_lshl_add_u64 v[206:207], s[24:25], 0, v[34:35]
	v_lshl_add_u64 v[206:207], v[206:207], 0, s[80:81]
	global_load_lds_dwordx4 v[206:207], off
	s_waitcnt vmcnt(8)
	s_waitcnt lgkmcnt(0)
	s_barrier
	s_waitcnt lgkmcnt(0)
	v_mfma_f32_16x16x32_f16 v[76:79], v[60:63], v[144:147], v[76:79]
	v_mfma_f32_16x16x32_f16 v[68:71], v[72:75], v[144:147], v[68:71]
	v_mfma_f32_16x16x32_f16 v[52:55], v[60:63], v[164:167], v[52:55]
	v_mfma_f32_16x16x32_f16 v[44:47], v[72:75], v[164:167], v[44:47]
	v_mfma_f32_16x16x32_f16 v[30:33], v[60:63], v[180:183], v[30:33]
	v_mfma_f32_16x16x32_f16 v[26:29], v[72:75], v[180:183], v[26:29]
	v_mfma_f32_16x16x32_f16 v[14:17], v[60:63], v[188:191], v[14:17]
	v_mfma_f32_16x16x32_f16 v[10:13], v[72:75], v[188:191], v[10:13]
	v_mfma_f32_16x16x32_f16 v[76:79], v[64:67], v[156:159], v[76:79]
	v_mfma_f32_16x16x32_f16 v[68:71], v[84:87], v[156:159], v[68:71]
	v_mfma_f32_16x16x32_f16 v[52:55], v[64:67], v[172:175], v[52:55]
	v_mfma_f32_16x16x32_f16 v[44:47], v[84:87], v[172:175], v[44:47]
	v_mfma_f32_16x16x32_f16 v[30:33], v[64:67], v[184:187], v[30:33]
	v_mfma_f32_16x16x32_f16 v[26:29], v[84:87], v[184:187], v[26:29]
	v_mfma_f32_16x16x32_f16 v[14:17], v[64:67], v[192:195], v[14:17]
	v_mfma_f32_16x16x32_f16 v[10:13], v[84:87], v[192:195], v[10:13]
	v_mfma_f32_16x16x32_f16 v[48:51], v[96:99], v[144:147], v[48:51]
	v_mfma_f32_16x16x32_f16 v[64:67], v[108:111], v[156:159], v[48:51]
	v_mfma_f32_16x16x32_f16 v[48:51], v[120:123], v[144:147], v[56:59]
	v_mfma_f32_16x16x32_f16 v[40:43], v[96:99], v[164:167], v[40:43]
	v_mfma_f32_16x16x32_f16 v[36:39], v[120:123], v[164:167], v[36:39]
	v_mfma_f32_16x16x32_f16 v[22:25], v[96:99], v[180:183], v[22:25]
	v_mfma_f32_16x16x32_f16 v[18:21], v[120:123], v[180:183], v[18:21]
	v_mfma_f32_16x16x32_f16 v[6:9], v[96:99], v[188:191], v[6:9]
	v_mfma_f32_16x16x32_f16 v[2:5], v[120:123], v[188:191], v[2:5]
	v_mfma_f32_16x16x32_f16 v[56:59], v[132:135], v[156:159], v[48:51]
	v_mfma_f32_16x16x32_f16 v[40:43], v[108:111], v[172:175], v[40:43]
	v_mfma_f32_16x16x32_f16 v[36:39], v[132:135], v[172:175], v[36:39]
	v_mfma_f32_16x16x32_f16 v[22:25], v[108:111], v[184:187], v[22:25]
	v_mfma_f32_16x16x32_f16 v[18:21], v[132:135], v[184:187], v[18:21]
	v_mfma_f32_16x16x32_f16 v[6:9], v[108:111], v[192:195], v[6:9]
	v_mfma_f32_16x16x32_f16 v[2:5], v[132:135], v[192:195], v[2:5]
	s_barrier
	s_add_u32 s22, s22, 0x100
	s_addc_u32 s23, s23, 0
	s_add_u32 s60, s60, 0x100
	s_addc_u32 s61, s61, 0
	s_cmp_ge_i32 s62, s46
	s_mov_b32 s24, s62
	s_cbranch_scc0 .LBB0_1758

; #define PG8_STAGE(...) PG8_STAGE_(__VA_ARGS__, 0u)
; #define PG8_WAIT_V(n) asm volatile("s_waitcnt vmcnt(" #n ")" ::: "memory")
; #define PG8_WAIT_L(n) asm volatile("s_waitcnt lgkmcnt(" #n ")" ::: "memory")
; #define PG8_BAR __builtin_amdgcn_s_barrier()
; #define PG8_SCHED __builtin_amdgcn_sched_barrier(0)
; template <class Epi, class Sched, bool ALIGN_EPI = true, bool SP2 = true>
; __device__ __forceinline__ void gemm_phase(LAS unsigned char* lds, const Gemm g, const Sched& S, const Epi& E) {
;     ...
;             PG8_LDB(B0, 0, 0); PG8_LDB(B1, 0, 1); PG8_SCHED; PG8_LDA(At, 0, 0); PG8_STAGE(PG8_SA(1, 1), a1, voffAh);
;             PG8_WAIT_V(8); PG8_WAIT_L(0); PG8_BAR; PG8_MMA(0, 0, At, B0); PG8_MMA(0, 1, At, B1); PG8_BAR; PG8_SCHED;
;             if constexpr (!Epi::HALF_M) PG8_LDA(At, 0, 1); PG8_STAGE(PG8_SB(0, 0), b2, voffB); PG8_STAGE(PG8_SB(0, 1), b2, voffBh); PG8_STAGE(PG8_SA(0, 0), a2, voffA);
;             PG8_WAIT_V(8); PG8_WAIT_L(0); PG8_BAR; if constexpr (!Epi::HALF_M) { PG8_MMA(1, 0, At, B0); PG8_MMA(1, 1, At, B1); } PG8_BAR; PG8_SCHED;
.LBB0_1838:
	v_add_u32_e32 v2, s21, v182
	v_add_u32_e32 v14, s43, v182
	ds_read_b128 v[18:21], v2
	ds_read_b128 v[22:25], v2 offset:1024
	ds_read_b128 v[26:29], v2 offset:2048
	ds_read_b128 v[30:33], v2 offset:3072
	ds_read_b128 v[2:5], v14
	ds_read_b128 v[6:9], v14 offset:1024
	ds_read_b128 v[10:13], v14 offset:2048
	ds_read_b128 v[14:17], v14 offset:3072
	s_add_i32 s64, s22, 2
	s_add_u32 s65, s2, 0x80
	s_addc_u32 s23, s3, 0
	s_cmp_eq_u32 s60, s22
	s_cselect_b32 s22, s63, s65
	s_cselect_b64 vcc, -1, 0
	s_cselect_b32 s23, s17, s23
	v_cndmask_b32_e32 v173, v171, v165, vcc
	v_cndmask_b32_e32 v172, v170, v185, vcc
	v_mov_b32_e32 v34, v179
	ds_read_b128 v[186:189], v184
	ds_read_b128 v[190:193], v184 offset:1024
	ds_read_b128 v[206:209], v184 offset:2048
	ds_read_b128 v[210:213], v184 offset:3072
	ds_read_b128 v[214:217], v184 offset:4096
	ds_read_b128 v[218:221], v184 offset:5120
	ds_read_b128 v[242:245], v184 offset:6144
	ds_read_b128 v[246:249], v184 offset:7168
	s_add_i32 m0, s46, 0xc000
	s_nop 0
	global_load_lds_dwordx4 v34, s[2:3]
	v_mov_b32_e32 v34, v180
	s_add_i32 m0, s46, 0xe000
	s_nop 0
	global_load_lds_dwordx4 v34, s[2:3]
	s_waitcnt vmcnt(8)
	s_waitcnt lgkmcnt(0)
	s_barrier
	s_waitcnt lgkmcnt(0)
	v_mfma_scale_f32_16x16x128_f8f6f4 v[156:159], v[18:25], v[186:193], v[156:159], v1, v1 op_sel_hi:[0,0,0]
	v_mfma_scale_f32_16x16x128_f8f6f4 v[152:155], v[26:33], v[186:193], v[152:155], v1, v1 op_sel_hi:[0,0,0]
	v_mfma_scale_f32_16x16x128_f8f6f4 v[144:147], v[18:25], v[206:213], v[144:147], v1, v1 op_sel_hi:[0,0,0]
	v_mfma_scale_f32_16x16x128_f8f6f4 v[136:139], v[26:33], v[206:213], v[136:139], v1, v1 op_sel_hi:[0,0,0]
	v_mfma_scale_f32_16x16x128_f8f6f4 v[128:131], v[18:25], v[214:221], v[128:131], v1, v1 op_sel_hi:[0,0,0]
	v_mfma_scale_f32_16x16x128_f8f6f4 v[120:123], v[26:33], v[214:221], v[120:123], v1, v1 op_sel_hi:[0,0,0]
	v_mfma_scale_f32_16x16x128_f8f6f4 v[112:115], v[18:25], v[242:249], v[112:115], v1, v1 op_sel_hi:[0,0,0]
	v_mfma_scale_f32_16x16x128_f8f6f4 v[104:107], v[26:33], v[242:249], v[104:107], v1, v1 op_sel_hi:[0,0,0]
	v_mfma_scale_f32_16x16x128_f8f6f4 v[160:163], v[2:9], v[186:193], v[160:163], v1, v1 op_sel_hi:[0,0,0]
	v_mfma_scale_f32_16x16x128_f8f6f4 v[148:151], v[10:17], v[186:193], v[148:151], v1, v1 op_sel_hi:[0,0,0]
	v_mfma_scale_f32_16x16x128_f8f6f4 v[140:143], v[2:9], v[206:213], v[140:143], v1, v1 op_sel_hi:[0,0,0]
	v_mfma_scale_f32_16x16x128_f8f6f4 v[132:135], v[10:17], v[206:213], v[132:135], v1, v1 op_sel_hi:[0,0,0]
	v_mfma_scale_f32_16x16x128_f8f6f4 v[124:127], v[2:9], v[214:221], v[124:127], v1, v1 op_sel_hi:[0,0,0]
	v_mfma_scale_f32_16x16x128_f8f6f4 v[116:119], v[10:17], v[214:221], v[116:119], v1, v1 op_sel_hi:[0,0,0]
	v_mfma_scale_f32_16x16x128_f8f6f4 v[108:111], v[2:9], v[242:249], v[108:111], v1, v1 op_sel_hi:[0,0,0]
	v_mfma_scale_f32_16x16x128_f8f6f4 v[100:103], v[10:17], v[242:249], v[100:103], v1, v1 op_sel_hi:[0,0,0]
	s_barrier
	v_mov_b32_e32 v34, v175
	s_mov_b32 m0, s41
	ds_read_b128 v[186:189], v184 offset:16384
	ds_read_b128 v[190:193], v184 offset:17408
	ds_read_b128 v[206:209], v184 offset:18432
	ds_read_b128 v[210:213], v184 offset:19456
	ds_read_b128 v[214:217], v184 offset:20480
	ds_read_b128 v[218:221], v184 offset:21504
	ds_read_b128 v[242:245], v184 offset:22528
	ds_read_b128 v[246:249], v184 offset:23552
	v_readfirstlane_b32 s66, v172
	v_readfirstlane_b32 s67, v173
	s_nop 4
	global_load_lds_dwordx4 v34, s[66:67]
	v_mov_b32_e32 v34, v177
	s_mov_b32 m0, s42
	s_nop 0
	global_load_lds_dwordx4 v34, s[66:67]
	v_mov_b32_e32 v34, v169
	s_mov_b32 m0, s44
	s_nop 0
	global_load_lds_dwordx4 v34, s[66:67]
	v_mov_b32_e32 v34, v178
	s_mov_b32 m0, s45
	s_nop 0
	global_load_lds_dwordx4 v34, s[66:67]
	v_mov_b32_e32 v34, v174
	s_mov_b32 m0, s46
	s_nop 0
	global_load_lds_dwordx4 v34, s[22:23]
	v_mov_b32_e32 v34, v176
	s_mov_b32 m0, s47
	s_nop 0
	global_load_lds_dwordx4 v34, s[22:23]
	s_waitcnt vmcnt(8)
	s_waitcnt lgkmcnt(0)
	s_barrier
	s_waitcnt lgkmcnt(0)
	v_mfma_scale_f32_16x16x128_f8f6f4 v[96:99], v[18:25], v[186:193], v[96:99], v1, v1 op_sel_hi:[0,0,0]
	v_mfma_scale_f32_16x16x128_f8f6f4 v[88:91], v[26:33], v[186:193], v[88:91], v1, v1 op_sel_hi:[0,0,0]
	v_mfma_scale_f32_16x16x128_f8f6f4 v[80:83], v[18:25], v[206:213], v[80:83], v1, v1 op_sel_hi:[0,0,0]
	v_mfma_scale_f32_16x16x128_f8f6f4 v[72:75], v[26:33], v[206:213], v[72:75], v1, v1 op_sel_hi:[0,0,0]
	v_mfma_scale_f32_16x16x128_f8f6f4 v[64:67], v[18:25], v[214:221], v[64:67], v1, v1 op_sel_hi:[0,0,0]
	v_mfma_scale_f32_16x16x128_f8f6f4 v[56:59], v[26:33], v[214:221], v[56:59], v1, v1 op_sel_hi:[0,0,0]
	v_mfma_scale_f32_16x16x128_f8f6f4 v[48:51], v[18:25], v[242:249], v[48:51], v1, v1 op_sel_hi:[0,0,0]
	v_mfma_scale_f32_16x16x128_f8f6f4 v[40:43], v[26:33], v[242:249], v[40:43], v1, v1 op_sel_hi:[0,0,0]
	v_mfma_scale_f32_16x16x128_f8f6f4 v[92:95], v[2:9], v[186:193], v[92:95], v1, v1 op_sel_hi:[0,0,0]
	v_mfma_scale_f32_16x16x128_f8f6f4 v[84:87], v[10:17], v[186:193], v[84:87], v1, v1 op_sel_hi:[0,0,0]
	v_mfma_scale_f32_16x16x128_f8f6f4 v[76:79], v[2:9], v[206:213], v[76:79], v1, v1 op_sel_hi:[0,0,0]
	v_mfma_scale_f32_16x16x128_f8f6f4 v[68:71], v[10:17], v[206:213], v[68:71], v1, v1 op_sel_hi:[0,0,0]
	v_mfma_scale_f32_16x16x128_f8f6f4 v[60:63], v[2:9], v[214:221], v[60:63], v1, v1 op_sel_hi:[0,0,0]
	v_mfma_scale_f32_16x16x128_f8f6f4 v[52:55], v[10:17], v[214:221], v[52:55], v1, v1 op_sel_hi:[0,0,0]
	v_mfma_scale_f32_16x16x128_f8f6f4 v[44:47], v[2:9], v[242:249], v[44:47], v1, v1 op_sel_hi:[0,0,0]
	v_mfma_scale_f32_16x16x128_f8f6f4 v[36:39], v[10:17], v[242:249], v[36:39], v1, v1 op_sel_hi:[0,0,0]
	s_barrier
; #define PG8_STAGE(...) PG8_STAGE_(__VA_ARGS__, 0u)
; #define PG8_WAIT_V(n) asm volatile("s_waitcnt vmcnt(" #n ")" ::: "memory")
; #define PG8_WAIT_L(n) asm volatile("s_waitcnt lgkmcnt(" #n ")" ::: "memory")
; #define PG8_BAR __builtin_amdgcn_s_barrier()
; #define PG8_SCHED __builtin_amdgcn_sched_barrier(0)
; template <class Epi, class Sched, bool ALIGN_EPI = true, bool SP2 = true>
; __device__ __forceinline__ void gemm_phase(LAS unsigned char* lds, const Gemm g, const Sched& S, const Epi& E) {
;     ...
;             PG8_LDB(B0, 1, 0); PG8_LDB(B1, 1, 1); PG8_SCHED; PG8_LDA(At, 1, 0); PG8_STAGE(PG8_SA(0, 1), a2, voffAh);
;             PG8_WAIT_V(8); PG8_WAIT_L(0); PG8_BAR; PG8_MMA(0, 0, At, B0); PG8_MMA(0, 1, At, B1); PG8_BAR; PG8_SCHED;
;             if constexpr (!Epi::HALF_M) PG8_LDA(At, 1, 1); PG8_STAGE(PG8_SB(1, 0), b3, voffB); PG8_STAGE(PG8_SB(1, 1), b3, voffBh); PG8_STAGE(PG8_SA(1, 0), a3, voffA);
;             PG8_WAIT_V(8); PG8_WAIT_L(0); PG8_BAR; if constexpr (!Epi::HALF_M) { PG8_MMA(1, 0, At, B0); PG8_MMA(1, 1, At, B1); } PG8_BAR; PG8_SCHED;
	v_add_u32_e32 v10, s52, v182
	v_add_u32_e32 v30, s57, v182
	ds_read_b128 v[2:5], v10
	ds_read_b128 v[6:9], v10 offset:1024
	ds_read_b128 v[18:21], v10 offset:2048
	ds_read_b128 v[22:25], v10 offset:3072
	ds_read_b128 v[10:13], v30
	ds_read_b128 v[14:17], v30 offset:1024
	ds_read_b128 v[26:29], v30 offset:2048
	ds_read_b128 v[30:33], v30 offset:3072
	v_mov_b32_e32 v34, v179
	s_mov_b32 m0, s48
	ds_read_b128 v[186:189], v184 offset:32768
	ds_read_b128 v[190:193], v184 offset:33792
	ds_read_b128 v[206:209], v184 offset:34816
	ds_read_b128 v[210:213], v184 offset:35840
	ds_read_b128 v[214:217], v184 offset:36864
	ds_read_b128 v[218:221], v184 offset:37888
	ds_read_b128 v[242:245], v184 offset:38912
	ds_read_b128 v[246:249], v184 offset:39936
	s_nop 0
	global_load_lds_dwordx4 v34, s[22:23]
	v_mov_b32_e32 v34, v180
	s_mov_b32 m0, s49
	s_nop 0
	global_load_lds_dwordx4 v34, s[22:23]
	s_waitcnt vmcnt(8)
	s_waitcnt lgkmcnt(0)
	s_barrier
	s_waitcnt lgkmcnt(0)
	v_mfma_scale_f32_16x16x128_f8f6f4 v[156:159], v[2:9], v[186:193], v[156:159], v1, v1 op_sel_hi:[0,0,0]
	v_mfma_scale_f32_16x16x128_f8f6f4 v[152:155], v[18:25], v[186:193], v[152:155], v1, v1 op_sel_hi:[0,0,0]
	v_mfma_scale_f32_16x16x128_f8f6f4 v[144:147], v[2:9], v[206:213], v[144:147], v1, v1 op_sel_hi:[0,0,0]
	v_mfma_scale_f32_16x16x128_f8f6f4 v[136:139], v[18:25], v[206:213], v[136:139], v1, v1 op_sel_hi:[0,0,0]
	v_mfma_scale_f32_16x16x128_f8f6f4 v[128:131], v[2:9], v[214:221], v[128:131], v1, v1 op_sel_hi:[0,0,0]
	v_mfma_scale_f32_16x16x128_f8f6f4 v[120:123], v[18:25], v[214:221], v[120:123], v1, v1 op_sel_hi:[0,0,0]
	v_mfma_scale_f32_16x16x128_f8f6f4 v[112:115], v[2:9], v[242:249], v[112:115], v1, v1 op_sel_hi:[0,0,0]
	v_mfma_scale_f32_16x16x128_f8f6f4 v[104:107], v[18:25], v[242:249], v[104:107], v1, v1 op_sel_hi:[0,0,0]
	v_mfma_scale_f32_16x16x128_f8f6f4 v[160:163], v[10:17], v[186:193], v[160:163], v1, v1 op_sel_hi:[0,0,0]
	v_mfma_scale_f32_16x16x128_f8f6f4 v[148:151], v[26:33], v[186:193], v[148:151], v1, v1 op_sel_hi:[0,0,0]
	v_mfma_scale_f32_16x16x128_f8f6f4 v[140:143], v[10:17], v[206:213], v[140:143], v1, v1 op_sel_hi:[0,0,0]
	v_mfma_scale_f32_16x16x128_f8f6f4 v[132:135], v[26:33], v[206:213], v[132:135], v1, v1 op_sel_hi:[0,0,0]
	v_mfma_scale_f32_16x16x128_f8f6f4 v[124:127], v[10:17], v[214:221], v[124:127], v1, v1 op_sel_hi:[0,0,0]
	v_mfma_scale_f32_16x16x128_f8f6f4 v[116:119], v[26:33], v[214:221], v[116:119], v1, v1 op_sel_hi:[0,0,0]
	v_mfma_scale_f32_16x16x128_f8f6f4 v[108:111], v[10:17], v[242:249], v[108:111], v1, v1 op_sel_hi:[0,0,0]
	v_mfma_scale_f32_16x16x128_f8f6f4 v[100:103], v[26:33], v[242:249], v[100:103], v1, v1 op_sel_hi:[0,0,0]
	s_barrier
	v_mov_b32_e32 v34, v175
	ds_read_b128 v[186:189], v184 offset:49152
	ds_read_b128 v[190:193], v184 offset:50176
	ds_read_b128 v[206:209], v184 offset:51200
	ds_read_b128 v[210:213], v184 offset:52224
	ds_read_b128 v[214:217], v184 offset:53248
	ds_read_b128 v[218:221], v184 offset:54272
	ds_read_b128 v[242:245], v184 offset:55296
	ds_read_b128 v[246:249], v184 offset:56320
	s_mov_b32 m0, s53
	v_lshl_add_u64 v[194:195], v[172:173], 0, v[34:35]
	v_lshl_add_u64 v[194:195], v[194:195], 0, s[80:81]
	v_mov_b32_e32 v34, v177
	global_load_lds_dwordx4 v[194:195], off
	s_mov_b32 m0, s54
	v_lshl_add_u64 v[194:195], v[172:173], 0, v[34:35]
	v_lshl_add_u64 v[194:195], v[194:195], 0, s[80:81]
	v_mov_b32_e32 v34, v169
	global_load_lds_dwordx4 v[194:195], off
	s_mov_b32 m0, s58
	v_lshl_add_u64 v[194:195], v[172:173], 0, v[34:35]
	v_lshl_add_u64 v[194:195], v[194:195], 0, s[80:81]
	v_mov_b32_e32 v34, v178
	global_load_lds_dwordx4 v[194:195], off
	s_mov_b32 m0, s59
	v_lshl_add_u64 v[172:173], v[172:173], 0, v[34:35]
	v_lshl_add_u64 v[172:173], v[172:173], 0, s[80:81]
	v_mov_b32_e32 v34, v174
	global_load_lds_dwordx4 v[172:173], off
	s_mov_b32 m0, s55
	v_lshl_add_u64 v[172:173], s[22:23], 0, v[34:35]
	v_lshl_add_u64 v[172:173], v[172:173], 0, s[80:81]
	v_mov_b32_e32 v34, v176
	global_load_lds_dwordx4 v[172:173], off
	s_mov_b32 m0, s56
	v_lshl_add_u64 v[172:173], s[22:23], 0, v[34:35]
	v_lshl_add_u64 v[172:173], v[172:173], 0, s[80:81]
	global_load_lds_dwordx4 v[172:173], off
	s_waitcnt vmcnt(8)
	s_waitcnt lgkmcnt(0)
	s_barrier
	s_waitcnt lgkmcnt(0)
	v_mfma_scale_f32_16x16x128_f8f6f4 v[96:99], v[2:9], v[186:193], v[96:99], v1, v1 op_sel_hi:[0,0,0]
	v_mfma_scale_f32_16x16x128_f8f6f4 v[88:91], v[18:25], v[186:193], v[88:91], v1, v1 op_sel_hi:[0,0,0]
	v_mfma_scale_f32_16x16x128_f8f6f4 v[80:83], v[2:9], v[206:213], v[80:83], v1, v1 op_sel_hi:[0,0,0]
	v_mfma_scale_f32_16x16x128_f8f6f4 v[72:75], v[18:25], v[206:213], v[72:75], v1, v1 op_sel_hi:[0,0,0]
	v_mfma_scale_f32_16x16x128_f8f6f4 v[64:67], v[2:9], v[214:221], v[64:67], v1, v1 op_sel_hi:[0,0,0]
	v_mfma_scale_f32_16x16x128_f8f6f4 v[56:59], v[18:25], v[214:221], v[56:59], v1, v1 op_sel_hi:[0,0,0]
	v_mfma_scale_f32_16x16x128_f8f6f4 v[48:51], v[2:9], v[242:249], v[48:51], v1, v1 op_sel_hi:[0,0,0]
	v_mfma_scale_f32_16x16x128_f8f6f4 v[40:43], v[18:25], v[242:249], v[40:43], v1, v1 op_sel_hi:[0,0,0]
	v_mfma_scale_f32_16x16x128_f8f6f4 v[92:95], v[10:17], v[186:193], v[92:95], v1, v1 op_sel_hi:[0,0,0]
	v_mfma_scale_f32_16x16x128_f8f6f4 v[84:87], v[26:33], v[186:193], v[84:87], v1, v1 op_sel_hi:[0,0,0]
	v_mfma_scale_f32_16x16x128_f8f6f4 v[76:79], v[10:17], v[206:213], v[76:79], v1, v1 op_sel_hi:[0,0,0]
	v_mfma_scale_f32_16x16x128_f8f6f4 v[68:71], v[26:33], v[206:213], v[68:71], v1, v1 op_sel_hi:[0,0,0]
	v_mfma_scale_f32_16x16x128_f8f6f4 v[60:63], v[10:17], v[214:221], v[60:63], v1, v1 op_sel_hi:[0,0,0]
	v_mfma_scale_f32_16x16x128_f8f6f4 v[52:55], v[26:33], v[214:221], v[52:55], v1, v1 op_sel_hi:[0,0,0]
	v_mfma_scale_f32_16x16x128_f8f6f4 v[44:47], v[10:17], v[242:249], v[44:47], v1, v1 op_sel_hi:[0,0,0]
	v_mfma_scale_f32_16x16x128_f8f6f4 v[36:39], v[26:33], v[242:249], v[36:39], v1, v1 op_sel_hi:[0,0,0]
	s_barrier
	s_add_u32 s2, s2, 0x100
	s_addc_u32 s3, s3, 0
	v_lshl_add_u64 v[170:171], v[170:171], 0, s[82:83]
	s_cmp_ge_i32 s64, s51
	s_mov_b32 s22, s64
	s_cbranch_scc0 .LBB0_1838

; #define PG8_STAGE(...) PG8_STAGE_(__VA_ARGS__, 0u)
; #define PG8_WAIT_V(n) asm volatile("s_waitcnt vmcnt(" #n ")" ::: "memory")
; #define PG8_WAIT_L(n) asm volatile("s_waitcnt lgkmcnt(" #n ")" ::: "memory")
; #define PG8_BAR __builtin_amdgcn_s_barrier()
; #define PG8_SCHED __builtin_amdgcn_sched_barrier(0)
; template <class Epi, class Sched, bool ALIGN_EPI = true, bool SP2 = true>
; __device__ __forceinline__ void gemm_phase(LAS unsigned char* lds, const Gemm g, const Sched& S, const Epi& E) {
;     ...
;             PG8_LDB(B0, 0, 0); PG8_LDB(B1, 0, 1); PG8_SCHED; PG8_LDA(At, 0, 0); PG8_STAGE(PG8_SA(1, 1), a1, voffAh);
;             PG8_WAIT_V(8); PG8_WAIT_L(0); PG8_BAR; PG8_MMA(0, 0, At, B0); PG8_MMA(0, 1, At, B1); PG8_BAR; PG8_SCHED;
;             if constexpr (!Epi::HALF_M) PG8_LDA(At, 0, 1); PG8_STAGE(PG8_SB(0, 0), b2, voffB); PG8_STAGE(PG8_SB(0, 1), b2, voffBh); PG8_STAGE(PG8_SA(0, 0), a2, voffA);
;             PG8_WAIT_V(8); PG8_WAIT_L(0); PG8_BAR; if constexpr (!Epi::HALF_M) { PG8_MMA(1, 0, At, B0); PG8_MMA(1, 1, At, B1); } PG8_BAR; PG8_SCHED;
.LBB0_1916:
	v_add_u32_e32 v2, s41, v183
	v_add_u32_e32 v14, s44, v183
	ds_read_b128 v[18:21], v2
	ds_read_b128 v[22:25], v2 offset:1024
	ds_read_b128 v[26:29], v2 offset:2048
	ds_read_b128 v[30:33], v2 offset:3072
	ds_read_b128 v[2:5], v14
	ds_read_b128 v[6:9], v14 offset:1024
	ds_read_b128 v[10:13], v14 offset:2048
	ds_read_b128 v[14:17], v14 offset:3072
	s_add_i32 s64, s18, 2
	s_add_u32 s65, s16, 0x80
	s_addc_u32 s19, s17, 0
	s_cmp_eq_u32 s60, s18
	s_cselect_b32 s18, s14, s65
	s_cselect_b64 vcc, -1, 0
	s_cselect_b32 s19, s15, s19
	v_cndmask_b32_e32 v173, v171, v169, vcc
	v_cndmask_b32_e32 v172, v170, v168, vcc
	v_mov_b32_e32 v34, v180
	ds_read_b128 v[188:191], v185
	ds_read_b128 v[192:195], v185 offset:1024
	ds_read_b128 v[206:209], v185 offset:2048
	ds_read_b128 v[210:213], v185 offset:3072
	ds_read_b128 v[214:217], v185 offset:4096
	ds_read_b128 v[218:221], v185 offset:5120
	ds_read_b128 v[242:245], v185 offset:6144
	ds_read_b128 v[246:249], v185 offset:7168
	s_add_i32 m0, s47, 0xc000
	s_nop 0
	global_load_lds_dwordx4 v34, s[16:17]
	v_mov_b32_e32 v34, v181
	s_add_i32 m0, s47, 0xe000
	s_nop 0
	global_load_lds_dwordx4 v34, s[16:17]
	s_waitcnt vmcnt(8)
	s_waitcnt lgkmcnt(0)
	s_barrier
	s_waitcnt lgkmcnt(0)
	v_mfma_scale_f32_16x16x128_f8f6f4 v[160:163], v[18:25], v[188:195], v[160:163], v1, v1 op_sel_hi:[0,0,0]
	v_mfma_scale_f32_16x16x128_f8f6f4 v[156:159], v[26:33], v[188:195], v[156:159], v1, v1 op_sel_hi:[0,0,0]
	v_mfma_scale_f32_16x16x128_f8f6f4 v[152:155], v[18:25], v[206:213], v[152:155], v1, v1 op_sel_hi:[0,0,0]
	v_mfma_scale_f32_16x16x128_f8f6f4 v[148:151], v[26:33], v[206:213], v[148:151], v1, v1 op_sel_hi:[0,0,0]
	v_mfma_scale_f32_16x16x128_f8f6f4 v[140:143], v[18:25], v[214:221], v[140:143], v1, v1 op_sel_hi:[0,0,0]
	v_mfma_scale_f32_16x16x128_f8f6f4 v[132:135], v[26:33], v[214:221], v[132:135], v1, v1 op_sel_hi:[0,0,0]
	v_mfma_scale_f32_16x16x128_f8f6f4 v[124:127], v[18:25], v[242:249], v[124:127], v1, v1 op_sel_hi:[0,0,0]
	v_mfma_scale_f32_16x16x128_f8f6f4 v[116:119], v[26:33], v[242:249], v[116:119], v1, v1 op_sel_hi:[0,0,0]
	v_mfma_scale_f32_16x16x128_f8f6f4 v[144:147], v[2:9], v[188:195], v[144:147], v1, v1 op_sel_hi:[0,0,0]
	v_mfma_scale_f32_16x16x128_f8f6f4 v[136:139], v[10:17], v[188:195], v[136:139], v1, v1 op_sel_hi:[0,0,0]
	v_mfma_scale_f32_16x16x128_f8f6f4 v[128:131], v[2:9], v[206:213], v[128:131], v1, v1 op_sel_hi:[0,0,0]
	v_mfma_scale_f32_16x16x128_f8f6f4 v[120:123], v[10:17], v[206:213], v[120:123], v1, v1 op_sel_hi:[0,0,0]
	v_mfma_scale_f32_16x16x128_f8f6f4 v[112:115], v[2:9], v[214:221], v[112:115], v1, v1 op_sel_hi:[0,0,0]
	v_mfma_scale_f32_16x16x128_f8f6f4 v[108:111], v[10:17], v[214:221], v[108:111], v1, v1 op_sel_hi:[0,0,0]
	v_mfma_scale_f32_16x16x128_f8f6f4 v[104:107], v[2:9], v[242:249], v[104:107], v1, v1 op_sel_hi:[0,0,0]
	v_mfma_scale_f32_16x16x128_f8f6f4 v[100:103], v[10:17], v[242:249], v[100:103], v1, v1 op_sel_hi:[0,0,0]
	s_barrier
	v_mov_b32_e32 v34, v165
	s_mov_b32 m0, s42
	ds_read_b128 v[188:191], v185 offset:16384
	ds_read_b128 v[192:195], v185 offset:17408
	ds_read_b128 v[206:209], v185 offset:18432
	ds_read_b128 v[210:213], v185 offset:19456
	ds_read_b128 v[214:217], v185 offset:20480
	ds_read_b128 v[218:221], v185 offset:21504
	ds_read_b128 v[242:245], v185 offset:22528
	ds_read_b128 v[246:249], v185 offset:23552
	v_readfirstlane_b32 s66, v172
	v_readfirstlane_b32 s67, v173
	s_nop 4
	global_load_lds_dwordx4 v34, s[66:67]
	v_mov_b32_e32 v34, v167
	s_mov_b32 m0, s43
	s_nop 0
	global_load_lds_dwordx4 v34, s[66:67]
	v_mov_b32_e32 v34, v178
	s_mov_b32 m0, s45
	s_nop 0
	global_load_lds_dwordx4 v34, s[66:67]
	v_mov_b32_e32 v34, v179
	s_mov_b32 m0, s46
	s_nop 0
	global_load_lds_dwordx4 v34, s[66:67]
	v_mov_b32_e32 v34, v164
	s_mov_b32 m0, s47
	s_nop 0
	global_load_lds_dwordx4 v34, s[18:19]
	v_mov_b32_e32 v34, v166
	s_mov_b32 m0, s48
	s_nop 0
	global_load_lds_dwordx4 v34, s[18:19]
	s_waitcnt vmcnt(8)
	s_waitcnt lgkmcnt(0)
	s_barrier
	s_waitcnt lgkmcnt(0)
	v_mfma_scale_f32_16x16x128_f8f6f4 v[96:99], v[18:25], v[188:195], v[96:99], v1, v1 op_sel_hi:[0,0,0]
	v_mfma_scale_f32_16x16x128_f8f6f4 v[92:95], v[26:33], v[188:195], v[92:95], v1, v1 op_sel_hi:[0,0,0]
	v_mfma_scale_f32_16x16x128_f8f6f4 v[88:91], v[18:25], v[206:213], v[88:91], v1, v1 op_sel_hi:[0,0,0]
	v_mfma_scale_f32_16x16x128_f8f6f4 v[84:87], v[26:33], v[206:213], v[84:87], v1, v1 op_sel_hi:[0,0,0]
	v_mfma_scale_f32_16x16x128_f8f6f4 v[76:79], v[18:25], v[214:221], v[76:79], v1, v1 op_sel_hi:[0,0,0]
	v_mfma_scale_f32_16x16x128_f8f6f4 v[68:71], v[26:33], v[214:221], v[68:71], v1, v1 op_sel_hi:[0,0,0]
	v_mfma_scale_f32_16x16x128_f8f6f4 v[60:63], v[18:25], v[242:249], v[60:63], v1, v1 op_sel_hi:[0,0,0]
	v_mfma_scale_f32_16x16x128_f8f6f4 v[52:55], v[26:33], v[242:249], v[52:55], v1, v1 op_sel_hi:[0,0,0]
	v_mfma_scale_f32_16x16x128_f8f6f4 v[80:83], v[2:9], v[188:195], v[80:83], v1, v1 op_sel_hi:[0,0,0]
	v_mfma_scale_f32_16x16x128_f8f6f4 v[72:75], v[10:17], v[188:195], v[72:75], v1, v1 op_sel_hi:[0,0,0]
	v_mfma_scale_f32_16x16x128_f8f6f4 v[64:67], v[2:9], v[206:213], v[64:67], v1, v1 op_sel_hi:[0,0,0]
	v_mfma_scale_f32_16x16x128_f8f6f4 v[56:59], v[10:17], v[206:213], v[56:59], v1, v1 op_sel_hi:[0,0,0]
	v_mfma_scale_f32_16x16x128_f8f6f4 v[48:51], v[2:9], v[214:221], v[48:51], v1, v1 op_sel_hi:[0,0,0]
	v_mfma_scale_f32_16x16x128_f8f6f4 v[44:47], v[10:17], v[214:221], v[44:47], v1, v1 op_sel_hi:[0,0,0]
	v_mfma_scale_f32_16x16x128_f8f6f4 v[40:43], v[2:9], v[242:249], v[40:43], v1, v1 op_sel_hi:[0,0,0]
	v_mfma_scale_f32_16x16x128_f8f6f4 v[36:39], v[10:17], v[242:249], v[36:39], v1, v1 op_sel_hi:[0,0,0]
	s_barrier
; #define PG8_STAGE(...) PG8_STAGE_(__VA_ARGS__, 0u)
; #define PG8_WAIT_V(n) asm volatile("s_waitcnt vmcnt(" #n ")" ::: "memory")
; #define PG8_WAIT_L(n) asm volatile("s_waitcnt lgkmcnt(" #n ")" ::: "memory")
; #define PG8_BAR __builtin_amdgcn_s_barrier()
; #define PG8_SCHED __builtin_amdgcn_sched_barrier(0)
; template <class Epi, class Sched, bool ALIGN_EPI = true, bool SP2 = true>
; __device__ __forceinline__ void gemm_phase(LAS unsigned char* lds, const Gemm g, const Sched& S, const Epi& E) {
;     ...
;             PG8_LDB(B0, 1, 0); PG8_LDB(B1, 1, 1); PG8_SCHED; PG8_LDA(At, 1, 0); PG8_STAGE(PG8_SA(0, 1), a2, voffAh);
;             PG8_WAIT_V(8); PG8_WAIT_L(0); PG8_BAR; PG8_MMA(0, 0, At, B0); PG8_MMA(0, 1, At, B1); PG8_BAR; PG8_SCHED;
;             if constexpr (!Epi::HALF_M) PG8_LDA(At, 1, 1); PG8_STAGE(PG8_SB(1, 0), b3, voffB); PG8_STAGE(PG8_SB(1, 1), b3, voffBh); PG8_STAGE(PG8_SA(1, 0), a3, voffA);
;             PG8_WAIT_V(8); PG8_WAIT_L(0); PG8_BAR; if constexpr (!Epi::HALF_M) { PG8_MMA(1, 0, At, B0); PG8_MMA(1, 1, At, B1); } PG8_BAR; PG8_SCHED;
	v_add_u32_e32 v10, s52, v183
	v_add_u32_e32 v30, s57, v183
	ds_read_b128 v[2:5], v10
	ds_read_b128 v[6:9], v10 offset:1024
	ds_read_b128 v[18:21], v10 offset:2048
	ds_read_b128 v[22:25], v10 offset:3072
	ds_read_b128 v[10:13], v30
	ds_read_b128 v[14:17], v30 offset:1024
	ds_read_b128 v[26:29], v30 offset:2048
	ds_read_b128 v[30:33], v30 offset:3072
	v_mov_b32_e32 v34, v180
	s_mov_b32 m0, s49
	ds_read_b128 v[188:191], v185 offset:32768
	ds_read_b128 v[192:195], v185 offset:33792
	ds_read_b128 v[206:209], v185 offset:34816
	ds_read_b128 v[210:213], v185 offset:35840
	ds_read_b128 v[214:217], v185 offset:36864
	ds_read_b128 v[218:221], v185 offset:37888
	ds_read_b128 v[242:245], v185 offset:38912
	ds_read_b128 v[246:249], v185 offset:39936
	s_nop 0
	global_load_lds_dwordx4 v34, s[18:19]
	v_mov_b32_e32 v34, v181
	s_mov_b32 m0, s50
	s_nop 0
	global_load_lds_dwordx4 v34, s[18:19]
	s_waitcnt vmcnt(8)
	s_waitcnt lgkmcnt(0)
	s_barrier
	s_waitcnt lgkmcnt(0)
	v_mfma_scale_f32_16x16x128_f8f6f4 v[160:163], v[2:9], v[188:195], v[160:163], v1, v1 op_sel_hi:[0,0,0]
	v_mfma_scale_f32_16x16x128_f8f6f4 v[156:159], v[18:25], v[188:195], v[156:159], v1, v1 op_sel_hi:[0,0,0]
	v_mfma_scale_f32_16x16x128_f8f6f4 v[152:155], v[2:9], v[206:213], v[152:155], v1, v1 op_sel_hi:[0,0,0]
	v_mfma_scale_f32_16x16x128_f8f6f4 v[148:151], v[18:25], v[206:213], v[148:151], v1, v1 op_sel_hi:[0,0,0]
	v_mfma_scale_f32_16x16x128_f8f6f4 v[140:143], v[2:9], v[214:221], v[140:143], v1, v1 op_sel_hi:[0,0,0]
	v_mfma_scale_f32_16x16x128_f8f6f4 v[132:135], v[18:25], v[214:221], v[132:135], v1, v1 op_sel_hi:[0,0,0]
	v_mfma_scale_f32_16x16x128_f8f6f4 v[124:127], v[2:9], v[242:249], v[124:127], v1, v1 op_sel_hi:[0,0,0]
	v_mfma_scale_f32_16x16x128_f8f6f4 v[116:119], v[18:25], v[242:249], v[116:119], v1, v1 op_sel_hi:[0,0,0]
	v_mfma_scale_f32_16x16x128_f8f6f4 v[144:147], v[10:17], v[188:195], v[144:147], v1, v1 op_sel_hi:[0,0,0]
	v_mfma_scale_f32_16x16x128_f8f6f4 v[136:139], v[26:33], v[188:195], v[136:139], v1, v1 op_sel_hi:[0,0,0]
	v_mfma_scale_f32_16x16x128_f8f6f4 v[128:131], v[10:17], v[206:213], v[128:131], v1, v1 op_sel_hi:[0,0,0]
	v_mfma_scale_f32_16x16x128_f8f6f4 v[120:123], v[26:33], v[206:213], v[120:123], v1, v1 op_sel_hi:[0,0,0]
	v_mfma_scale_f32_16x16x128_f8f6f4 v[112:115], v[10:17], v[214:221], v[112:115], v1, v1 op_sel_hi:[0,0,0]
	v_mfma_scale_f32_16x16x128_f8f6f4 v[108:111], v[26:33], v[214:221], v[108:111], v1, v1 op_sel_hi:[0,0,0]
	v_mfma_scale_f32_16x16x128_f8f6f4 v[104:107], v[10:17], v[242:249], v[104:107], v1, v1 op_sel_hi:[0,0,0]
	v_mfma_scale_f32_16x16x128_f8f6f4 v[100:103], v[26:33], v[242:249], v[100:103], v1, v1 op_sel_hi:[0,0,0]
	s_barrier
	v_mov_b32_e32 v34, v165
	ds_read_b128 v[188:191], v185 offset:49152
	ds_read_b128 v[192:195], v185 offset:50176
	ds_read_b128 v[206:209], v185 offset:51200
	ds_read_b128 v[210:213], v185 offset:52224
	ds_read_b128 v[214:217], v185 offset:53248
	ds_read_b128 v[218:221], v185 offset:54272
	ds_read_b128 v[242:245], v185 offset:55296
	ds_read_b128 v[246:249], v185 offset:56320
	s_mov_b32 m0, s53
	v_lshl_add_u64 v[174:175], v[172:173], 0, v[34:35]
	v_lshl_add_u64 v[174:175], v[174:175], 0, s[80:81]
	v_mov_b32_e32 v34, v167
	global_load_lds_dwordx4 v[174:175], off
	s_mov_b32 m0, s54
	v_lshl_add_u64 v[174:175], v[172:173], 0, v[34:35]
	v_lshl_add_u64 v[174:175], v[174:175], 0, s[80:81]
	v_mov_b32_e32 v34, v178
	global_load_lds_dwordx4 v[174:175], off
	s_mov_b32 m0, s58
	v_lshl_add_u64 v[174:175], v[172:173], 0, v[34:35]
	v_lshl_add_u64 v[174:175], v[174:175], 0, s[80:81]
	v_mov_b32_e32 v34, v179
	global_load_lds_dwordx4 v[174:175], off
	s_mov_b32 m0, s59
	v_lshl_add_u64 v[172:173], v[172:173], 0, v[34:35]
	v_lshl_add_u64 v[172:173], v[172:173], 0, s[80:81]
	v_mov_b32_e32 v34, v164
	global_load_lds_dwordx4 v[172:173], off
	s_mov_b32 m0, s55
	v_lshl_add_u64 v[172:173], s[18:19], 0, v[34:35]
	v_lshl_add_u64 v[172:173], v[172:173], 0, s[80:81]
	v_mov_b32_e32 v34, v166
	global_load_lds_dwordx4 v[172:173], off
	s_mov_b32 m0, s56
	v_lshl_add_u64 v[172:173], s[18:19], 0, v[34:35]
	v_lshl_add_u64 v[172:173], v[172:173], 0, s[80:81]
	global_load_lds_dwordx4 v[172:173], off
	s_waitcnt vmcnt(8)
	s_waitcnt lgkmcnt(0)
	s_barrier
; #define PG8_STAGE(...) PG8_STAGE_(__VA_ARGS__, 0u)
; #define PG8_WAIT_V(n) asm volatile("s_waitcnt vmcnt(" #n ")" ::: "memory")
; #define PG8_WAIT_L(n) asm volatile("s_waitcnt lgkmcnt(" #n ")" ::: "memory")
; #define PG8_BAR __builtin_amdgcn_s_barrier()
; #define PG8_SCHED __builtin_amdgcn_sched_barrier(0)
; template <class Epi, class Sched, bool ALIGN_EPI = true, bool SP2 = true>
; __device__ __forceinline__ void gemm_phase(LAS unsigned char* lds, const Gemm g, const Sched& S, const Epi& E) {
;     ...
;             PG8_WAIT_V(8); PG8_WAIT_L(0); PG8_BAR; if constexpr (!Epi::HALF_M) { PG8_MMA(1, 0, At, B0); PG8_MMA(1, 1, At, B1); } PG8_BAR; PG8_SCHED;
;             PG8_LDB(B0, 1, 0); PG8_LDB(B1, 1, 1); PG8_SCHED; PG8_LDA(At, 1, 0); PG8_STAGE(PG8_SA(0, 1), a2, voffAh);
;             PG8_WAIT_V(8); PG8_WAIT_L(0); PG8_BAR; PG8_MMA(0, 0, At, B0); PG8_MMA(0, 1, At, B1); PG8_BAR; PG8_SCHED;
;             if constexpr (!Epi::HALF_M) PG8_LDA(At, 1, 1); PG8_STAGE(PG8_SB(1, 0), b3, voffB); PG8_STAGE(PG8_SB(1, 1), b3, voffBh); PG8_STAGE(PG8_SA(1, 0), a3, voffA);
;             PG8_WAIT_V(8); PG8_WAIT_L(0); PG8_BAR; if constexpr (!Epi::HALF_M) { PG8_MMA(1, 0, At, B0); PG8_MMA(1, 1, At, B1); } PG8_BAR; PG8_SCHED;
;     __device__ __forceinline__ void operator()(const Acc& acc, const Unit& u, int wr, int wc, int fr, int fq) const {
;     ...
;             for (int m = 0; m < 4; ++m) { bf16_t* rowp = O + (size_t)(row0 + ai * HALF + m * 16) * ldc + col0;
; #pragma unroll
;                 for (int bj = 0; bj < 2; ++bj) { f32x4 v0 = acc[ai][bj][m][0], v1 = acc[ai][bj][m][1]; if (F8) { v0 = v0 * sc; v1 = v1 * sc; }
	s_waitcnt lgkmcnt(0)
	v_mfma_scale_f32_16x16x128_f8f6f4 v[96:99], v[2:9], v[188:195], v[96:99], v1, v1 op_sel_hi:[0,0,0]
	v_mfma_scale_f32_16x16x128_f8f6f4 v[92:95], v[18:25], v[188:195], v[92:95], v1, v1 op_sel_hi:[0,0,0]
	v_mfma_scale_f32_16x16x128_f8f6f4 v[88:91], v[2:9], v[206:213], v[88:91], v1, v1 op_sel_hi:[0,0,0]
	v_mfma_scale_f32_16x16x128_f8f6f4 v[84:87], v[18:25], v[206:213], v[84:87], v1, v1 op_sel_hi:[0,0,0]
	v_mfma_scale_f32_16x16x128_f8f6f4 v[76:79], v[2:9], v[214:221], v[76:79], v1, v1 op_sel_hi:[0,0,0]
	v_mfma_scale_f32_16x16x128_f8f6f4 v[68:71], v[18:25], v[214:221], v[68:71], v1, v1 op_sel_hi:[0,0,0]
	v_mfma_scale_f32_16x16x128_f8f6f4 v[60:63], v[2:9], v[242:249], v[60:63], v1, v1 op_sel_hi:[0,0,0]
	v_mfma_scale_f32_16x16x128_f8f6f4 v[52:55], v[18:25], v[242:249], v[52:55], v1, v1 op_sel_hi:[0,0,0]
	v_mfma_scale_f32_16x16x128_f8f6f4 v[80:83], v[10:17], v[188:195], v[80:83], v1, v1 op_sel_hi:[0,0,0]
	v_mfma_scale_f32_16x16x128_f8f6f4 v[72:75], v[26:33], v[188:195], v[72:75], v1, v1 op_sel_hi:[0,0,0]
	v_mfma_scale_f32_16x16x128_f8f6f4 v[64:67], v[10:17], v[206:213], v[64:67], v1, v1 op_sel_hi:[0,0,0]
	v_mfma_scale_f32_16x16x128_f8f6f4 v[56:59], v[26:33], v[206:213], v[56:59], v1, v1 op_sel_hi:[0,0,0]
	v_mfma_scale_f32_16x16x128_f8f6f4 v[48:51], v[10:17], v[214:221], v[48:51], v1, v1 op_sel_hi:[0,0,0]
	v_mfma_scale_f32_16x16x128_f8f6f4 v[44:47], v[26:33], v[214:221], v[44:47], v1, v1 op_sel_hi:[0,0,0]
	v_mfma_scale_f32_16x16x128_f8f6f4 v[40:43], v[10:17], v[242:249], v[40:43], v1, v1 op_sel_hi:[0,0,0]
	v_mfma_scale_f32_16x16x128_f8f6f4 v[36:39], v[26:33], v[242:249], v[36:39], v1, v1 op_sel_hi:[0,0,0]
	s_barrier
	s_add_u32 s16, s16, 0x100
	s_addc_u32 s17, s17, 0
	v_lshl_add_u64 v[170:171], v[170:171], 0, s[82:83]
	s_cmp_ge_i32 s64, s51
	s_mov_b32 s18, s64
	s_cbranch_scc0 .LBB0_1916
	s_mov_b32 s16, 0x3a000000
	v_pk_mul_f32 v[162:163], v[162:163], s[16:17] op_sel_hi:[1,0]
	v_pk_mul_f32 v[160:161], v[160:161], s[16:17] op_sel_hi:[1,0]
	v_pk_mul_f32 v[158:159], v[158:159], s[16:17] op_sel_hi:[1,0]
	v_pk_mul_f32 v[156:157], v[156:157], s[16:17] op_sel_hi:[1,0]
	v_pk_mul_f32 v[170:171], v[146:147], s[16:17] op_sel_hi:[1,0]
	v_pk_mul_f32 v[174:175], v[144:145], s[16:17] op_sel_hi:[1,0]
	v_pk_mul_f32 v[172:173], v[138:139], s[16:17] op_sel_hi:[1,0]
	v_pk_mul_f32 v[176:177], v[136:137], s[16:17] op_sel_hi:[1,0]
	v_pk_mul_f32 v[136:137], v[154:155], s[16:17] op_sel_hi:[1,0]
	v_pk_mul_f32 v[144:145], v[152:153], s[16:17] op_sel_hi:[1,0]
	v_pk_mul_f32 v[138:139], v[150:151], s[16:17] op_sel_hi:[1,0]
	v_pk_mul_f32 v[146:147], v[148:149], s[16:17] op_sel_hi:[1,0]
	v_pk_mul_f32 v[148:149], v[130:131], s[16:17] op_sel_hi:[1,0]
	v_pk_mul_f32 v[152:153], v[128:129], s[16:17] op_sel_hi:[1,0]
	v_pk_mul_f32 v[150:151], v[122:123], s[16:17] op_sel_hi:[1,0]
	v_pk_mul_f32 v[154:155], v[120:121], s[16:17] op_sel_hi:[1,0]
	v_pk_mul_f32 v[120:121], v[142:143], s[16:17] op_sel_hi:[1,0]
	v_pk_mul_f32 v[128:129], v[140:141], s[16:17] op_sel_hi:[1,0]
	v_pk_mul_f32 v[122:123], v[134:135], s[16:17] op_sel_hi:[1,0]
	v_pk_mul_f32 v[130:131], v[132:133], s[16:17] op_sel_hi:[1,0]
	v_pk_mul_f32 v[114:115], v[114:115], s[16:17] op_sel_hi:[1,0]
	v_pk_mul_f32 v[134:135], v[112:113], s[16:17] op_sel_hi:[1,0]
	v_pk_mul_f32 v[132:133], v[110:111], s[16:17] op_sel_hi:[1,0]
	v_pk_mul_f32 v[140:141], v[108:109], s[16:17] op_sel_hi:[1,0]
	v_pk_mul_f32 v[30:31], v[126:127], s[16:17] op_sel_hi:[1,0]
	v_pk_mul_f32 v[110:111], v[124:125], s[16:17] op_sel_hi:[1,0]
	v_pk_mul_f32 v[108:109], v[118:119], s[16:17] op_sel_hi:[1,0]
	v_pk_mul_f32 v[112:113], v[116:117], s[16:17] op_sel_hi:[1,0]
	v_pk_mul_f32 v[106:107], v[106:107], s[16:17] op_sel_hi:[1,0]
	v_pk_mul_f32 v[104:105], v[104:105], s[16:17] op_sel_hi:[1,0]
	v_pk_mul_f32 v[102:103], v[102:103], s[16:17] op_sel_hi:[1,0]
	v_pk_mul_f32 v[100:101], v[100:101], s[16:17] op_sel_hi:[1,0]
	v_pk_mul_f32 v[98:99], v[98:99], s[16:17] op_sel_hi:[1,0]
	v_pk_mul_f32 v[96:97], v[96:97], s[16:17] op_sel_hi:[1,0]
	v_pk_mul_f32 v[94:95], v[94:95], s[16:17] op_sel_hi:[1,0]
	v_pk_mul_f32 v[92:93], v[92:93], s[16:17] op_sel_hi:[1,0]
	v_pk_mul_f32 v[82:83], v[82:83], s[16:17] op_sel_hi:[1,0]
	v_pk_mul_f32 v[116:117], v[80:81], s[16:17] op_sel_hi:[1,0]
	v_pk_mul_f32 v[80:81], v[74:75], s[16:17] op_sel_hi:[1,0]
	v_pk_mul_f32 v[118:119], v[72:73], s[16:17] op_sel_hi:[1,0]
	v_pk_mul_f32 v[26:27], v[90:91], s[16:17] op_sel_hi:[1,0]
	v_pk_mul_f32 v[72:73], v[88:89], s[16:17] op_sel_hi:[1,0]
	v_pk_mul_f32 v[32:33], v[86:87], s[16:17] op_sel_hi:[1,0]
	v_pk_mul_f32 v[74:75], v[84:85], s[16:17] op_sel_hi:[1,0]
	v_pk_mul_f32 v[66:67], v[66:67], s[16:17] op_sel_hi:[1,0]
	v_pk_mul_f32 v[64:65], v[64:65], s[16:17] op_sel_hi:[1,0]
	v_pk_mul_f32 v[58:59], v[58:59], s[16:17] op_sel_hi:[1,0]
	v_pk_mul_f32 v[56:57], v[56:57], s[16:17] op_sel_hi:[1,0]
	v_pk_mul_f32 v[10:11], v[78:79], s[16:17] op_sel_hi:[1,0]
	v_pk_mul_f32 v[18:19], v[76:77], s[16:17] op_sel_hi:[1,0]
	v_pk_mul_f32 v[14:15], v[70:71], s[16:17] op_sel_hi:[1,0]
	v_pk_mul_f32 v[22:23], v[68:69], s[16:17] op_sel_hi:[1,0]
	v_pk_mul_f32 v[28:29], v[50:51], s[16:17] op_sel_hi:[1,0]
	v_pk_mul_f32 v[48:49], v[48:49], s[16:17] op_sel_hi:[1,0]
	v_pk_mul_f32 v[46:47], v[46:47], s[16:17] op_sel_hi:[1,0]
	v_pk_mul_f32 v[44:45], v[44:45], s[16:17] op_sel_hi:[1,0]
	v_pk_mul_f32 v[2:3], v[62:63], s[16:17] op_sel_hi:[1,0]
	v_pk_mul_f32 v[6:7], v[60:61], s[16:17] op_sel_hi:[1,0]
	v_pk_mul_f32 v[4:5], v[54:55], s[16:17] op_sel_hi:[1,0]
	v_pk_mul_f32 v[8:9], v[52:53], s[16:17] op_sel_hi:[1,0]
	v_pk_mul_f32 v[12:13], v[42:43], s[16:17] op_sel_hi:[1,0]
	v_pk_mul_f32 v[20:21], v[40:41], s[16:17] op_sel_hi:[1,0]
	v_pk_mul_f32 v[16:17], v[38:39], s[16:17] op_sel_hi:[1,0]
	v_pk_mul_f32 v[24:25], v[36:37], s[16:17] op_sel_hi:[1,0]

; #define PG8_STAGE(...) PG8_STAGE_(__VA_ARGS__, 0u)
; #define PG8_WAIT_V(n) asm volatile("s_waitcnt vmcnt(" #n ")" ::: "memory")
; #define PG8_WAIT_L(n) asm volatile("s_waitcnt lgkmcnt(" #n ")" ::: "memory")
; #define PG8_BAR __builtin_amdgcn_s_barrier()
; #define PG8_SCHED __builtin_amdgcn_sched_barrier(0)
; template <class Epi, class Sched, bool ALIGN_EPI = true, bool SP2 = true>
; __device__ __forceinline__ void gemm_phase(LAS unsigned char* lds, const Gemm g, const Sched& S, const Epi& E) {
;     ...
;             PG8_LDB(B0, 0, 0); PG8_LDB(B1, 0, 1); PG8_SCHED; PG8_LDA(At, 0, 0); PG8_STAGE(PG8_SA(1, 1), a1, voffAh);
;             PG8_WAIT_V(8); PG8_WAIT_L(0); PG8_BAR; PG8_MMA(0, 0, At, B0); PG8_MMA(0, 1, At, B1); PG8_BAR; PG8_SCHED;
;             if constexpr (!Epi::HALF_M) PG8_LDA(At, 0, 1); PG8_STAGE(PG8_SB(0, 0), b2, voffB); PG8_STAGE(PG8_SB(0, 1), b2, voffBh); PG8_STAGE(PG8_SA(0, 0), a2, voffA);
;             PG8_WAIT_V(8); PG8_WAIT_L(0); PG8_BAR; if constexpr (!Epi::HALF_M) { PG8_MMA(1, 0, At, B0); PG8_MMA(1, 1, At, B1); } PG8_BAR; PG8_SCHED;
;             PG8_LDB(B0, 1, 0); PG8_LDB(B1, 1, 1); PG8_SCHED; PG8_LDA(At, 1, 0); PG8_STAGE(PG8_SA(0, 1), a2, voffAh);
;             PG8_WAIT_V(8); PG8_WAIT_L(0); PG8_BAR; PG8_MMA(0, 0, At, B0); PG8_MMA(0, 1, At, B1); PG8_BAR; PG8_SCHED;
.LBB0_1941:
	v_add_u32_e32 v34, s11, v76
	ds_read_b128 v[88:91], v34
	ds_read_b128 v[92:95], v34 offset:1024
	ds_read_b128 v[96:99], v34 offset:2048
	ds_read_b128 v[100:103], v34 offset:3072
	v_add_u32_e32 v34, s14, v76
	ds_read_b128 v[104:107], v34
	ds_read_b128 v[108:111], v34 offset:1024
	ds_read_b128 v[112:115], v34 offset:2048
	ds_read_b128 v[116:119], v34 offset:3072
	s_add_i32 s20, s6, 2
	s_add_u32 s7, s4, 0xd6600080
	s_addc_u32 s35, s5, -1
	s_cmp_lg_u32 s34, s6
	s_cselect_b32 s36, s7, 0
	s_cselect_b32 s37, s35, 0
	s_add_u32 s6, s0, s36
	s_addc_u32 s7, s1, s37
	v_lshl_add_u64 v[74:75], v[72:73], 0, s[36:37]
	s_add_i32 m0, s17, 0xc000
	v_mov_b32_e32 v34, v68
	s_add_u32 s36, s21, s4
	ds_read_b128 v[120:123], v77
	ds_read_b128 v[124:127], v77 offset:1024
	ds_read_b128 v[128:131], v77 offset:2048
	ds_read_b128 v[132:135], v77 offset:3072
	ds_read_b128 v[136:139], v77 offset:4096
	ds_read_b128 v[140:143], v77 offset:5120
	ds_read_b128 v[144:147], v77 offset:6144
	ds_read_b128 v[148:151], v77 offset:7168
	s_addc_u32 s37, s22, s5
	global_load_lds_dwordx4 v34, s[36:37]
	v_mov_b32_e32 v34, v70
	s_add_i32 m0, s17, 0xe000
	s_nop 0
	global_load_lds_dwordx4 v34, s[36:37]
	s_waitcnt vmcnt(8)
	s_waitcnt lgkmcnt(0)
	s_barrier
	s_waitcnt lgkmcnt(0)
	v_mfma_scale_f32_16x16x128_f8f6f4 v[64:67], v[88:95], v[120:127], v[64:67], v1, v1 op_sel_hi:[0,0,0]
	v_mfma_scale_f32_16x16x128_f8f6f4 v[60:63], v[96:103], v[120:127], v[60:63], v1, v1 op_sel_hi:[0,0,0]
	v_mfma_scale_f32_16x16x128_f8f6f4 v[56:59], v[88:95], v[128:135], v[56:59], v1, v1 op_sel_hi:[0,0,0]
	v_mfma_scale_f32_16x16x128_f8f6f4 v[52:55], v[96:103], v[128:135], v[52:55], v1, v1 op_sel_hi:[0,0,0]
	v_mfma_scale_f32_16x16x128_f8f6f4 v[44:47], v[88:95], v[136:143], v[44:47], v1, v1 op_sel_hi:[0,0,0]
	v_mfma_scale_f32_16x16x128_f8f6f4 v[36:39], v[96:103], v[136:143], v[36:39], v1, v1 op_sel_hi:[0,0,0]
	v_mfma_scale_f32_16x16x128_f8f6f4 v[26:29], v[88:95], v[144:151], v[26:29], v1, v1 op_sel_hi:[0,0,0]
	v_mfma_scale_f32_16x16x128_f8f6f4 v[18:21], v[96:103], v[144:151], v[18:21], v1, v1 op_sel_hi:[0,0,0]
	v_mfma_scale_f32_16x16x128_f8f6f4 v[48:51], v[104:111], v[120:127], v[48:51], v1, v1 op_sel_hi:[0,0,0]
	v_mfma_scale_f32_16x16x128_f8f6f4 v[40:43], v[112:119], v[120:127], v[40:43], v1, v1 op_sel_hi:[0,0,0]
	v_mfma_scale_f32_16x16x128_f8f6f4 v[30:33], v[104:111], v[128:135], v[30:33], v1, v1 op_sel_hi:[0,0,0]
	v_mfma_scale_f32_16x16x128_f8f6f4 v[22:25], v[112:119], v[128:135], v[22:25], v1, v1 op_sel_hi:[0,0,0]
	v_mfma_scale_f32_16x16x128_f8f6f4 v[14:17], v[104:111], v[136:143], v[14:17], v1, v1 op_sel_hi:[0,0,0]
	v_mfma_scale_f32_16x16x128_f8f6f4 v[10:13], v[112:119], v[136:143], v[10:13], v1, v1 op_sel_hi:[0,0,0]
	v_mfma_scale_f32_16x16x128_f8f6f4 v[6:9], v[104:111], v[144:151], v[6:9], v1, v1 op_sel_hi:[0,0,0]
	v_mfma_scale_f32_16x16x128_f8f6f4 v[2:5], v[112:119], v[144:151], v[2:5], v1, v1 op_sel_hi:[0,0,0]
	s_barrier
	v_mov_b32_e32 v34, v83
	s_mov_b32 m0, s12
	v_readfirstlane_b32 s36, v74
	v_readfirstlane_b32 s37, v75
	s_nop 4
	global_load_lds_dwordx4 v34, s[36:37]
	v_mov_b32_e32 v34, v84
	s_mov_b32 m0, s13
	s_nop 0
	global_load_lds_dwordx4 v34, s[36:37]
	v_mov_b32_e32 v34, v85
	s_mov_b32 m0, s15
	s_nop 0
	global_load_lds_dwordx4 v34, s[36:37]
	v_mov_b32_e32 v34, v86
	s_mov_b32 m0, s16
	s_nop 0
	global_load_lds_dwordx4 v34, s[36:37]
	v_mov_b32_e32 v34, v68
	s_mov_b32 m0, s17
	s_nop 0
	global_load_lds_dwordx4 v34, s[6:7]
	v_mov_b32_e32 v34, v70
	s_mov_b32 m0, s18
	s_nop 0
	global_load_lds_dwordx4 v34, s[6:7]
	s_waitcnt vmcnt(8)
	s_waitcnt lgkmcnt(0)
	s_barrier
	s_barrier
	v_add_u32_e32 v34, s24, v76
	ds_read_b128 v[88:91], v34
	ds_read_b128 v[92:95], v34 offset:1024
	ds_read_b128 v[96:99], v34 offset:2048
	ds_read_b128 v[100:103], v34 offset:3072
	v_add_u32_e32 v34, s29, v76
	ds_read_b128 v[104:107], v34
	ds_read_b128 v[108:111], v34 offset:1024
	ds_read_b128 v[112:115], v34 offset:2048
	ds_read_b128 v[116:119], v34 offset:3072
	v_mov_b32_e32 v34, v68
	s_mov_b32 m0, s19
	ds_read_b128 v[120:123], v77 offset:32768
	ds_read_b128 v[124:127], v77 offset:33792
	ds_read_b128 v[128:131], v77 offset:34816
	ds_read_b128 v[132:135], v77 offset:35840
	ds_read_b128 v[136:139], v77 offset:36864
	ds_read_b128 v[140:143], v77 offset:37888
	ds_read_b128 v[144:147], v77 offset:38912
	ds_read_b128 v[148:151], v77 offset:39936
	s_nop 0
	global_load_lds_dwordx4 v34, s[6:7]
	v_mov_b32_e32 v34, v70
	s_mov_b32 m0, s23
	s_nop 0
	global_load_lds_dwordx4 v34, s[6:7]
	s_waitcnt vmcnt(8)
	s_waitcnt lgkmcnt(0)
	s_barrier
; #define PG8_STAGE(...) PG8_STAGE_(__VA_ARGS__, 0u)
; #define PG8_WAIT_V(n) asm volatile("s_waitcnt vmcnt(" #n ")" ::: "memory")
; #define PG8_WAIT_L(n) asm volatile("s_waitcnt lgkmcnt(" #n ")" ::: "memory")
; #define PG8_BAR __builtin_amdgcn_s_barrier()
; #define PG8_SCHED __builtin_amdgcn_sched_barrier(0)
; template <class Epi, class Sched, bool ALIGN_EPI = true, bool SP2 = true>
; __device__ __forceinline__ void gemm_phase(LAS unsigned char* lds, const Gemm g, const Sched& S, const Epi& E) {
;     ...
;             PG8_WAIT_V(8); PG8_WAIT_L(0); PG8_BAR; PG8_MMA(0, 0, At, B0); PG8_MMA(0, 1, At, B1); PG8_BAR; PG8_SCHED;
;             if constexpr (!Epi::HALF_M) PG8_LDA(At, 1, 1); PG8_STAGE(PG8_SB(1, 0), b3, voffB); PG8_STAGE(PG8_SB(1, 1), b3, voffBh); PG8_STAGE(PG8_SA(1, 0), a3, voffA);
;             PG8_WAIT_V(8); PG8_WAIT_L(0); PG8_BAR; if constexpr (!Epi::HALF_M) { PG8_MMA(1, 0, At, B0); PG8_MMA(1, 1, At, B1); } PG8_BAR; PG8_SCHED;
;     __device__ __forceinline__ void operator()(Acc& acc, const Unit& u, int wr, int wc, int fr, int fq) const {
;     ...
;         for (int m = 0; m < 4; ++m) { bf16_t* rowp = O + (size_t)(row0 + m * 16) * ldc + col0;
; #pragma unroll
;             for (int bj = 0; bj < 2; ++bj) { f32x4 v0 = acc[0][bj][m][0], v1 = acc[0][bj][m][1]; if (F8) { v0 = v0 * sc; v1 = v1 * sc; }
	s_waitcnt lgkmcnt(0)
	v_mfma_scale_f32_16x16x128_f8f6f4 v[64:67], v[88:95], v[120:127], v[64:67], v1, v1 op_sel_hi:[0,0,0]
	v_mfma_scale_f32_16x16x128_f8f6f4 v[60:63], v[96:103], v[120:127], v[60:63], v1, v1 op_sel_hi:[0,0,0]
	v_mfma_scale_f32_16x16x128_f8f6f4 v[56:59], v[88:95], v[128:135], v[56:59], v1, v1 op_sel_hi:[0,0,0]
	v_mfma_scale_f32_16x16x128_f8f6f4 v[52:55], v[96:103], v[128:135], v[52:55], v1, v1 op_sel_hi:[0,0,0]
	v_mfma_scale_f32_16x16x128_f8f6f4 v[44:47], v[88:95], v[136:143], v[44:47], v1, v1 op_sel_hi:[0,0,0]
	v_mfma_scale_f32_16x16x128_f8f6f4 v[36:39], v[96:103], v[136:143], v[36:39], v1, v1 op_sel_hi:[0,0,0]
	v_mfma_scale_f32_16x16x128_f8f6f4 v[26:29], v[88:95], v[144:151], v[26:29], v1, v1 op_sel_hi:[0,0,0]
	v_mfma_scale_f32_16x16x128_f8f6f4 v[18:21], v[96:103], v[144:151], v[18:21], v1, v1 op_sel_hi:[0,0,0]
	v_mfma_scale_f32_16x16x128_f8f6f4 v[48:51], v[104:111], v[120:127], v[48:51], v1, v1 op_sel_hi:[0,0,0]
	v_mfma_scale_f32_16x16x128_f8f6f4 v[40:43], v[112:119], v[120:127], v[40:43], v1, v1 op_sel_hi:[0,0,0]
	v_mfma_scale_f32_16x16x128_f8f6f4 v[30:33], v[104:111], v[128:135], v[30:33], v1, v1 op_sel_hi:[0,0,0]
	v_mfma_scale_f32_16x16x128_f8f6f4 v[22:25], v[112:119], v[128:135], v[22:25], v1, v1 op_sel_hi:[0,0,0]
	v_mfma_scale_f32_16x16x128_f8f6f4 v[14:17], v[104:111], v[136:143], v[14:17], v1, v1 op_sel_hi:[0,0,0]
	v_mfma_scale_f32_16x16x128_f8f6f4 v[10:13], v[112:119], v[136:143], v[10:13], v1, v1 op_sel_hi:[0,0,0]
	v_mfma_scale_f32_16x16x128_f8f6f4 v[6:9], v[104:111], v[144:151], v[6:9], v1, v1 op_sel_hi:[0,0,0]
	v_mfma_scale_f32_16x16x128_f8f6f4 v[2:5], v[112:119], v[144:151], v[2:5], v1, v1 op_sel_hi:[0,0,0]
	s_barrier
	v_mov_b32_e32 v34, v83
	s_mov_b32 m0, s25
	v_lshl_add_u64 v[78:79], v[74:75], 0, v[34:35]
	v_lshl_add_u64 v[78:79], v[78:79], 0, s[80:81]
	v_mov_b32_e32 v34, v84
	global_load_lds_dwordx4 v[78:79], off
	s_mov_b32 m0, s26
	v_lshl_add_u64 v[78:79], v[74:75], 0, v[34:35]
	v_lshl_add_u64 v[78:79], v[78:79], 0, s[80:81]
	v_mov_b32_e32 v34, v85
	global_load_lds_dwordx4 v[78:79], off
	s_mov_b32 m0, s30
	v_lshl_add_u64 v[78:79], v[74:75], 0, v[34:35]
	v_lshl_add_u64 v[78:79], v[78:79], 0, s[80:81]
	v_mov_b32_e32 v34, v86
	global_load_lds_dwordx4 v[78:79], off
	s_mov_b32 m0, s31
	v_lshl_add_u64 v[74:75], v[74:75], 0, v[34:35]
	v_lshl_add_u64 v[74:75], v[74:75], 0, s[80:81]
	v_mov_b32_e32 v34, v68
	global_load_lds_dwordx4 v[74:75], off
	s_mov_b32 m0, s27
	v_lshl_add_u64 v[74:75], s[6:7], 0, v[34:35]
	v_lshl_add_u64 v[74:75], v[74:75], 0, s[80:81]
	v_mov_b32_e32 v34, v70
	global_load_lds_dwordx4 v[74:75], off
	s_mov_b32 m0, s28
	v_lshl_add_u64 v[74:75], s[6:7], 0, v[34:35]
	v_lshl_add_u64 v[74:75], v[74:75], 0, s[80:81]
	global_load_lds_dwordx4 v[74:75], off
	s_waitcnt vmcnt(8)
	s_waitcnt lgkmcnt(0)
	s_barrier
	s_barrier
	s_add_u32 s4, s4, 0x100
	s_addc_u32 s5, s5, 0
	s_cmp_ge_i32 s20, s33
	s_mov_b32 s6, s20
	s_cbranch_scc0 .LBB0_1941
	s_mov_b32 s0, 0x3a000000
	v_pk_mul_f32 v[66:67], v[66:67], s[0:1] op_sel_hi:[1,0]
	v_pk_mul_f32 v[64:65], v[64:65], s[0:1] op_sel_hi:[1,0]
	v_pk_mul_f32 v[62:63], v[62:63], s[0:1] op_sel_hi:[1,0]
	v_pk_mul_f32 v[60:61], v[60:61], s[0:1] op_sel_hi:[1,0]
	v_pk_mul_f32 v[74:75], v[50:51], s[0:1] op_sel_hi:[1,0]
	v_pk_mul_f32 v[78:79], v[48:49], s[0:1] op_sel_hi:[1,0]
	v_pk_mul_f32 v[76:77], v[42:43], s[0:1] op_sel_hi:[1,0]
	v_pk_mul_f32 v[80:81], v[40:41], s[0:1] op_sel_hi:[1,0]
	v_pk_mul_f32 v[40:41], v[58:59], s[0:1] op_sel_hi:[1,0]
	v_pk_mul_f32 v[48:49], v[56:57], s[0:1] op_sel_hi:[1,0]
	v_pk_mul_f32 v[42:43], v[54:55], s[0:1] op_sel_hi:[1,0]
	v_pk_mul_f32 v[50:51], v[52:53], s[0:1] op_sel_hi:[1,0]
	v_pk_mul_f32 v[52:53], v[32:33], s[0:1] op_sel_hi:[1,0]
	v_pk_mul_f32 v[56:57], v[30:31], s[0:1] op_sel_hi:[1,0]
	v_pk_mul_f32 v[54:55], v[24:25], s[0:1] op_sel_hi:[1,0]
	v_pk_mul_f32 v[58:59], v[22:23], s[0:1] op_sel_hi:[1,0]
	v_pk_mul_f32 v[22:23], v[46:47], s[0:1] op_sel_hi:[1,0]
	v_pk_mul_f32 v[30:31], v[44:45], s[0:1] op_sel_hi:[1,0]
	v_pk_mul_f32 v[24:25], v[38:39], s[0:1] op_sel_hi:[1,0]
	v_pk_mul_f32 v[32:33], v[36:37], s[0:1] op_sel_hi:[1,0]
	v_pk_mul_f32 v[36:37], v[16:17], s[0:1] op_sel_hi:[1,0]
	v_pk_mul_f32 v[44:45], v[14:15], s[0:1] op_sel_hi:[1,0]
	v_pk_mul_f32 v[38:39], v[12:13], s[0:1] op_sel_hi:[1,0]
	v_pk_mul_f32 v[46:47], v[10:11], s[0:1] op_sel_hi:[1,0]
	v_pk_mul_f32 v[10:11], v[28:29], s[0:1] op_sel_hi:[1,0]
	v_pk_mul_f32 v[14:15], v[26:27], s[0:1] op_sel_hi:[1,0]
	v_pk_mul_f32 v[12:13], v[20:21], s[0:1] op_sel_hi:[1,0]
	v_pk_mul_f32 v[16:17], v[18:19], s[0:1] op_sel_hi:[1,0]
	v_pk_mul_f32 v[8:9], v[8:9], s[0:1] op_sel_hi:[1,0]
	v_pk_mul_f32 v[6:7], v[6:7], s[0:1] op_sel_hi:[1,0]
	v_pk_mul_f32 v[4:5], v[4:5], s[0:1] op_sel_hi:[1,0]
	v_pk_mul_f32 v[2:3], v[2:3], s[0:1] op_sel_hi:[1,0]

; #define PG8_STAGE(...) PG8_STAGE_(__VA_ARGS__, 0u)
; #define PG8_WAIT_V(n) asm volatile("s_waitcnt vmcnt(" #n ")" ::: "memory")
; #define PG8_WAIT_L(n) asm volatile("s_waitcnt lgkmcnt(" #n ")" ::: "memory")
; #define PG8_BAR __builtin_amdgcn_s_barrier()
; #define PG8_SCHED __builtin_amdgcn_sched_barrier(0)
; template <class Epi, class Sched, bool ALIGN_EPI = true, bool SP2 = true>
; __device__ __forceinline__ void gemm_phase(LAS unsigned char* lds, const Gemm g, const Sched& S, const Epi& E) {
;     ...
;             PG8_LDB(B0, 0, 0); PG8_LDB(B1, 0, 1); PG8_SCHED; PG8_LDA(At, 0, 0); PG8_STAGE(PG8_SA(1, 1), a1, voffAh);
;             PG8_WAIT_V(8); PG8_WAIT_L(0); PG8_BAR; PG8_MMA(0, 0, At, B0); PG8_MMA(0, 1, At, B1); PG8_BAR; PG8_SCHED;
;             if constexpr (!Epi::HALF_M) PG8_LDA(At, 0, 1); PG8_STAGE(PG8_SB(0, 0), b2, voffB); PG8_STAGE(PG8_SB(0, 1), b2, voffBh); PG8_STAGE(PG8_SA(0, 0), a2, voffA);
;             PG8_WAIT_V(8); PG8_WAIT_L(0); PG8_BAR; if constexpr (!Epi::HALF_M) { PG8_MMA(1, 0, At, B0); PG8_MMA(1, 1, At, B1); } PG8_BAR; PG8_SCHED;
.LBB0_2143:
	v_add_u32_e32 v2, s19, v173
	v_add_u32_e32 v14, s40, v173
	ds_read_b128 v[18:21], v2
	ds_read_b128 v[22:25], v2 offset:1024
	ds_read_b128 v[26:29], v2 offset:2048
	ds_read_b128 v[30:33], v2 offset:3072
	ds_read_b128 v[2:5], v14
	ds_read_b128 v[6:9], v14 offset:1024
	ds_read_b128 v[10:13], v14 offset:2048
	ds_read_b128 v[14:17], v14 offset:3072
	s_add_i32 s64, s22, 2
	s_add_u32 s24, s20, 0x80
	s_addc_u32 s23, s21, 0
	s_cmp_eq_u32 s56, s22
	s_cselect_b32 s22, s13, s24
	s_cselect_b32 s23, s11, s23
	s_cselect_b32 s25, s60, s63
	s_cselect_b32 s24, s61, s62
	v_mov_b32_e32 v34, v170
	ds_read_b128 v[176:179], v175
	ds_read_b128 v[180:183], v175 offset:1024
	ds_read_b128 v[184:187], v175 offset:2048
	ds_read_b128 v[188:191], v175 offset:3072
	ds_read_b128 v[206:209], v175 offset:4096
	ds_read_b128 v[210:213], v175 offset:5120
	ds_read_b128 v[214:217], v175 offset:6144
	ds_read_b128 v[218:221], v175 offset:7168
	s_add_i32 m0, s43, 0xc000
	s_nop 0
	global_load_lds_dwordx4 v34, s[20:21]
	v_mov_b32_e32 v34, v171
	s_add_i32 m0, s43, 0xe000
	s_nop 0
	global_load_lds_dwordx4 v34, s[20:21]
	s_waitcnt vmcnt(8)
	s_waitcnt lgkmcnt(0)
	s_barrier
	s_waitcnt lgkmcnt(0)
	v_mfma_scale_f32_16x16x128_f8f6f4 v[156:159], v[18:25], v[176:183], v[156:159], v1, v1 op_sel_hi:[0,0,0]
	v_mfma_scale_f32_16x16x128_f8f6f4 v[152:155], v[26:33], v[176:183], v[152:155], v1, v1 op_sel_hi:[0,0,0]
	v_mfma_scale_f32_16x16x128_f8f6f4 v[144:147], v[18:25], v[184:191], v[144:147], v1, v1 op_sel_hi:[0,0,0]
	v_mfma_scale_f32_16x16x128_f8f6f4 v[136:139], v[26:33], v[184:191], v[136:139], v1, v1 op_sel_hi:[0,0,0]
	v_mfma_scale_f32_16x16x128_f8f6f4 v[128:131], v[18:25], v[206:213], v[128:131], v1, v1 op_sel_hi:[0,0,0]
	v_mfma_scale_f32_16x16x128_f8f6f4 v[120:123], v[26:33], v[206:213], v[120:123], v1, v1 op_sel_hi:[0,0,0]
	v_mfma_scale_f32_16x16x128_f8f6f4 v[112:115], v[18:25], v[214:221], v[112:115], v1, v1 op_sel_hi:[0,0,0]
	v_mfma_scale_f32_16x16x128_f8f6f4 v[104:107], v[26:33], v[214:221], v[104:107], v1, v1 op_sel_hi:[0,0,0]
	v_mfma_scale_f32_16x16x128_f8f6f4 v[160:163], v[2:9], v[176:183], v[160:163], v1, v1 op_sel_hi:[0,0,0]
	v_mfma_scale_f32_16x16x128_f8f6f4 v[148:151], v[10:17], v[176:183], v[148:151], v1, v1 op_sel_hi:[0,0,0]
	v_mfma_scale_f32_16x16x128_f8f6f4 v[140:143], v[2:9], v[184:191], v[140:143], v1, v1 op_sel_hi:[0,0,0]
	v_mfma_scale_f32_16x16x128_f8f6f4 v[132:135], v[10:17], v[184:191], v[132:135], v1, v1 op_sel_hi:[0,0,0]
	v_mfma_scale_f32_16x16x128_f8f6f4 v[124:127], v[2:9], v[206:213], v[124:127], v1, v1 op_sel_hi:[0,0,0]
	v_mfma_scale_f32_16x16x128_f8f6f4 v[116:119], v[10:17], v[206:213], v[116:119], v1, v1 op_sel_hi:[0,0,0]
	v_mfma_scale_f32_16x16x128_f8f6f4 v[108:111], v[2:9], v[214:221], v[108:111], v1, v1 op_sel_hi:[0,0,0]
	v_mfma_scale_f32_16x16x128_f8f6f4 v[100:103], v[10:17], v[214:221], v[100:103], v1, v1 op_sel_hi:[0,0,0]
	s_barrier
	v_mov_b32_e32 v34, v165
	s_mov_b32 m0, s38
	ds_read_b128 v[176:179], v175 offset:16384
	ds_read_b128 v[180:183], v175 offset:17408
	ds_read_b128 v[184:187], v175 offset:18432
	ds_read_b128 v[188:191], v175 offset:19456
	ds_read_b128 v[206:209], v175 offset:20480
	ds_read_b128 v[210:213], v175 offset:21504
	ds_read_b128 v[214:217], v175 offset:22528
	ds_read_b128 v[218:221], v175 offset:23552
	s_nop 0
	global_load_lds_dwordx4 v34, s[24:25]
	v_mov_b32_e32 v34, v167
	s_mov_b32 m0, s39
	s_nop 0
	global_load_lds_dwordx4 v34, s[24:25]
	v_mov_b32_e32 v34, v168
	s_mov_b32 m0, s41
	s_nop 0
	global_load_lds_dwordx4 v34, s[24:25]
	v_mov_b32_e32 v34, v169
	s_mov_b32 m0, s42
	s_nop 0
	global_load_lds_dwordx4 v34, s[24:25]
	v_mov_b32_e32 v34, v164
	s_mov_b32 m0, s43
	s_nop 0
	global_load_lds_dwordx4 v34, s[22:23]
	v_mov_b32_e32 v34, v166
	s_mov_b32 m0, s44
	s_nop 0
	global_load_lds_dwordx4 v34, s[22:23]
	s_waitcnt vmcnt(8)
	s_waitcnt lgkmcnt(0)
	s_barrier
	s_waitcnt lgkmcnt(0)
	v_mfma_scale_f32_16x16x128_f8f6f4 v[96:99], v[18:25], v[176:183], v[96:99], v1, v1 op_sel_hi:[0,0,0]
	v_mfma_scale_f32_16x16x128_f8f6f4 v[88:91], v[26:33], v[176:183], v[88:91], v1, v1 op_sel_hi:[0,0,0]
	v_mfma_scale_f32_16x16x128_f8f6f4 v[80:83], v[18:25], v[184:191], v[80:83], v1, v1 op_sel_hi:[0,0,0]
	v_mfma_scale_f32_16x16x128_f8f6f4 v[72:75], v[26:33], v[184:191], v[72:75], v1, v1 op_sel_hi:[0,0,0]
	v_mfma_scale_f32_16x16x128_f8f6f4 v[64:67], v[18:25], v[206:213], v[64:67], v1, v1 op_sel_hi:[0,0,0]
	v_mfma_scale_f32_16x16x128_f8f6f4 v[56:59], v[26:33], v[206:213], v[56:59], v1, v1 op_sel_hi:[0,0,0]
	v_mfma_scale_f32_16x16x128_f8f6f4 v[48:51], v[18:25], v[214:221], v[48:51], v1, v1 op_sel_hi:[0,0,0]
	v_mfma_scale_f32_16x16x128_f8f6f4 v[40:43], v[26:33], v[214:221], v[40:43], v1, v1 op_sel_hi:[0,0,0]
	v_mfma_scale_f32_16x16x128_f8f6f4 v[92:95], v[2:9], v[176:183], v[92:95], v1, v1 op_sel_hi:[0,0,0]
	v_mfma_scale_f32_16x16x128_f8f6f4 v[84:87], v[10:17], v[176:183], v[84:87], v1, v1 op_sel_hi:[0,0,0]
	v_mfma_scale_f32_16x16x128_f8f6f4 v[76:79], v[2:9], v[184:191], v[76:79], v1, v1 op_sel_hi:[0,0,0]
	v_mfma_scale_f32_16x16x128_f8f6f4 v[68:71], v[10:17], v[184:191], v[68:71], v1, v1 op_sel_hi:[0,0,0]
	v_mfma_scale_f32_16x16x128_f8f6f4 v[60:63], v[2:9], v[206:213], v[60:63], v1, v1 op_sel_hi:[0,0,0]
	v_mfma_scale_f32_16x16x128_f8f6f4 v[52:55], v[10:17], v[206:213], v[52:55], v1, v1 op_sel_hi:[0,0,0]
	v_mfma_scale_f32_16x16x128_f8f6f4 v[44:47], v[2:9], v[214:221], v[44:47], v1, v1 op_sel_hi:[0,0,0]
	v_mfma_scale_f32_16x16x128_f8f6f4 v[36:39], v[10:17], v[214:221], v[36:39], v1, v1 op_sel_hi:[0,0,0]
	s_barrier
; #define PG8_STAGE(...) PG8_STAGE_(__VA_ARGS__, 0u)
; #define PG8_WAIT_V(n) asm volatile("s_waitcnt vmcnt(" #n ")" ::: "memory")
; #define PG8_WAIT_L(n) asm volatile("s_waitcnt lgkmcnt(" #n ")" ::: "memory")
; #define PG8_BAR __builtin_amdgcn_s_barrier()
; #define PG8_SCHED __builtin_amdgcn_sched_barrier(0)
; template <class Epi, class Sched, bool ALIGN_EPI = true, bool SP2 = true>
; __device__ __forceinline__ void gemm_phase(LAS unsigned char* lds, const Gemm g, const Sched& S, const Epi& E) {
;     ...
;             PG8_LDB(B0, 1, 0); PG8_LDB(B1, 1, 1); PG8_SCHED; PG8_LDA(At, 1, 0); PG8_STAGE(PG8_SA(0, 1), a2, voffAh);
;             PG8_WAIT_V(8); PG8_WAIT_L(0); PG8_BAR; PG8_MMA(0, 0, At, B0); PG8_MMA(0, 1, At, B1); PG8_BAR; PG8_SCHED;
;             if constexpr (!Epi::HALF_M) PG8_LDA(At, 1, 1); PG8_STAGE(PG8_SB(1, 0), b3, voffB); PG8_STAGE(PG8_SB(1, 1), b3, voffBh); PG8_STAGE(PG8_SA(1, 0), a3, voffA);
;             PG8_WAIT_V(8); PG8_WAIT_L(0); PG8_BAR; if constexpr (!Epi::HALF_M) { PG8_MMA(1, 0, At, B0); PG8_MMA(1, 1, At, B1); } PG8_BAR; PG8_SCHED;
	v_add_u32_e32 v10, s48, v173
	v_add_u32_e32 v30, s53, v173
	ds_read_b128 v[2:5], v10
	ds_read_b128 v[6:9], v10 offset:1024
	ds_read_b128 v[18:21], v10 offset:2048
	ds_read_b128 v[22:25], v10 offset:3072
	ds_read_b128 v[10:13], v30
	ds_read_b128 v[14:17], v30 offset:1024
	ds_read_b128 v[26:29], v30 offset:2048
	ds_read_b128 v[30:33], v30 offset:3072
	v_mov_b32_e32 v34, v170
	s_mov_b32 m0, s45
	ds_read_b128 v[176:179], v175 offset:32768
	ds_read_b128 v[180:183], v175 offset:33792
	ds_read_b128 v[184:187], v175 offset:34816
	ds_read_b128 v[188:191], v175 offset:35840
	ds_read_b128 v[206:209], v175 offset:36864
	ds_read_b128 v[210:213], v175 offset:37888
	ds_read_b128 v[214:217], v175 offset:38912
	ds_read_b128 v[218:221], v175 offset:39936
	s_nop 0
	global_load_lds_dwordx4 v34, s[22:23]
	v_mov_b32_e32 v34, v171
	s_mov_b32 m0, s46
	s_nop 0
	global_load_lds_dwordx4 v34, s[22:23]
	s_waitcnt vmcnt(8)
	s_waitcnt lgkmcnt(0)
	s_barrier
	s_waitcnt lgkmcnt(0)
	v_mfma_scale_f32_16x16x128_f8f6f4 v[156:159], v[2:9], v[176:183], v[156:159], v1, v1 op_sel_hi:[0,0,0]
	v_mfma_scale_f32_16x16x128_f8f6f4 v[152:155], v[18:25], v[176:183], v[152:155], v1, v1 op_sel_hi:[0,0,0]
	v_mfma_scale_f32_16x16x128_f8f6f4 v[144:147], v[2:9], v[184:191], v[144:147], v1, v1 op_sel_hi:[0,0,0]
	v_mfma_scale_f32_16x16x128_f8f6f4 v[136:139], v[18:25], v[184:191], v[136:139], v1, v1 op_sel_hi:[0,0,0]
	v_mfma_scale_f32_16x16x128_f8f6f4 v[128:131], v[2:9], v[206:213], v[128:131], v1, v1 op_sel_hi:[0,0,0]
	v_mfma_scale_f32_16x16x128_f8f6f4 v[120:123], v[18:25], v[206:213], v[120:123], v1, v1 op_sel_hi:[0,0,0]
	v_mfma_scale_f32_16x16x128_f8f6f4 v[112:115], v[2:9], v[214:221], v[112:115], v1, v1 op_sel_hi:[0,0,0]
	v_mfma_scale_f32_16x16x128_f8f6f4 v[104:107], v[18:25], v[214:221], v[104:107], v1, v1 op_sel_hi:[0,0,0]
	v_mfma_scale_f32_16x16x128_f8f6f4 v[160:163], v[10:17], v[176:183], v[160:163], v1, v1 op_sel_hi:[0,0,0]
	v_mfma_scale_f32_16x16x128_f8f6f4 v[148:151], v[26:33], v[176:183], v[148:151], v1, v1 op_sel_hi:[0,0,0]
	v_mfma_scale_f32_16x16x128_f8f6f4 v[140:143], v[10:17], v[184:191], v[140:143], v1, v1 op_sel_hi:[0,0,0]
	v_mfma_scale_f32_16x16x128_f8f6f4 v[132:135], v[26:33], v[184:191], v[132:135], v1, v1 op_sel_hi:[0,0,0]
	v_mfma_scale_f32_16x16x128_f8f6f4 v[124:127], v[10:17], v[206:213], v[124:127], v1, v1 op_sel_hi:[0,0,0]
	v_mfma_scale_f32_16x16x128_f8f6f4 v[116:119], v[26:33], v[206:213], v[116:119], v1, v1 op_sel_hi:[0,0,0]
	v_mfma_scale_f32_16x16x128_f8f6f4 v[108:111], v[10:17], v[214:221], v[108:111], v1, v1 op_sel_hi:[0,0,0]
	v_mfma_scale_f32_16x16x128_f8f6f4 v[100:103], v[26:33], v[214:221], v[100:103], v1, v1 op_sel_hi:[0,0,0]
	s_barrier
	v_mov_b32_e32 v34, v165
	ds_read_b128 v[176:179], v175 offset:49152
	ds_read_b128 v[180:183], v175 offset:50176
	ds_read_b128 v[184:187], v175 offset:51200
	ds_read_b128 v[188:191], v175 offset:52224
	ds_read_b128 v[206:209], v175 offset:53248
	ds_read_b128 v[210:213], v175 offset:54272
	ds_read_b128 v[214:217], v175 offset:55296
	ds_read_b128 v[218:221], v175 offset:56320
	s_mov_b32 m0, s49
	v_lshl_add_u64 v[192:193], s[24:25], 0, v[34:35]
	v_lshl_add_u64 v[192:193], v[192:193], 0, s[80:81]
	v_mov_b32_e32 v34, v167
	global_load_lds_dwordx4 v[192:193], off
	s_mov_b32 m0, s50
	v_lshl_add_u64 v[192:193], s[24:25], 0, v[34:35]
	v_lshl_add_u64 v[192:193], v[192:193], 0, s[80:81]
	v_mov_b32_e32 v34, v168
	global_load_lds_dwordx4 v[192:193], off
	s_mov_b32 m0, s54
	v_lshl_add_u64 v[192:193], s[24:25], 0, v[34:35]
	v_lshl_add_u64 v[192:193], v[192:193], 0, s[80:81]
	v_mov_b32_e32 v34, v169
	global_load_lds_dwordx4 v[192:193], off
	s_mov_b32 m0, s55
	v_lshl_add_u64 v[192:193], s[24:25], 0, v[34:35]
	v_lshl_add_u64 v[192:193], v[192:193], 0, s[80:81]
	v_mov_b32_e32 v34, v164
	global_load_lds_dwordx4 v[192:193], off
	s_mov_b32 m0, s51
	v_lshl_add_u64 v[192:193], s[22:23], 0, v[34:35]
	v_lshl_add_u64 v[192:193], v[192:193], 0, s[80:81]
	v_mov_b32_e32 v34, v166
	global_load_lds_dwordx4 v[192:193], off
	s_mov_b32 m0, s52
	v_lshl_add_u64 v[192:193], s[22:23], 0, v[34:35]
	v_lshl_add_u64 v[192:193], v[192:193], 0, s[80:81]
	global_load_lds_dwordx4 v[192:193], off
	s_waitcnt vmcnt(8)
	s_waitcnt lgkmcnt(0)
	s_barrier
	s_waitcnt lgkmcnt(0)
	v_mfma_scale_f32_16x16x128_f8f6f4 v[96:99], v[2:9], v[176:183], v[96:99], v1, v1 op_sel_hi:[0,0,0]
	v_mfma_scale_f32_16x16x128_f8f6f4 v[88:91], v[18:25], v[176:183], v[88:91], v1, v1 op_sel_hi:[0,0,0]
	v_mfma_scale_f32_16x16x128_f8f6f4 v[80:83], v[2:9], v[184:191], v[80:83], v1, v1 op_sel_hi:[0,0,0]
	v_mfma_scale_f32_16x16x128_f8f6f4 v[72:75], v[18:25], v[184:191], v[72:75], v1, v1 op_sel_hi:[0,0,0]
	v_mfma_scale_f32_16x16x128_f8f6f4 v[64:67], v[2:9], v[206:213], v[64:67], v1, v1 op_sel_hi:[0,0,0]
	v_mfma_scale_f32_16x16x128_f8f6f4 v[56:59], v[18:25], v[206:213], v[56:59], v1, v1 op_sel_hi:[0,0,0]
	v_mfma_scale_f32_16x16x128_f8f6f4 v[48:51], v[2:9], v[214:221], v[48:51], v1, v1 op_sel_hi:[0,0,0]
	v_mfma_scale_f32_16x16x128_f8f6f4 v[40:43], v[18:25], v[214:221], v[40:43], v1, v1 op_sel_hi:[0,0,0]
	v_mfma_scale_f32_16x16x128_f8f6f4 v[92:95], v[10:17], v[176:183], v[92:95], v1, v1 op_sel_hi:[0,0,0]
	v_mfma_scale_f32_16x16x128_f8f6f4 v[84:87], v[26:33], v[176:183], v[84:87], v1, v1 op_sel_hi:[0,0,0]
	v_mfma_scale_f32_16x16x128_f8f6f4 v[76:79], v[10:17], v[184:191], v[76:79], v1, v1 op_sel_hi:[0,0,0]
	v_mfma_scale_f32_16x16x128_f8f6f4 v[68:71], v[26:33], v[184:191], v[68:71], v1, v1 op_sel_hi:[0,0,0]
	v_mfma_scale_f32_16x16x128_f8f6f4 v[60:63], v[10:17], v[206:213], v[60:63], v1, v1 op_sel_hi:[0,0,0]
	v_mfma_scale_f32_16x16x128_f8f6f4 v[52:55], v[26:33], v[206:213], v[52:55], v1, v1 op_sel_hi:[0,0,0]
	v_mfma_scale_f32_16x16x128_f8f6f4 v[44:47], v[10:17], v[214:221], v[44:47], v1, v1 op_sel_hi:[0,0,0]
	v_mfma_scale_f32_16x16x128_f8f6f4 v[36:39], v[26:33], v[214:221], v[36:39], v1, v1 op_sel_hi:[0,0,0]
	s_barrier
	s_add_u32 s20, s20, 0x100
	s_addc_u32 s21, s21, 0
	s_add_u32 s62, s62, 0x100
	s_addc_u32 s63, s63, 0
	s_cmp_ge_i32 s64, s47
	s_mov_b32 s22, s64
	s_cbranch_scc0 .LBB0_2143

; #define PG8_STAGE(...) PG8_STAGE_(__VA_ARGS__, 0u)
; #define PG8_WAIT_V(n) asm volatile("s_waitcnt vmcnt(" #n ")" ::: "memory")
; #define PG8_WAIT_L(n) asm volatile("s_waitcnt lgkmcnt(" #n ")" ::: "memory")
; #define PG8_BAR __builtin_amdgcn_s_barrier()
; #define PG8_SCHED __builtin_amdgcn_sched_barrier(0)
; template <class Epi, class Sched, bool ALIGN_EPI = true, bool SP2 = true>
; __device__ __forceinline__ void gemm_phase(LAS unsigned char* lds, const Gemm g, const Sched& S, const Epi& E) {
;     ...
;             PG8_LDB(B0, 0, 0); PG8_LDB(B1, 0, 1); PG8_SCHED; PG8_LDA(At, 0, 0); PG8_STAGE(PG8_SA(1, 1), a1, voffAh);
;             PG8_WAIT_V(8); PG8_WAIT_L(0); PG8_BAR; PG8_MMA(0, 0, At, B0); PG8_MMA(0, 1, At, B1); PG8_BAR; PG8_SCHED;
;             if constexpr (!Epi::HALF_M) PG8_LDA(At, 0, 1); PG8_STAGE(PG8_SB(0, 0), b2, voffB); PG8_STAGE(PG8_SB(0, 1), b2, voffBh); PG8_STAGE(PG8_SA(0, 0), a2, voffA);
;             PG8_WAIT_V(8); PG8_WAIT_L(0); PG8_BAR; if constexpr (!Epi::HALF_M) { PG8_MMA(1, 0, At, B0); PG8_MMA(1, 1, At, B1); } PG8_BAR; PG8_SCHED;
.LBB0_2170:
	v_add_u32_e32 v34, s5, v247
	ds_read_b128 v[48:51], v34
	ds_read_b128 v[60:63], v34 offset:1024
	ds_read_b128 v[72:75], v34 offset:2048
	ds_read_b128 v[84:87], v34 offset:3072
	v_add_u32_e32 v34, s39, v247
	ds_read_b128 v[96:99], v34
	ds_read_b128 v[108:111], v34 offset:1024
	ds_read_b128 v[120:123], v34 offset:2048
	ds_read_b128 v[132:135], v34 offset:3072
	s_add_i32 s62, s24, 2
	s_add_u32 s26, s22, 0x80
	s_addc_u32 s25, s23, 0
	s_cmp_eq_u32 s55, s24
	s_cselect_b32 s24, s17, s26
	s_cselect_b32 s25, s15, s25
	s_cselect_b32 s27, s33, s61
	s_cselect_b32 s26, s59, s60
	v_mov_b32_e32 v34, v244
	ds_read_b128 v[144:147], v249
	ds_read_b128 v[156:159], v249 offset:1024
	ds_read_b128 v[164:167], v249 offset:2048
	ds_read_b128 v[172:175], v249 offset:3072
	ds_read_b128 v[180:183], v249 offset:4096
	ds_read_b128 v[184:187], v249 offset:5120
	ds_read_b128 v[188:191], v249 offset:6144
	ds_read_b128 v[192:195], v249 offset:7168
	s_add_i32 m0, s42, 0xc000
	s_nop 0
	global_load_lds_dwordx4 v34, s[22:23]
	v_mov_b32_e32 v34, v245
	s_add_i32 m0, s42, 0xe000
	s_nop 0
	global_load_lds_dwordx4 v34, s[22:23]
	s_waitcnt vmcnt(8)
	s_waitcnt lgkmcnt(0)
	s_barrier
	s_waitcnt lgkmcnt(0)
	v_mfma_f32_16x16x32_f16 v[176:179], v[48:51], v[144:147], v[176:179]
	v_mfma_f32_16x16x32_f16 v[168:171], v[72:75], v[144:147], v[168:171]
	v_mfma_f32_16x16x32_f16 v[148:151], v[48:51], v[164:167], v[148:151]
	v_mfma_f32_16x16x32_f16 v[140:143], v[72:75], v[164:167], v[140:143]
	v_mfma_f32_16x16x32_f16 v[124:127], v[48:51], v[180:183], v[124:127]
	v_mfma_f32_16x16x32_f16 v[116:119], v[72:75], v[180:183], v[116:119]
	v_mfma_f32_16x16x32_f16 v[100:103], v[48:51], v[188:191], v[100:103]
	v_mfma_f32_16x16x32_f16 v[92:95], v[72:75], v[188:191], v[92:95]
	v_mfma_f32_16x16x32_f16 v[176:179], v[60:63], v[156:159], v[176:179]
	v_mfma_f32_16x16x32_f16 v[168:171], v[84:87], v[156:159], v[168:171]
	v_mfma_f32_16x16x32_f16 v[148:151], v[60:63], v[172:175], v[148:151]
	v_mfma_f32_16x16x32_f16 v[140:143], v[84:87], v[172:175], v[140:143]
	v_mfma_f32_16x16x32_f16 v[124:127], v[60:63], v[184:187], v[124:127]
	v_mfma_f32_16x16x32_f16 v[116:119], v[84:87], v[184:187], v[116:119]
	v_mfma_f32_16x16x32_f16 v[100:103], v[60:63], v[192:195], v[100:103]
	v_mfma_f32_16x16x32_f16 v[92:95], v[84:87], v[192:195], v[92:95]
	v_mfma_f32_16x16x32_f16 v[160:163], v[96:99], v[144:147], v[160:163]
	v_mfma_f32_16x16x32_f16 v[136:139], v[96:99], v[164:167], v[136:139]
	v_mfma_f32_16x16x32_f16 v[128:131], v[120:123], v[164:167], v[128:131]
	v_mfma_f32_16x16x32_f16 v[112:115], v[96:99], v[180:183], v[112:115]
	v_mfma_f32_16x16x32_f16 v[104:107], v[120:123], v[180:183], v[104:107]
	v_mfma_f32_16x16x32_f16 v[88:91], v[96:99], v[188:191], v[88:91]
	v_mfma_f32_16x16x32_f16 v[80:83], v[120:123], v[188:191], v[80:83]
	v_mfma_f32_16x16x32_f16 v[160:163], v[108:111], v[156:159], v[160:163]
	v_mfma_f32_16x16x32_f16 v[144:147], v[120:123], v[144:147], v[152:155]
	v_mfma_f32_16x16x32_f16 v[136:139], v[108:111], v[172:175], v[136:139]
	v_mfma_f32_16x16x32_f16 v[128:131], v[132:135], v[172:175], v[128:131]
	v_mfma_f32_16x16x32_f16 v[112:115], v[108:111], v[184:187], v[112:115]
	v_mfma_f32_16x16x32_f16 v[104:107], v[132:135], v[184:187], v[104:107]
	v_mfma_f32_16x16x32_f16 v[88:91], v[108:111], v[192:195], v[88:91]
	v_mfma_f32_16x16x32_f16 v[80:83], v[132:135], v[192:195], v[80:83]
	v_mfma_f32_16x16x32_f16 v[144:147], v[132:135], v[156:159], v[144:147]
	s_barrier
	v_mov_b32_e32 v34, v224
	s_mov_b32 m0, s37
	ds_read_b128 v[152:155], v249 offset:16384
	ds_read_b128 v[156:159], v249 offset:17408
	ds_read_b128 v[164:167], v249 offset:18432
	ds_read_b128 v[172:175], v249 offset:19456
	ds_read_b128 v[180:183], v249 offset:20480
	ds_read_b128 v[184:187], v249 offset:21504
	ds_read_b128 v[188:191], v249 offset:22528
	ds_read_b128 v[192:195], v249 offset:23552
	s_nop 0
	global_load_lds_dwordx4 v34, s[26:27]
	v_mov_b32_e32 v34, v241
	s_mov_b32 m0, s38
	s_nop 0
	global_load_lds_dwordx4 v34, s[26:27]
	v_mov_b32_e32 v34, v242
	s_mov_b32 m0, s40
	s_nop 0
	global_load_lds_dwordx4 v34, s[26:27]
	v_mov_b32_e32 v34, v243
	s_mov_b32 m0, s41
	s_nop 0
	global_load_lds_dwordx4 v34, s[26:27]
	v_mov_b32_e32 v34, v197
	s_mov_b32 m0, s42
	s_nop 0
	global_load_lds_dwordx4 v34, s[24:25]
	v_mov_b32_e32 v34, v225
	s_mov_b32 m0, s43
	s_nop 0
	global_load_lds_dwordx4 v34, s[24:25]
	s_waitcnt vmcnt(8)
	s_waitcnt lgkmcnt(0)
	s_barrier
	s_waitcnt lgkmcnt(0)
	v_mfma_f32_16x16x32_f16 v[76:79], v[48:51], v[152:155], v[76:79]
	v_mfma_f32_16x16x32_f16 v[68:71], v[72:75], v[152:155], v[68:71]
	v_mfma_f32_16x16x32_f16 v[52:55], v[48:51], v[164:167], v[52:55]
	v_mfma_f32_16x16x32_f16 v[44:47], v[72:75], v[164:167], v[44:47]
	v_mfma_f32_16x16x32_f16 v[30:33], v[48:51], v[180:183], v[30:33]
	v_mfma_f32_16x16x32_f16 v[26:29], v[72:75], v[180:183], v[26:29]
	v_mfma_f32_16x16x32_f16 v[14:17], v[48:51], v[188:191], v[14:17]
	v_mfma_f32_16x16x32_f16 v[10:13], v[72:75], v[188:191], v[10:13]
	v_mfma_f32_16x16x32_f16 v[76:79], v[60:63], v[156:159], v[76:79]
	v_mfma_f32_16x16x32_f16 v[68:71], v[84:87], v[156:159], v[68:71]
	v_mfma_f32_16x16x32_f16 v[52:55], v[60:63], v[172:175], v[52:55]
	v_mfma_f32_16x16x32_f16 v[44:47], v[84:87], v[172:175], v[44:47]
	v_mfma_f32_16x16x32_f16 v[30:33], v[60:63], v[184:187], v[30:33]
	v_mfma_f32_16x16x32_f16 v[26:29], v[84:87], v[184:187], v[26:29]
	v_mfma_f32_16x16x32_f16 v[14:17], v[60:63], v[192:195], v[14:17]
	v_mfma_f32_16x16x32_f16 v[10:13], v[84:87], v[192:195], v[10:13]
	v_mfma_f32_16x16x32_f16 v[56:59], v[120:123], v[152:155], v[56:59]
	v_mfma_f32_16x16x32_f16 v[40:43], v[96:99], v[164:167], v[40:43]
	v_mfma_f32_16x16x32_f16 v[36:39], v[120:123], v[164:167], v[36:39]
	v_mfma_f32_16x16x32_f16 v[22:25], v[96:99], v[180:183], v[22:25]
	v_mfma_f32_16x16x32_f16 v[18:21], v[120:123], v[180:183], v[18:21]
	v_mfma_f32_16x16x32_f16 v[6:9], v[96:99], v[188:191], v[6:9]
	v_mfma_f32_16x16x32_f16 v[2:5], v[120:123], v[188:191], v[2:5]
	v_mfma_f32_16x16x32_f16 v[48:51], v[96:99], v[152:155], v[64:67]
	v_mfma_f32_16x16x32_f16 v[56:59], v[132:135], v[156:159], v[56:59]
	v_mfma_f32_16x16x32_f16 v[40:43], v[108:111], v[172:175], v[40:43]
	v_mfma_f32_16x16x32_f16 v[36:39], v[132:135], v[172:175], v[36:39]
	v_mfma_f32_16x16x32_f16 v[22:25], v[108:111], v[184:187], v[22:25]
	v_mfma_f32_16x16x32_f16 v[18:21], v[132:135], v[184:187], v[18:21]
	v_mfma_f32_16x16x32_f16 v[6:9], v[108:111], v[192:195], v[6:9]
	v_mfma_f32_16x16x32_f16 v[2:5], v[132:135], v[192:195], v[2:5]
	v_mfma_f32_16x16x32_f16 v[48:51], v[108:111], v[156:159], v[48:51]
	s_barrier
; #define PG8_STAGE(...) PG8_STAGE_(__VA_ARGS__, 0u)
; #define PG8_WAIT_V(n) asm volatile("s_waitcnt vmcnt(" #n ")" ::: "memory")
; #define PG8_WAIT_L(n) asm volatile("s_waitcnt lgkmcnt(" #n ")" ::: "memory")
; #define PG8_BAR __builtin_amdgcn_s_barrier()
; #define PG8_SCHED __builtin_amdgcn_sched_barrier(0)
; template <class Epi, class Sched, bool ALIGN_EPI = true, bool SP2 = true>
; __device__ __forceinline__ void gemm_phase(LAS unsigned char* lds, const Gemm g, const Sched& S, const Epi& E) {
;     ...
;             PG8_LDB(B0, 1, 0); PG8_LDB(B1, 1, 1); PG8_SCHED; PG8_LDA(At, 1, 0); PG8_STAGE(PG8_SA(0, 1), a2, voffAh);
;             PG8_WAIT_V(8); PG8_WAIT_L(0); PG8_BAR; PG8_MMA(0, 0, At, B0); PG8_MMA(0, 1, At, B1); PG8_BAR; PG8_SCHED;
	v_add_u32_e32 v34, s47, v247
	ds_read_b128 v[60:63], v34
	ds_read_b128 v[64:67], v34 offset:1024
	ds_read_b128 v[72:75], v34 offset:2048
	ds_read_b128 v[84:87], v34 offset:3072
	v_add_u32_e32 v34, s52, v247
	ds_read_b128 v[96:99], v34
	ds_read_b128 v[108:111], v34 offset:1024
	ds_read_b128 v[120:123], v34 offset:2048
	ds_read_b128 v[132:135], v34 offset:3072
	v_mov_b32_e32 v34, v244
	s_mov_b32 m0, s44
	ds_read_b128 v[152:155], v249 offset:32768
	ds_read_b128 v[156:159], v249 offset:33792
	ds_read_b128 v[164:167], v249 offset:34816
	ds_read_b128 v[172:175], v249 offset:35840
	ds_read_b128 v[180:183], v249 offset:36864
	ds_read_b128 v[184:187], v249 offset:37888
	ds_read_b128 v[188:191], v249 offset:38912
	ds_read_b128 v[192:195], v249 offset:39936
	s_nop 0
	global_load_lds_dwordx4 v34, s[24:25]
	v_mov_b32_e32 v34, v245
	s_mov_b32 m0, s45
	s_nop 0
	global_load_lds_dwordx4 v34, s[24:25]
	s_waitcnt vmcnt(8)
	s_waitcnt lgkmcnt(0)
	s_barrier
	s_waitcnt lgkmcnt(0)
	v_mfma_f32_16x16x32_f16 v[176:179], v[60:63], v[152:155], v[176:179]
	v_mfma_f32_16x16x32_f16 v[168:171], v[72:75], v[152:155], v[168:171]
	v_mfma_f32_16x16x32_f16 v[148:151], v[60:63], v[164:167], v[148:151]
	v_mfma_f32_16x16x32_f16 v[140:143], v[72:75], v[164:167], v[140:143]
	v_mfma_f32_16x16x32_f16 v[124:127], v[60:63], v[180:183], v[124:127]
	v_mfma_f32_16x16x32_f16 v[116:119], v[72:75], v[180:183], v[116:119]
	v_mfma_f32_16x16x32_f16 v[100:103], v[60:63], v[188:191], v[100:103]
	v_mfma_f32_16x16x32_f16 v[92:95], v[72:75], v[188:191], v[92:95]
	v_mfma_f32_16x16x32_f16 v[176:179], v[64:67], v[156:159], v[176:179]
	v_mfma_f32_16x16x32_f16 v[168:171], v[84:87], v[156:159], v[168:171]
	v_mfma_f32_16x16x32_f16 v[148:151], v[64:67], v[172:175], v[148:151]
	v_mfma_f32_16x16x32_f16 v[140:143], v[84:87], v[172:175], v[140:143]
	v_mfma_f32_16x16x32_f16 v[124:127], v[64:67], v[184:187], v[124:127]
	v_mfma_f32_16x16x32_f16 v[116:119], v[84:87], v[184:187], v[116:119]
	v_mfma_f32_16x16x32_f16 v[100:103], v[64:67], v[192:195], v[100:103]
	v_mfma_f32_16x16x32_f16 v[92:95], v[84:87], v[192:195], v[92:95]
	v_mfma_f32_16x16x32_f16 v[160:163], v[96:99], v[152:155], v[160:163]
	v_mfma_f32_16x16x32_f16 v[144:147], v[120:123], v[152:155], v[144:147]
	v_mfma_f32_16x16x32_f16 v[136:139], v[96:99], v[164:167], v[136:139]
	v_mfma_f32_16x16x32_f16 v[128:131], v[120:123], v[164:167], v[128:131]
	v_mfma_f32_16x16x32_f16 v[112:115], v[96:99], v[180:183], v[112:115]
	v_mfma_f32_16x16x32_f16 v[104:107], v[120:123], v[180:183], v[104:107]
	v_mfma_f32_16x16x32_f16 v[88:91], v[96:99], v[188:191], v[88:91]
	v_mfma_f32_16x16x32_f16 v[80:83], v[120:123], v[188:191], v[80:83]
	v_mfma_f32_16x16x32_f16 v[160:163], v[108:111], v[156:159], v[160:163]
	v_mfma_f32_16x16x32_f16 v[152:155], v[132:135], v[156:159], v[144:147]
	v_mfma_f32_16x16x32_f16 v[136:139], v[108:111], v[172:175], v[136:139]
	v_mfma_f32_16x16x32_f16 v[128:131], v[132:135], v[172:175], v[128:131]
	v_mfma_f32_16x16x32_f16 v[112:115], v[108:111], v[184:187], v[112:115]
	v_mfma_f32_16x16x32_f16 v[104:107], v[132:135], v[184:187], v[104:107]
	v_mfma_f32_16x16x32_f16 v[88:91], v[108:111], v[192:195], v[88:91]
	v_mfma_f32_16x16x32_f16 v[80:83], v[132:135], v[192:195], v[80:83]
	s_barrier
; #define PG8_STAGE(...) PG8_STAGE_(__VA_ARGS__, 0u)
; #define PG8_WAIT_V(n) asm volatile("s_waitcnt vmcnt(" #n ")" ::: "memory")
; #define PG8_WAIT_L(n) asm volatile("s_waitcnt lgkmcnt(" #n ")" ::: "memory")
; #define PG8_BAR __builtin_amdgcn_s_barrier()
; #define PG8_SCHED __builtin_amdgcn_sched_barrier(0)
; template <class Epi, class Sched, bool ALIGN_EPI = true, bool SP2 = true>
; __device__ __forceinline__ void gemm_phase(LAS unsigned char* lds, const Gemm g, const Sched& S, const Epi& E) {
;     ...
;             if constexpr (!Epi::HALF_M) PG8_LDA(At, 1, 1); PG8_STAGE(PG8_SB(1, 0), b3, voffB); PG8_STAGE(PG8_SB(1, 1), b3, voffBh); PG8_STAGE(PG8_SA(1, 0), a3, voffA);
;             PG8_WAIT_V(8); PG8_WAIT_L(0); PG8_BAR; if constexpr (!Epi::HALF_M) { PG8_MMA(1, 0, At, B0); PG8_MMA(1, 1, At, B1); } PG8_BAR; PG8_SCHED;
	v_mov_b32_e32 v34, v224
	ds_read_b128 v[144:147], v249 offset:49152
	ds_read_b128 v[156:159], v249 offset:50176
	ds_read_b128 v[164:167], v249 offset:51200
	ds_read_b128 v[172:175], v249 offset:52224
	ds_read_b128 v[180:183], v249 offset:53248
	ds_read_b128 v[184:187], v249 offset:54272
	ds_read_b128 v[188:191], v249 offset:55296
	ds_read_b128 v[192:195], v249 offset:56320
	s_mov_b32 m0, s48
	v_lshl_add_u64 v[206:207], s[26:27], 0, v[34:35]
	v_lshl_add_u64 v[206:207], v[206:207], 0, s[80:81]
	v_mov_b32_e32 v34, v241
	global_load_lds_dwordx4 v[206:207], off
	s_mov_b32 m0, s49
	v_lshl_add_u64 v[206:207], s[26:27], 0, v[34:35]
	v_lshl_add_u64 v[206:207], v[206:207], 0, s[80:81]
	v_mov_b32_e32 v34, v242
	global_load_lds_dwordx4 v[206:207], off
	s_mov_b32 m0, s53
	v_lshl_add_u64 v[206:207], s[26:27], 0, v[34:35]
	v_lshl_add_u64 v[206:207], v[206:207], 0, s[80:81]
	v_mov_b32_e32 v34, v243
	global_load_lds_dwordx4 v[206:207], off
	s_mov_b32 m0, s54
	v_lshl_add_u64 v[206:207], s[26:27], 0, v[34:35]
	v_lshl_add_u64 v[206:207], v[206:207], 0, s[80:81]
	v_mov_b32_e32 v34, v197
	global_load_lds_dwordx4 v[206:207], off
	s_mov_b32 m0, s50
	v_lshl_add_u64 v[206:207], s[24:25], 0, v[34:35]
	v_lshl_add_u64 v[206:207], v[206:207], 0, s[80:81]
	v_mov_b32_e32 v34, v225
	global_load_lds_dwordx4 v[206:207], off
	s_mov_b32 m0, s51
	v_lshl_add_u64 v[206:207], s[24:25], 0, v[34:35]
	v_lshl_add_u64 v[206:207], v[206:207], 0, s[80:81]
	global_load_lds_dwordx4 v[206:207], off
	s_waitcnt vmcnt(8)
	s_waitcnt lgkmcnt(0)
	s_barrier
	s_waitcnt lgkmcnt(0)
	v_mfma_f32_16x16x32_f16 v[76:79], v[60:63], v[144:147], v[76:79]
	v_mfma_f32_16x16x32_f16 v[68:71], v[72:75], v[144:147], v[68:71]
	v_mfma_f32_16x16x32_f16 v[52:55], v[60:63], v[164:167], v[52:55]
	v_mfma_f32_16x16x32_f16 v[44:47], v[72:75], v[164:167], v[44:47]
	v_mfma_f32_16x16x32_f16 v[30:33], v[60:63], v[180:183], v[30:33]
	v_mfma_f32_16x16x32_f16 v[26:29], v[72:75], v[180:183], v[26:29]
	v_mfma_f32_16x16x32_f16 v[14:17], v[60:63], v[188:191], v[14:17]
	v_mfma_f32_16x16x32_f16 v[10:13], v[72:75], v[188:191], v[10:13]
	v_mfma_f32_16x16x32_f16 v[76:79], v[64:67], v[156:159], v[76:79]
	v_mfma_f32_16x16x32_f16 v[68:71], v[84:87], v[156:159], v[68:71]
	v_mfma_f32_16x16x32_f16 v[52:55], v[64:67], v[172:175], v[52:55]
	v_mfma_f32_16x16x32_f16 v[44:47], v[84:87], v[172:175], v[44:47]
	v_mfma_f32_16x16x32_f16 v[30:33], v[64:67], v[184:187], v[30:33]
	v_mfma_f32_16x16x32_f16 v[26:29], v[84:87], v[184:187], v[26:29]
	v_mfma_f32_16x16x32_f16 v[14:17], v[64:67], v[192:195], v[14:17]
	v_mfma_f32_16x16x32_f16 v[10:13], v[84:87], v[192:195], v[10:13]
	v_mfma_f32_16x16x32_f16 v[48:51], v[96:99], v[144:147], v[48:51]
	v_mfma_f32_16x16x32_f16 v[64:67], v[108:111], v[156:159], v[48:51]
	v_mfma_f32_16x16x32_f16 v[48:51], v[120:123], v[144:147], v[56:59]
	v_mfma_f32_16x16x32_f16 v[40:43], v[96:99], v[164:167], v[40:43]
	v_mfma_f32_16x16x32_f16 v[36:39], v[120:123], v[164:167], v[36:39]
	v_mfma_f32_16x16x32_f16 v[22:25], v[96:99], v[180:183], v[22:25]
	v_mfma_f32_16x16x32_f16 v[18:21], v[120:123], v[180:183], v[18:21]
	v_mfma_f32_16x16x32_f16 v[6:9], v[96:99], v[188:191], v[6:9]
	v_mfma_f32_16x16x32_f16 v[2:5], v[120:123], v[188:191], v[2:5]
	v_mfma_f32_16x16x32_f16 v[56:59], v[132:135], v[156:159], v[48:51]
	v_mfma_f32_16x16x32_f16 v[40:43], v[108:111], v[172:175], v[40:43]
	v_mfma_f32_16x16x32_f16 v[36:39], v[132:135], v[172:175], v[36:39]
	v_mfma_f32_16x16x32_f16 v[22:25], v[108:111], v[184:187], v[22:25]
	v_mfma_f32_16x16x32_f16 v[18:21], v[132:135], v[184:187], v[18:21]
	v_mfma_f32_16x16x32_f16 v[6:9], v[108:111], v[192:195], v[6:9]
	v_mfma_f32_16x16x32_f16 v[2:5], v[132:135], v[192:195], v[2:5]
	s_barrier
	s_add_u32 s22, s22, 0x100
	s_addc_u32 s23, s23, 0
	s_add_u32 s60, s60, 0x100
	s_addc_u32 s61, s61, 0
	s_cmp_ge_i32 s62, s46
	s_mov_b32 s24, s62
	s_cbranch_scc0 .LBB0_2170

; #define PG8_STAGE(...) PG8_STAGE_(__VA_ARGS__, 0u)
; #define PG8_WAIT_V(n) asm volatile("s_waitcnt vmcnt(" #n ")" ::: "memory")
; #define PG8_WAIT_L(n) asm volatile("s_waitcnt lgkmcnt(" #n ")" ::: "memory")
; #define PG8_BAR __builtin_amdgcn_s_barrier()
; #define PG8_SCHED __builtin_amdgcn_sched_barrier(0)
; template <class Epi, class Sched, bool ALIGN_EPI = true, bool SP2 = true>
; __device__ __forceinline__ void gemm_phase(LAS unsigned char* lds, const Gemm g, const Sched& S, const Epi& E) {
;     ...
;             PG8_LDB(B0, 0, 0); PG8_LDB(B1, 0, 1); PG8_SCHED; PG8_LDA(At, 0, 0); PG8_STAGE(PG8_SA(1, 1), a1, voffAh);
;             PG8_WAIT_V(8); PG8_WAIT_L(0); PG8_BAR; PG8_MMA(0, 0, At, B0); PG8_MMA(0, 1, At, B1); PG8_BAR; PG8_SCHED;
;             if constexpr (!Epi::HALF_M) PG8_LDA(At, 0, 1); PG8_STAGE(PG8_SB(0, 0), b2, voffB); PG8_STAGE(PG8_SB(0, 1), b2, voffBh); PG8_STAGE(PG8_SA(0, 0), a2, voffA);
;             PG8_WAIT_V(8); PG8_WAIT_L(0); PG8_BAR; if constexpr (!Epi::HALF_M) { PG8_MMA(1, 0, At, B0); PG8_MMA(1, 1, At, B1); } PG8_BAR; PG8_SCHED;
.LBB0_2251:
	v_add_u32_e32 v14, s37, v173
	v_add_u32_e32 v30, s40, v173
	ds_read_b128 v[2:5], v14
	ds_read_b128 v[6:9], v14 offset:1024
	ds_read_b128 v[10:13], v14 offset:2048
	ds_read_b128 v[14:17], v14 offset:3072
	ds_read_b128 v[18:21], v30
	ds_read_b128 v[22:25], v30 offset:1024
	ds_read_b128 v[26:29], v30 offset:2048
	ds_read_b128 v[30:33], v30 offset:3072
	s_add_i32 s65, s20, 2
	s_add_u32 s22, s18, 0x80
	s_addc_u32 s21, s19, 0
	s_cmp_eq_u32 s58, s20
	s_cselect_b32 s20, s6, s22
	s_cselect_b32 s21, s7, s21
	s_cselect_b32 s23, s17, s64
	s_cselect_b32 s22, s16, s63
	v_mov_b32_e32 v34, v170
	ds_read_b128 v[176:179], v174
	ds_read_b128 v[180:183], v174 offset:1024
	ds_read_b128 v[184:187], v174 offset:2048
	ds_read_b128 v[188:191], v174 offset:3072
	ds_read_b128 v[206:209], v174 offset:4096
	ds_read_b128 v[210:213], v174 offset:5120
	ds_read_b128 v[214:217], v174 offset:6144
	ds_read_b128 v[218:221], v174 offset:7168
	s_add_i32 m0, s43, 0xc000
	s_nop 0
	global_load_lds_dwordx4 v34, s[18:19]
	v_mov_b32_e32 v34, v171
	s_add_i32 m0, s43, 0xe000
	s_nop 0
	global_load_lds_dwordx4 v34, s[18:19]
	s_waitcnt vmcnt(8)
	s_waitcnt lgkmcnt(0)
	s_barrier
	s_waitcnt lgkmcnt(0)
	v_mfma_scale_f32_16x16x128_f8f6f4 v[160:163], v[2:9], v[176:183], v[160:163], v1, v1 op_sel_hi:[0,0,0]
	v_mfma_scale_f32_16x16x128_f8f6f4 v[156:159], v[10:17], v[176:183], v[156:159], v1, v1 op_sel_hi:[0,0,0]
	v_mfma_scale_f32_16x16x128_f8f6f4 v[40:43], v[2:9], v[184:191], v[40:43], v1, v1 op_sel_hi:[0,0,0]
	v_mfma_scale_f32_16x16x128_f8f6f4 v[36:39], v[10:17], v[184:191], v[36:39], v1, v1 op_sel_hi:[0,0,0]
	v_mfma_scale_f32_16x16x128_f8f6f4 v[56:59], v[2:9], v[206:213], v[56:59], v1, v1 op_sel_hi:[0,0,0]
	v_mfma_scale_f32_16x16x128_f8f6f4 v[52:55], v[10:17], v[206:213], v[52:55], v1, v1 op_sel_hi:[0,0,0]
	v_mfma_scale_f32_16x16x128_f8f6f4 v[72:75], v[2:9], v[214:221], v[72:75], v1, v1 op_sel_hi:[0,0,0]
	v_mfma_scale_f32_16x16x128_f8f6f4 v[68:71], v[10:17], v[214:221], v[68:71], v1, v1 op_sel_hi:[0,0,0]
	v_mfma_scale_f32_16x16x128_f8f6f4 v[152:155], v[18:25], v[176:183], v[152:155], v1, v1 op_sel_hi:[0,0,0]
	v_mfma_scale_f32_16x16x128_f8f6f4 v[148:151], v[26:33], v[176:183], v[148:151], v1, v1 op_sel_hi:[0,0,0]
	v_mfma_scale_f32_16x16x128_f8f6f4 v[144:147], v[18:25], v[184:191], v[144:147], v1, v1 op_sel_hi:[0,0,0]
	v_mfma_scale_f32_16x16x128_f8f6f4 v[140:143], v[26:33], v[184:191], v[140:143], v1, v1 op_sel_hi:[0,0,0]
	v_mfma_scale_f32_16x16x128_f8f6f4 v[136:139], v[18:25], v[206:213], v[136:139], v1, v1 op_sel_hi:[0,0,0]
	v_mfma_scale_f32_16x16x128_f8f6f4 v[132:135], v[26:33], v[206:213], v[132:135], v1, v1 op_sel_hi:[0,0,0]
	v_mfma_scale_f32_16x16x128_f8f6f4 v[48:51], v[18:25], v[214:221], v[48:51], v1, v1 op_sel_hi:[0,0,0]
	v_mfma_scale_f32_16x16x128_f8f6f4 v[44:47], v[26:33], v[214:221], v[44:47], v1, v1 op_sel_hi:[0,0,0]
	s_barrier
	v_mov_b32_e32 v34, v165
	s_mov_b32 m0, s38
	ds_read_b128 v[176:179], v174 offset:16384
	ds_read_b128 v[180:183], v174 offset:17408
	ds_read_b128 v[184:187], v174 offset:18432
	ds_read_b128 v[188:191], v174 offset:19456
	ds_read_b128 v[206:209], v174 offset:20480
	ds_read_b128 v[210:213], v174 offset:21504
	ds_read_b128 v[214:217], v174 offset:22528
	ds_read_b128 v[218:221], v174 offset:23552
	s_nop 0
	global_load_lds_dwordx4 v34, s[22:23]
	v_mov_b32_e32 v34, v167
	s_mov_b32 m0, s39
	s_nop 0
	global_load_lds_dwordx4 v34, s[22:23]
	v_mov_b32_e32 v34, v168
	s_mov_b32 m0, s41
	s_nop 0
	global_load_lds_dwordx4 v34, s[22:23]
	v_mov_b32_e32 v34, v169
	s_mov_b32 m0, s42
	s_nop 0
	global_load_lds_dwordx4 v34, s[22:23]
	v_mov_b32_e32 v34, v164
	s_mov_b32 m0, s43
	s_nop 0
	global_load_lds_dwordx4 v34, s[20:21]
	v_mov_b32_e32 v34, v166
	s_mov_b32 m0, s44
	s_nop 0
	global_load_lds_dwordx4 v34, s[20:21]
	s_waitcnt vmcnt(8)
	s_waitcnt lgkmcnt(0)
	s_barrier
	s_waitcnt lgkmcnt(0)
	v_mfma_scale_f32_16x16x128_f8f6f4 v[112:115], v[2:9], v[176:183], v[112:115], v1, v1 op_sel_hi:[0,0,0]
	v_mfma_scale_f32_16x16x128_f8f6f4 v[108:111], v[10:17], v[176:183], v[108:111], v1, v1 op_sel_hi:[0,0,0]
	v_mfma_scale_f32_16x16x128_f8f6f4 v[128:131], v[2:9], v[184:191], v[128:131], v1, v1 op_sel_hi:[0,0,0]
	v_mfma_scale_f32_16x16x128_f8f6f4 v[124:127], v[10:17], v[184:191], v[124:127], v1, v1 op_sel_hi:[0,0,0]
	v_mfma_scale_f32_16x16x128_f8f6f4 v[120:123], v[2:9], v[206:213], v[120:123], v1, v1 op_sel_hi:[0,0,0]
	v_mfma_scale_f32_16x16x128_f8f6f4 v[116:119], v[10:17], v[206:213], v[116:119], v1, v1 op_sel_hi:[0,0,0]
	v_mfma_scale_f32_16x16x128_f8f6f4 v[88:91], v[2:9], v[214:221], v[88:91], v1, v1 op_sel_hi:[0,0,0]
	v_mfma_scale_f32_16x16x128_f8f6f4 v[84:87], v[10:17], v[214:221], v[84:87], v1, v1 op_sel_hi:[0,0,0]
	v_mfma_scale_f32_16x16x128_f8f6f4 v[64:67], v[18:25], v[176:183], v[64:67], v1, v1 op_sel_hi:[0,0,0]
	v_mfma_scale_f32_16x16x128_f8f6f4 v[60:63], v[26:33], v[176:183], v[60:63], v1, v1 op_sel_hi:[0,0,0]
	v_mfma_scale_f32_16x16x128_f8f6f4 v[96:99], v[18:25], v[184:191], v[96:99], v1, v1 op_sel_hi:[0,0,0]
	v_mfma_scale_f32_16x16x128_f8f6f4 v[92:95], v[26:33], v[184:191], v[92:95], v1, v1 op_sel_hi:[0,0,0]
	v_mfma_scale_f32_16x16x128_f8f6f4 v[104:107], v[18:25], v[206:213], v[104:107], v1, v1 op_sel_hi:[0,0,0]
	v_mfma_scale_f32_16x16x128_f8f6f4 v[100:103], v[26:33], v[206:213], v[100:103], v1, v1 op_sel_hi:[0,0,0]
	v_mfma_scale_f32_16x16x128_f8f6f4 v[80:83], v[18:25], v[214:221], v[80:83], v1, v1 op_sel_hi:[0,0,0]
	v_mfma_scale_f32_16x16x128_f8f6f4 v[76:79], v[26:33], v[214:221], v[76:79], v1, v1 op_sel_hi:[0,0,0]
	s_barrier
; #define PG8_STAGE(...) PG8_STAGE_(__VA_ARGS__, 0u)
; #define PG8_WAIT_V(n) asm volatile("s_waitcnt vmcnt(" #n ")" ::: "memory")
; #define PG8_WAIT_L(n) asm volatile("s_waitcnt lgkmcnt(" #n ")" ::: "memory")
; #define PG8_BAR __builtin_amdgcn_s_barrier()
; #define PG8_SCHED __builtin_amdgcn_sched_barrier(0)
; template <class Epi, class Sched, bool ALIGN_EPI = true, bool SP2 = true>
; __device__ __forceinline__ void gemm_phase(LAS unsigned char* lds, const Gemm g, const Sched& S, const Epi& E) {
;     ...
;             PG8_LDB(B0, 1, 0); PG8_LDB(B1, 1, 1); PG8_SCHED; PG8_LDA(At, 1, 0); PG8_STAGE(PG8_SA(0, 1), a2, voffAh);
;             PG8_WAIT_V(8); PG8_WAIT_L(0); PG8_BAR; PG8_MMA(0, 0, At, B0); PG8_MMA(0, 1, At, B1); PG8_BAR; PG8_SCHED;
;             if constexpr (!Epi::HALF_M) PG8_LDA(At, 1, 1); PG8_STAGE(PG8_SB(1, 0), b3, voffB); PG8_STAGE(PG8_SB(1, 1), b3, voffBh); PG8_STAGE(PG8_SA(1, 0), a3, voffA);
;             PG8_WAIT_V(8); PG8_WAIT_L(0); PG8_BAR; if constexpr (!Epi::HALF_M) { PG8_MMA(1, 0, At, B0); PG8_MMA(1, 1, At, B1); } PG8_BAR; PG8_SCHED;
	v_add_u32_e32 v2, s47, v173
	v_add_u32_e32 v22, s53, v173
	ds_read_b128 v[10:13], v2
	ds_read_b128 v[14:17], v2 offset:1024
	ds_read_b128 v[26:29], v2 offset:2048
	ds_read_b128 v[30:33], v2 offset:3072
	ds_read_b128 v[2:5], v22
	ds_read_b128 v[6:9], v22 offset:1024
	ds_read_b128 v[18:21], v22 offset:2048
	ds_read_b128 v[22:25], v22 offset:3072
	v_mov_b32_e32 v34, v170
	s_mov_b32 m0, s45
	ds_read_b128 v[176:179], v174 offset:32768
	ds_read_b128 v[180:183], v174 offset:33792
	ds_read_b128 v[184:187], v174 offset:34816
	ds_read_b128 v[188:191], v174 offset:35840
	ds_read_b128 v[206:209], v174 offset:36864
	ds_read_b128 v[210:213], v174 offset:37888
	ds_read_b128 v[214:217], v174 offset:38912
	ds_read_b128 v[218:221], v174 offset:39936
	s_nop 0
	global_load_lds_dwordx4 v34, s[20:21]
	v_mov_b32_e32 v34, v171
	s_mov_b32 m0, s46
	s_nop 0
	global_load_lds_dwordx4 v34, s[20:21]
	s_waitcnt vmcnt(8)
	s_waitcnt lgkmcnt(0)
	s_barrier
	s_waitcnt lgkmcnt(0)
	v_mfma_scale_f32_16x16x128_f8f6f4 v[160:163], v[10:17], v[176:183], v[160:163], v1, v1 op_sel_hi:[0,0,0]
	v_mfma_scale_f32_16x16x128_f8f6f4 v[156:159], v[26:33], v[176:183], v[156:159], v1, v1 op_sel_hi:[0,0,0]
	v_mfma_scale_f32_16x16x128_f8f6f4 v[40:43], v[10:17], v[184:191], v[40:43], v1, v1 op_sel_hi:[0,0,0]
	v_mfma_scale_f32_16x16x128_f8f6f4 v[36:39], v[26:33], v[184:191], v[36:39], v1, v1 op_sel_hi:[0,0,0]
	v_mfma_scale_f32_16x16x128_f8f6f4 v[56:59], v[10:17], v[206:213], v[56:59], v1, v1 op_sel_hi:[0,0,0]
	v_mfma_scale_f32_16x16x128_f8f6f4 v[52:55], v[26:33], v[206:213], v[52:55], v1, v1 op_sel_hi:[0,0,0]
	v_mfma_scale_f32_16x16x128_f8f6f4 v[72:75], v[10:17], v[214:221], v[72:75], v1, v1 op_sel_hi:[0,0,0]
	v_mfma_scale_f32_16x16x128_f8f6f4 v[68:71], v[26:33], v[214:221], v[68:71], v1, v1 op_sel_hi:[0,0,0]
	v_mfma_scale_f32_16x16x128_f8f6f4 v[152:155], v[2:9], v[176:183], v[152:155], v1, v1 op_sel_hi:[0,0,0]
	v_mfma_scale_f32_16x16x128_f8f6f4 v[148:151], v[18:25], v[176:183], v[148:151], v1, v1 op_sel_hi:[0,0,0]
	v_mfma_scale_f32_16x16x128_f8f6f4 v[144:147], v[2:9], v[184:191], v[144:147], v1, v1 op_sel_hi:[0,0,0]
	v_mfma_scale_f32_16x16x128_f8f6f4 v[140:143], v[18:25], v[184:191], v[140:143], v1, v1 op_sel_hi:[0,0,0]
	v_mfma_scale_f32_16x16x128_f8f6f4 v[136:139], v[2:9], v[206:213], v[136:139], v1, v1 op_sel_hi:[0,0,0]
	v_mfma_scale_f32_16x16x128_f8f6f4 v[132:135], v[18:25], v[206:213], v[132:135], v1, v1 op_sel_hi:[0,0,0]
	v_mfma_scale_f32_16x16x128_f8f6f4 v[48:51], v[2:9], v[214:221], v[48:51], v1, v1 op_sel_hi:[0,0,0]
	v_mfma_scale_f32_16x16x128_f8f6f4 v[44:47], v[18:25], v[214:221], v[44:47], v1, v1 op_sel_hi:[0,0,0]
	s_barrier
	v_mov_b32_e32 v34, v165
	ds_read_b128 v[176:179], v174 offset:49152
	ds_read_b128 v[180:183], v174 offset:50176
	ds_read_b128 v[184:187], v174 offset:51200
	ds_read_b128 v[188:191], v174 offset:52224
	ds_read_b128 v[206:209], v174 offset:53248
	ds_read_b128 v[210:213], v174 offset:54272
	ds_read_b128 v[214:217], v174 offset:55296
	ds_read_b128 v[218:221], v174 offset:56320
	s_mov_b32 m0, s48
	v_lshl_add_u64 v[192:193], s[22:23], 0, v[34:35]
	v_lshl_add_u64 v[192:193], v[192:193], 0, s[80:81]
	v_mov_b32_e32 v34, v167
	global_load_lds_dwordx4 v[192:193], off
	s_mov_b32 m0, s49
	v_lshl_add_u64 v[192:193], s[22:23], 0, v[34:35]
	v_lshl_add_u64 v[192:193], v[192:193], 0, s[80:81]
	v_mov_b32_e32 v34, v168
	global_load_lds_dwordx4 v[192:193], off
	s_mov_b32 m0, s54
	v_lshl_add_u64 v[192:193], s[22:23], 0, v[34:35]
	v_lshl_add_u64 v[192:193], v[192:193], 0, s[80:81]
	v_mov_b32_e32 v34, v169
	global_load_lds_dwordx4 v[192:193], off
	s_mov_b32 m0, s55
	v_lshl_add_u64 v[192:193], s[22:23], 0, v[34:35]
	v_lshl_add_u64 v[192:193], v[192:193], 0, s[80:81]
	v_mov_b32_e32 v34, v164
	global_load_lds_dwordx4 v[192:193], off
	s_mov_b32 m0, s50
	v_lshl_add_u64 v[192:193], s[20:21], 0, v[34:35]
	v_lshl_add_u64 v[192:193], v[192:193], 0, s[80:81]
	v_mov_b32_e32 v34, v166
	global_load_lds_dwordx4 v[192:193], off
	s_mov_b32 m0, s52
	v_lshl_add_u64 v[192:193], s[20:21], 0, v[34:35]
	v_lshl_add_u64 v[192:193], v[192:193], 0, s[80:81]
	global_load_lds_dwordx4 v[192:193], off
	s_waitcnt vmcnt(8)
	s_waitcnt lgkmcnt(0)
	s_barrier
	s_waitcnt lgkmcnt(0)
	v_mfma_scale_f32_16x16x128_f8f6f4 v[112:115], v[10:17], v[176:183], v[112:115], v1, v1 op_sel_hi:[0,0,0]
	v_mfma_scale_f32_16x16x128_f8f6f4 v[108:111], v[26:33], v[176:183], v[108:111], v1, v1 op_sel_hi:[0,0,0]
	v_mfma_scale_f32_16x16x128_f8f6f4 v[128:131], v[10:17], v[184:191], v[128:131], v1, v1 op_sel_hi:[0,0,0]
	v_mfma_scale_f32_16x16x128_f8f6f4 v[124:127], v[26:33], v[184:191], v[124:127], v1, v1 op_sel_hi:[0,0,0]
	v_mfma_scale_f32_16x16x128_f8f6f4 v[120:123], v[10:17], v[206:213], v[120:123], v1, v1 op_sel_hi:[0,0,0]
	v_mfma_scale_f32_16x16x128_f8f6f4 v[116:119], v[26:33], v[206:213], v[116:119], v1, v1 op_sel_hi:[0,0,0]
	v_mfma_scale_f32_16x16x128_f8f6f4 v[88:91], v[10:17], v[214:221], v[88:91], v1, v1 op_sel_hi:[0,0,0]
	v_mfma_scale_f32_16x16x128_f8f6f4 v[84:87], v[26:33], v[214:221], v[84:87], v1, v1 op_sel_hi:[0,0,0]
	v_mfma_scale_f32_16x16x128_f8f6f4 v[64:67], v[2:9], v[176:183], v[64:67], v1, v1 op_sel_hi:[0,0,0]
	v_mfma_scale_f32_16x16x128_f8f6f4 v[60:63], v[18:25], v[176:183], v[60:63], v1, v1 op_sel_hi:[0,0,0]
	v_mfma_scale_f32_16x16x128_f8f6f4 v[96:99], v[2:9], v[184:191], v[96:99], v1, v1 op_sel_hi:[0,0,0]
	v_mfma_scale_f32_16x16x128_f8f6f4 v[92:95], v[18:25], v[184:191], v[92:95], v1, v1 op_sel_hi:[0,0,0]
	v_mfma_scale_f32_16x16x128_f8f6f4 v[104:107], v[2:9], v[206:213], v[104:107], v1, v1 op_sel_hi:[0,0,0]
	v_mfma_scale_f32_16x16x128_f8f6f4 v[100:103], v[18:25], v[206:213], v[100:103], v1, v1 op_sel_hi:[0,0,0]
	v_mfma_scale_f32_16x16x128_f8f6f4 v[80:83], v[2:9], v[214:221], v[80:83], v1, v1 op_sel_hi:[0,0,0]
	v_mfma_scale_f32_16x16x128_f8f6f4 v[76:79], v[18:25], v[214:221], v[76:79], v1, v1 op_sel_hi:[0,0,0]
	s_barrier
	s_add_u32 s18, s18, 0x100
	s_addc_u32 s19, s19, 0
	s_add_u32 s63, s63, 0x100
	s_addc_u32 s64, s64, 0
	s_cmp_ge_i32 s65, s57
	s_mov_b32 s20, s65
	s_cbranch_scc0 .LBB0_2251
